# K-loops restructured into 4 merged phases (8 barriers per trip instead of 16), fragment reads complete before the phase barrier, never more than 15 LDS reads in flight
# speedup vs baseline: 1.0050x; 1.0050x over previous
.LBB0_122:
	v_mov_b64_e32 v[0:1], 0x180
	s_ashr_i32 s15, s14, 31
	v_cmp_lt_i64_e32 vcc, s[16:17], v[0:1]
	s_lshl_b64 s[16:17], s[14:15], 19
	s_add_u32 s16, s30, s16
	s_addc_u32 s17, s31, s17
	s_and_b64 s[18:19], vcc, exec
	s_cselect_b32 s7, s17, s21
	s_cselect_b32 s9, s16, s20
	s_ashr_i32 s13, s12, 31
	s_lshl_b64 s[18:19], s[12:13], 19
	s_add_u32 s18, s34, s18
	s_addc_u32 s19, s35, s19
	s_and_b64 s[22:23], vcc, exec
	s_cselect_b32 s13, s19, s3
	s_cselect_b32 s15, s18, s2
	s_add_u32 s20, s20, 0x40080
	s_addc_u32 s21, s21, 0
	s_add_u32 s50, s2, 0x100
	s_addc_u32 s51, s3, 0
	s_mov_b32 s52, -2
	s_add_u32 s2, s20, 0xfffc0080
	s_addc_u32 s3, s21, -1
	ds_read_b128 v[24:27], v164
	ds_read_b128 v[28:31], v164 offset:1024
	ds_read_b128 v[32:35], v164 offset:2048
	ds_read_b128 v[36:39], v164 offset:3072
	s_cmp_eq_u32 s52, 12
	s_cselect_b32 s23, s7, s3
	s_cselect_b32 s22, s9, s2
	s_cselect_b32 s3, s13, s51
	s_cselect_b32 s2, s15, s50
	s_add_i32 m0, s37, 0xc000
	ds_read_b128 v[154:157], v165
	ds_read_b128 v[158:161], v165 offset:1024
	ds_read_b128 v[180:183], v165 offset:2048
	ds_read_b128 v[184:187], v165 offset:3072
	ds_read_b128 v[188:191], v165 offset:4096
	ds_read_b128 v[192:195], v165 offset:5120
	ds_read_b128 v[196:199], v165 offset:6144
	global_load_lds_dwordx4 v150, s[20:21]
	s_add_i32 m0, s37, 0xe000
	ds_read_b128 v[200:203], v165 offset:7168
	global_load_lds_dwordx4 v152, s[20:21]
	s_waitcnt lgkmcnt(11)
	ds_read_b128 v[204:207], v164 offset:16384
	ds_read_b128 v[208:211], v164 offset:17408
	ds_read_b128 v[212:215], v164 offset:18432
	ds_read_b128 v[216:219], v164 offset:19456
	s_waitcnt lgkmcnt(0)
	s_barrier
	v_mfma_f32_16x16x32_bf16 v[140:143], v[24:27], v[154:157], 0
	v_mfma_f32_16x16x32_bf16 v[136:139], v[32:35], v[154:157], 0
	v_mfma_f32_16x16x32_bf16 v[124:127], v[24:27], v[180:183], 0
	v_mfma_f32_16x16x32_bf16 v[120:123], v[32:35], v[180:183], 0
	v_mfma_f32_16x16x32_bf16 v[108:111], v[24:27], v[188:191], 0
	v_mfma_f32_16x16x32_bf16 v[104:107], v[32:35], v[188:191], 0
	v_mfma_f32_16x16x32_bf16 v[92:95], v[24:27], v[196:199], 0
	v_mfma_f32_16x16x32_bf16 v[88:91], v[32:35], v[196:199], 0
	v_mfma_f32_16x16x32_bf16 v[140:143], v[28:31], v[158:161], v[140:143]
	v_mfma_f32_16x16x32_bf16 v[136:139], v[36:39], v[158:161], v[136:139]
	v_mfma_f32_16x16x32_bf16 v[124:127], v[28:31], v[184:187], v[124:127]
	v_mfma_f32_16x16x32_bf16 v[120:123], v[36:39], v[184:187], v[120:123]
	v_mfma_f32_16x16x32_bf16 v[108:111], v[28:31], v[192:195], v[108:111]
	v_mfma_f32_16x16x32_bf16 v[104:107], v[36:39], v[192:195], v[104:107]
	v_mfma_f32_16x16x32_bf16 v[92:95], v[28:31], v[200:203], v[92:95]
	v_mfma_f32_16x16x32_bf16 v[88:91], v[36:39], v[200:203], v[88:91]
	v_mfma_f32_16x16x32_bf16 v[132:135], v[204:207], v[154:157], 0
	v_mfma_f32_16x16x32_bf16 v[128:131], v[212:215], v[154:157], 0
	v_mfma_f32_16x16x32_bf16 v[116:119], v[204:207], v[180:183], 0
	v_mfma_f32_16x16x32_bf16 v[112:115], v[212:215], v[180:183], 0
	v_mfma_f32_16x16x32_bf16 v[100:103], v[204:207], v[188:191], 0
	v_mfma_f32_16x16x32_bf16 v[96:99], v[212:215], v[188:191], 0
	v_mfma_f32_16x16x32_bf16 v[84:87], v[204:207], v[196:199], 0
	v_mfma_f32_16x16x32_bf16 v[80:83], v[212:215], v[196:199], 0
	v_mfma_f32_16x16x32_bf16 v[132:135], v[208:211], v[158:161], v[132:135]
	v_mfma_f32_16x16x32_bf16 v[128:131], v[216:219], v[158:161], v[128:131]
	v_mfma_f32_16x16x32_bf16 v[116:119], v[208:211], v[184:187], v[116:119]
	v_mfma_f32_16x16x32_bf16 v[112:115], v[216:219], v[184:187], v[112:115]
	v_mfma_f32_16x16x32_bf16 v[100:103], v[208:211], v[192:195], v[100:103]
	v_mfma_f32_16x16x32_bf16 v[96:99], v[216:219], v[192:195], v[96:99]
	v_mfma_f32_16x16x32_bf16 v[84:87], v[208:211], v[200:203], v[84:87]
	v_mfma_f32_16x16x32_bf16 v[80:83], v[216:219], v[200:203], v[80:83]
	s_barrier
	s_add_i32 m0, s36, 0x10000
	ds_read_b128 v[154:157], v165 offset:16384
	global_load_lds_dwordx4 v168, s[2:3]
	s_add_i32 m0, s36, 0x12000
	s_add_u32 s98, s2, 0x80
	s_addc_u32 s99, s3, 0
	global_load_lds_dwordx4 v148, s[2:3]
	s_mov_b32 m0, s37
	s_add_u32 s100, s22, 0x80
	s_addc_u32 s101, s23, 0
	ds_read_b128 v[158:161], v165 offset:17408
	ds_read_b128 v[180:183], v165 offset:18432
	ds_read_b128 v[184:187], v165 offset:19456
	ds_read_b128 v[188:191], v165 offset:20480
	ds_read_b128 v[192:195], v165 offset:21504
	ds_read_b128 v[196:199], v165 offset:22528
	global_load_lds_dwordx4 v144, s[22:23]
	s_mov_b32 m0, s38
	ds_read_b128 v[200:203], v165 offset:23552
	global_load_lds_dwordx4 v146, s[22:23]
	s_add_i32 m0, s36, 0x14000
	s_add_u32 s54, s2, 0x40000
	s_addc_u32 s55, s3, 0
	global_load_lds_dwordx4 v168, s[54:55]
	s_add_i32 m0, s36, 0x16000
	s_add_u32 s22, s22, 0x40000
	s_addc_u32 s23, s23, 0
	global_load_lds_dwordx4 v148, s[54:55]
	s_waitcnt lgkmcnt(0)
	s_waitcnt vmcnt(6)
	s_barrier
	v_mfma_f32_16x16x32_bf16 v[76:79], v[24:27], v[154:157], 0
	v_mfma_f32_16x16x32_bf16 v[72:75], v[32:35], v[154:157], 0
	v_mfma_f32_16x16x32_bf16 v[60:63], v[24:27], v[180:183], 0
	v_mfma_f32_16x16x32_bf16 v[56:59], v[32:35], v[180:183], 0
	v_mfma_f32_16x16x32_bf16 v[44:47], v[24:27], v[188:191], 0
	v_mfma_f32_16x16x32_bf16 v[40:43], v[32:35], v[188:191], 0
	v_mfma_f32_16x16x32_bf16 v[12:15], v[24:27], v[196:199], 0
	v_mfma_f32_16x16x32_bf16 v[8:11], v[32:35], v[196:199], 0
	v_mfma_f32_16x16x32_bf16 v[76:79], v[28:31], v[158:161], v[76:79]
	v_mfma_f32_16x16x32_bf16 v[72:75], v[36:39], v[158:161], v[72:75]
	v_mfma_f32_16x16x32_bf16 v[60:63], v[28:31], v[184:187], v[60:63]
	v_mfma_f32_16x16x32_bf16 v[56:59], v[36:39], v[184:187], v[56:59]
	v_mfma_f32_16x16x32_bf16 v[44:47], v[28:31], v[192:195], v[44:47]
	v_mfma_f32_16x16x32_bf16 v[40:43], v[36:39], v[192:195], v[40:43]
	v_mfma_f32_16x16x32_bf16 v[12:15], v[28:31], v[200:203], v[12:15]
	v_mfma_f32_16x16x32_bf16 v[8:11], v[36:39], v[200:203], v[8:11]
	v_mfma_f32_16x16x32_bf16 v[20:23], v[204:207], v[188:191], 0
	v_mfma_f32_16x16x32_bf16 v[16:19], v[212:215], v[188:191], 0
	v_mfma_f32_16x16x32_bf16 v[4:7], v[204:207], v[196:199], 0
	v_mfma_f32_16x16x32_bf16 v[0:3], v[212:215], v[196:199], 0
	v_mfma_f32_16x16x32_bf16 v[24:27], v[204:207], v[154:157], 0
	v_mfma_f32_16x16x32_bf16 v[28:31], v[212:215], v[154:157], 0
	v_mfma_f32_16x16x32_bf16 v[32:35], v[204:207], v[180:183], 0
	v_mfma_f32_16x16x32_bf16 v[36:39], v[212:215], v[180:183], 0
	v_mfma_f32_16x16x32_bf16 v[20:23], v[208:211], v[192:195], v[20:23]
	v_mfma_f32_16x16x32_bf16 v[16:19], v[216:219], v[192:195], v[16:19]
	v_mfma_f32_16x16x32_bf16 v[4:7], v[208:211], v[200:203], v[4:7]
	v_mfma_f32_16x16x32_bf16 v[0:3], v[216:219], v[200:203], v[0:3]
	v_mfma_f32_16x16x32_bf16 v[24:27], v[208:211], v[158:161], v[24:27]
	v_mfma_f32_16x16x32_bf16 v[28:31], v[216:219], v[158:161], v[28:31]
	v_mfma_f32_16x16x32_bf16 v[32:35], v[208:211], v[184:187], v[32:35]
	v_mfma_f32_16x16x32_bf16 v[36:39], v[216:219], v[184:187], v[36:39]
	s_barrier
	ds_read_b128 v[48:51], v164 offset:32768
	ds_read_b128 v[52:55], v164 offset:33792
	ds_read_b128 v[64:67], v164 offset:34816
	ds_read_b128 v[68:71], v164 offset:35840
	s_mov_b32 m0, s39
	ds_read_b128 v[154:157], v165 offset:32768
	ds_read_b128 v[158:161], v165 offset:33792
	ds_read_b128 v[180:183], v165 offset:34816
	ds_read_b128 v[184:187], v165 offset:35840
	ds_read_b128 v[188:191], v165 offset:36864
	ds_read_b128 v[192:195], v165 offset:37888
	ds_read_b128 v[196:199], v165 offset:38912
	global_load_lds_dwordx4 v144, s[22:23]
	s_mov_b32 m0, s40
	ds_read_b128 v[200:203], v165 offset:39936
	global_load_lds_dwordx4 v146, s[22:23]
	s_waitcnt lgkmcnt(11)
	ds_read_b128 v[204:207], v164 offset:49152
	ds_read_b128 v[208:211], v164 offset:50176
	ds_read_b128 v[212:215], v164 offset:51200
	ds_read_b128 v[216:219], v164 offset:52224
	s_waitcnt lgkmcnt(0)
	s_barrier
	v_mfma_f32_16x16x32_bf16 v[140:143], v[48:51], v[154:157], v[140:143]
	v_mfma_f32_16x16x32_bf16 v[136:139], v[64:67], v[154:157], v[136:139]
	v_mfma_f32_16x16x32_bf16 v[124:127], v[48:51], v[180:183], v[124:127]
	v_mfma_f32_16x16x32_bf16 v[120:123], v[64:67], v[180:183], v[120:123]
	v_mfma_f32_16x16x32_bf16 v[108:111], v[48:51], v[188:191], v[108:111]
	v_mfma_f32_16x16x32_bf16 v[104:107], v[64:67], v[188:191], v[104:107]
	v_mfma_f32_16x16x32_bf16 v[92:95], v[48:51], v[196:199], v[92:95]
	v_mfma_f32_16x16x32_bf16 v[88:91], v[64:67], v[196:199], v[88:91]
	v_mfma_f32_16x16x32_bf16 v[140:143], v[52:55], v[158:161], v[140:143]
	v_mfma_f32_16x16x32_bf16 v[136:139], v[68:71], v[158:161], v[136:139]
	v_mfma_f32_16x16x32_bf16 v[124:127], v[52:55], v[184:187], v[124:127]
	v_mfma_f32_16x16x32_bf16 v[120:123], v[68:71], v[184:187], v[120:123]
	v_mfma_f32_16x16x32_bf16 v[108:111], v[52:55], v[192:195], v[108:111]
	v_mfma_f32_16x16x32_bf16 v[104:107], v[68:71], v[192:195], v[104:107]
	v_mfma_f32_16x16x32_bf16 v[92:95], v[52:55], v[200:203], v[92:95]
	v_mfma_f32_16x16x32_bf16 v[88:91], v[68:71], v[200:203], v[88:91]
	v_mfma_f32_16x16x32_bf16 v[132:135], v[204:207], v[154:157], v[132:135]
	v_mfma_f32_16x16x32_bf16 v[128:131], v[212:215], v[154:157], v[128:131]
	v_mfma_f32_16x16x32_bf16 v[116:119], v[204:207], v[180:183], v[116:119]
	v_mfma_f32_16x16x32_bf16 v[112:115], v[212:215], v[180:183], v[112:115]
	v_mfma_f32_16x16x32_bf16 v[100:103], v[204:207], v[188:191], v[100:103]
	v_mfma_f32_16x16x32_bf16 v[96:99], v[212:215], v[188:191], v[96:99]
	v_mfma_f32_16x16x32_bf16 v[84:87], v[204:207], v[196:199], v[84:87]
	v_mfma_f32_16x16x32_bf16 v[80:83], v[212:215], v[196:199], v[80:83]
	v_mfma_f32_16x16x32_bf16 v[132:135], v[208:211], v[158:161], v[132:135]
	v_mfma_f32_16x16x32_bf16 v[128:131], v[216:219], v[158:161], v[128:131]
	v_mfma_f32_16x16x32_bf16 v[116:119], v[208:211], v[184:187], v[116:119]
	v_mfma_f32_16x16x32_bf16 v[112:115], v[216:219], v[184:187], v[112:115]
	v_mfma_f32_16x16x32_bf16 v[100:103], v[208:211], v[192:195], v[100:103]
	v_mfma_f32_16x16x32_bf16 v[96:99], v[216:219], v[192:195], v[96:99]
	v_mfma_f32_16x16x32_bf16 v[84:87], v[208:211], v[200:203], v[84:87]
	v_mfma_f32_16x16x32_bf16 v[80:83], v[216:219], v[200:203], v[80:83]
	s_barrier
	s_add_i32 m0, s36, 0x18000
	ds_read_b128 v[154:157], v165 offset:49152
	global_load_lds_dwordx4 v168, s[98:99]
	s_add_i32 m0, s36, 0x1a000
	ds_read_b128 v[158:161], v165 offset:50176
	global_load_lds_dwordx4 v148, s[98:99]
	s_mov_b32 m0, s45
	ds_read_b128 v[180:183], v165 offset:51200
	ds_read_b128 v[184:187], v165 offset:52224
	ds_read_b128 v[188:191], v165 offset:53248
	ds_read_b128 v[192:195], v165 offset:54272
	ds_read_b128 v[196:199], v165 offset:55296
	global_load_lds_dwordx4 v144, s[100:101]
	s_mov_b32 m0, s46
	ds_read_b128 v[200:203], v165 offset:56320
	global_load_lds_dwordx4 v146, s[100:101]
	s_add_i32 m0, s36, 0x1c000
	s_add_u32 s2, s2, 0x40080
	s_addc_u32 s3, s3, 0
	global_load_lds_dwordx4 v168, s[2:3]
	s_add_i32 m0, s36, 0x1e000
	s_add_i32 s52, s52, 2
	global_load_lds_dwordx4 v148, s[2:3]
	s_waitcnt lgkmcnt(0)
	s_waitcnt vmcnt(6)
	s_barrier
	v_mfma_f32_16x16x32_bf16 v[76:79], v[48:51], v[154:157], v[76:79]
	v_mfma_f32_16x16x32_bf16 v[72:75], v[64:67], v[154:157], v[72:75]
	v_mfma_f32_16x16x32_bf16 v[60:63], v[48:51], v[180:183], v[60:63]
	v_mfma_f32_16x16x32_bf16 v[56:59], v[64:67], v[180:183], v[56:59]
	v_mfma_f32_16x16x32_bf16 v[44:47], v[48:51], v[188:191], v[44:47]
	v_mfma_f32_16x16x32_bf16 v[40:43], v[64:67], v[188:191], v[40:43]
	v_mfma_f32_16x16x32_bf16 v[12:15], v[48:51], v[196:199], v[12:15]
	v_mfma_f32_16x16x32_bf16 v[8:11], v[64:67], v[196:199], v[8:11]
	v_mfma_f32_16x16x32_bf16 v[76:79], v[52:55], v[158:161], v[76:79]
	v_mfma_f32_16x16x32_bf16 v[72:75], v[68:71], v[158:161], v[72:75]
	v_mfma_f32_16x16x32_bf16 v[60:63], v[52:55], v[184:187], v[60:63]
	v_mfma_f32_16x16x32_bf16 v[56:59], v[68:71], v[184:187], v[56:59]
	v_mfma_f32_16x16x32_bf16 v[44:47], v[52:55], v[192:195], v[44:47]
	v_mfma_f32_16x16x32_bf16 v[40:43], v[68:71], v[192:195], v[40:43]
	v_mfma_f32_16x16x32_bf16 v[12:15], v[52:55], v[200:203], v[12:15]
	v_mfma_f32_16x16x32_bf16 v[8:11], v[68:71], v[200:203], v[8:11]
	v_mfma_f32_16x16x32_bf16 v[24:27], v[204:207], v[154:157], v[24:27]
	v_mfma_f32_16x16x32_bf16 v[68:71], v[208:211], v[158:161], v[24:27]
	v_mfma_f32_16x16x32_bf16 v[24:27], v[212:215], v[154:157], v[28:31]
	v_mfma_f32_16x16x32_bf16 v[64:67], v[216:219], v[158:161], v[24:27]
	v_mfma_f32_16x16x32_bf16 v[24:27], v[204:207], v[180:183], v[32:35]
	v_mfma_f32_16x16x32_bf16 v[52:55], v[208:211], v[184:187], v[24:27]
	v_mfma_f32_16x16x32_bf16 v[24:27], v[212:215], v[180:183], v[36:39]
	v_mfma_f32_16x16x32_bf16 v[20:23], v[204:207], v[188:191], v[20:23]
	v_mfma_f32_16x16x32_bf16 v[16:19], v[212:215], v[188:191], v[16:19]
	v_mfma_f32_16x16x32_bf16 v[4:7], v[204:207], v[196:199], v[4:7]
	v_mfma_f32_16x16x32_bf16 v[0:3], v[212:215], v[196:199], v[0:3]
	v_mfma_f32_16x16x32_bf16 v[48:51], v[216:219], v[184:187], v[24:27]
	v_mfma_f32_16x16x32_bf16 v[20:23], v[208:211], v[192:195], v[20:23]
	v_mfma_f32_16x16x32_bf16 v[16:19], v[216:219], v[192:195], v[16:19]
	v_mfma_f32_16x16x32_bf16 v[4:7], v[208:211], v[200:203], v[4:7]
	v_mfma_f32_16x16x32_bf16 v[0:3], v[216:219], v[200:203], v[0:3]
	s_add_u32 s20, s20, 0x100
	s_addc_u32 s21, s21, 0
	s_add_u32 s50, s50, 0x100
	s_addc_u32 s51, s51, 0
	s_cmp_gt_u32 s52, 13
	s_barrier
.LBB0_123:
	s_add_u32 s2, s20, 0xfffc0080
	s_addc_u32 s3, s21, -1
	ds_read_b128 v[24:27], v164
	ds_read_b128 v[28:31], v164 offset:1024
	ds_read_b128 v[32:35], v164 offset:2048
	ds_read_b128 v[36:39], v164 offset:3072
	s_cmp_eq_u32 s52, 12
	s_cselect_b32 s23, s7, s3
	s_cselect_b32 s22, s9, s2
	s_cselect_b32 s3, s13, s51
	s_cselect_b32 s2, s15, s50
	s_add_i32 m0, s37, 0xc000
	ds_read_b128 v[154:157], v165
	ds_read_b128 v[158:161], v165 offset:1024
	ds_read_b128 v[180:183], v165 offset:2048
	ds_read_b128 v[184:187], v165 offset:3072
	ds_read_b128 v[188:191], v165 offset:4096
	ds_read_b128 v[192:195], v165 offset:5120
	ds_read_b128 v[196:199], v165 offset:6144
	global_load_lds_dwordx4 v150, s[20:21]
	s_add_i32 m0, s37, 0xe000
	ds_read_b128 v[200:203], v165 offset:7168
	global_load_lds_dwordx4 v152, s[20:21]
	s_waitcnt lgkmcnt(11)
	ds_read_b128 v[204:207], v164 offset:16384
	ds_read_b128 v[208:211], v164 offset:17408
	ds_read_b128 v[212:215], v164 offset:18432
	ds_read_b128 v[216:219], v164 offset:19456
	s_waitcnt lgkmcnt(0)
	s_barrier
	v_mfma_f32_16x16x32_bf16 v[140:143], v[24:27], v[154:157], v[140:143]
	v_mfma_f32_16x16x32_bf16 v[136:139], v[32:35], v[154:157], v[136:139]
	v_mfma_f32_16x16x32_bf16 v[124:127], v[24:27], v[180:183], v[124:127]
	v_mfma_f32_16x16x32_bf16 v[120:123], v[32:35], v[180:183], v[120:123]
	v_mfma_f32_16x16x32_bf16 v[108:111], v[24:27], v[188:191], v[108:111]
	v_mfma_f32_16x16x32_bf16 v[104:107], v[32:35], v[188:191], v[104:107]
	v_mfma_f32_16x16x32_bf16 v[92:95], v[24:27], v[196:199], v[92:95]
	v_mfma_f32_16x16x32_bf16 v[88:91], v[32:35], v[196:199], v[88:91]
	v_mfma_f32_16x16x32_bf16 v[140:143], v[28:31], v[158:161], v[140:143]
	v_mfma_f32_16x16x32_bf16 v[136:139], v[36:39], v[158:161], v[136:139]
	v_mfma_f32_16x16x32_bf16 v[124:127], v[28:31], v[184:187], v[124:127]
	v_mfma_f32_16x16x32_bf16 v[120:123], v[36:39], v[184:187], v[120:123]
	v_mfma_f32_16x16x32_bf16 v[108:111], v[28:31], v[192:195], v[108:111]
	v_mfma_f32_16x16x32_bf16 v[104:107], v[36:39], v[192:195], v[104:107]
	v_mfma_f32_16x16x32_bf16 v[92:95], v[28:31], v[200:203], v[92:95]
	v_mfma_f32_16x16x32_bf16 v[88:91], v[36:39], v[200:203], v[88:91]
	v_mfma_f32_16x16x32_bf16 v[132:135], v[204:207], v[154:157], v[132:135]
	v_mfma_f32_16x16x32_bf16 v[128:131], v[212:215], v[154:157], v[128:131]
	v_mfma_f32_16x16x32_bf16 v[116:119], v[204:207], v[180:183], v[116:119]
	v_mfma_f32_16x16x32_bf16 v[112:115], v[212:215], v[180:183], v[112:115]
	v_mfma_f32_16x16x32_bf16 v[100:103], v[204:207], v[188:191], v[100:103]
	v_mfma_f32_16x16x32_bf16 v[96:99], v[212:215], v[188:191], v[96:99]
	v_mfma_f32_16x16x32_bf16 v[84:87], v[204:207], v[196:199], v[84:87]
	v_mfma_f32_16x16x32_bf16 v[80:83], v[212:215], v[196:199], v[80:83]
	v_mfma_f32_16x16x32_bf16 v[132:135], v[208:211], v[158:161], v[132:135]
	v_mfma_f32_16x16x32_bf16 v[128:131], v[216:219], v[158:161], v[128:131]
	v_mfma_f32_16x16x32_bf16 v[116:119], v[208:211], v[184:187], v[116:119]
	v_mfma_f32_16x16x32_bf16 v[112:115], v[216:219], v[184:187], v[112:115]
	v_mfma_f32_16x16x32_bf16 v[100:103], v[208:211], v[192:195], v[100:103]
	v_mfma_f32_16x16x32_bf16 v[96:99], v[216:219], v[192:195], v[96:99]
	v_mfma_f32_16x16x32_bf16 v[84:87], v[208:211], v[200:203], v[84:87]
	v_mfma_f32_16x16x32_bf16 v[80:83], v[216:219], v[200:203], v[80:83]
	s_barrier
	s_add_i32 m0, s36, 0x10000
	ds_read_b128 v[154:157], v165 offset:16384
	global_load_lds_dwordx4 v168, s[2:3]
	s_add_i32 m0, s36, 0x12000
	s_add_u32 s98, s2, 0x80
	s_addc_u32 s99, s3, 0
	global_load_lds_dwordx4 v148, s[2:3]
	s_mov_b32 m0, s37
	s_add_u32 s100, s22, 0x80
	s_addc_u32 s101, s23, 0
	ds_read_b128 v[158:161], v165 offset:17408
	ds_read_b128 v[180:183], v165 offset:18432
	ds_read_b128 v[184:187], v165 offset:19456
	ds_read_b128 v[188:191], v165 offset:20480
	ds_read_b128 v[192:195], v165 offset:21504
	ds_read_b128 v[196:199], v165 offset:22528
	global_load_lds_dwordx4 v144, s[22:23]
	s_mov_b32 m0, s38
	ds_read_b128 v[200:203], v165 offset:23552
	global_load_lds_dwordx4 v146, s[22:23]
	s_add_i32 m0, s36, 0x14000
	s_add_u32 s54, s2, 0x40000
	s_addc_u32 s55, s3, 0
	global_load_lds_dwordx4 v168, s[54:55]
	s_add_i32 m0, s36, 0x16000
	s_add_u32 s22, s22, 0x40000
	s_addc_u32 s23, s23, 0
	global_load_lds_dwordx4 v148, s[54:55]
	s_waitcnt lgkmcnt(0)
	s_waitcnt vmcnt(6)
	s_barrier
	v_mfma_f32_16x16x32_bf16 v[76:79], v[24:27], v[154:157], v[76:79]
	v_mfma_f32_16x16x32_bf16 v[72:75], v[32:35], v[154:157], v[72:75]
	v_mfma_f32_16x16x32_bf16 v[60:63], v[24:27], v[180:183], v[60:63]
	v_mfma_f32_16x16x32_bf16 v[56:59], v[32:35], v[180:183], v[56:59]
	v_mfma_f32_16x16x32_bf16 v[44:47], v[24:27], v[188:191], v[44:47]
	v_mfma_f32_16x16x32_bf16 v[40:43], v[32:35], v[188:191], v[40:43]
	v_mfma_f32_16x16x32_bf16 v[12:15], v[24:27], v[196:199], v[12:15]
	v_mfma_f32_16x16x32_bf16 v[8:11], v[32:35], v[196:199], v[8:11]
	v_mfma_f32_16x16x32_bf16 v[76:79], v[28:31], v[158:161], v[76:79]
	v_mfma_f32_16x16x32_bf16 v[72:75], v[36:39], v[158:161], v[72:75]
	v_mfma_f32_16x16x32_bf16 v[60:63], v[28:31], v[184:187], v[60:63]
	v_mfma_f32_16x16x32_bf16 v[56:59], v[36:39], v[184:187], v[56:59]
	v_mfma_f32_16x16x32_bf16 v[44:47], v[28:31], v[192:195], v[44:47]
	v_mfma_f32_16x16x32_bf16 v[40:43], v[36:39], v[192:195], v[40:43]
	v_mfma_f32_16x16x32_bf16 v[12:15], v[28:31], v[200:203], v[12:15]
	v_mfma_f32_16x16x32_bf16 v[8:11], v[36:39], v[200:203], v[8:11]
	v_mfma_f32_16x16x32_bf16 v[20:23], v[204:207], v[188:191], v[20:23]
	v_mfma_f32_16x16x32_bf16 v[16:19], v[212:215], v[188:191], v[16:19]
	v_mfma_f32_16x16x32_bf16 v[4:7], v[204:207], v[196:199], v[4:7]
	v_mfma_f32_16x16x32_bf16 v[0:3], v[212:215], v[196:199], v[0:3]
	v_mfma_f32_16x16x32_bf16 v[24:27], v[204:207], v[154:157], v[68:71]
	v_mfma_f32_16x16x32_bf16 v[28:31], v[212:215], v[154:157], v[64:67]
	v_mfma_f32_16x16x32_bf16 v[32:35], v[204:207], v[180:183], v[52:55]
	v_mfma_f32_16x16x32_bf16 v[36:39], v[212:215], v[180:183], v[48:51]
	v_mfma_f32_16x16x32_bf16 v[20:23], v[208:211], v[192:195], v[20:23]
	v_mfma_f32_16x16x32_bf16 v[16:19], v[216:219], v[192:195], v[16:19]
	v_mfma_f32_16x16x32_bf16 v[4:7], v[208:211], v[200:203], v[4:7]
	v_mfma_f32_16x16x32_bf16 v[0:3], v[216:219], v[200:203], v[0:3]
	v_mfma_f32_16x16x32_bf16 v[24:27], v[208:211], v[158:161], v[24:27]
	v_mfma_f32_16x16x32_bf16 v[28:31], v[216:219], v[158:161], v[28:31]
	v_mfma_f32_16x16x32_bf16 v[32:35], v[208:211], v[184:187], v[32:35]
	v_mfma_f32_16x16x32_bf16 v[36:39], v[216:219], v[184:187], v[36:39]
	s_barrier
	ds_read_b128 v[48:51], v164 offset:32768
	ds_read_b128 v[52:55], v164 offset:33792
	ds_read_b128 v[64:67], v164 offset:34816
	ds_read_b128 v[68:71], v164 offset:35840
	s_mov_b32 m0, s39
	ds_read_b128 v[154:157], v165 offset:32768
	ds_read_b128 v[158:161], v165 offset:33792
	ds_read_b128 v[180:183], v165 offset:34816
	ds_read_b128 v[184:187], v165 offset:35840
	ds_read_b128 v[188:191], v165 offset:36864
	ds_read_b128 v[192:195], v165 offset:37888
	ds_read_b128 v[196:199], v165 offset:38912
	global_load_lds_dwordx4 v144, s[22:23]
	s_mov_b32 m0, s40
	ds_read_b128 v[200:203], v165 offset:39936
	global_load_lds_dwordx4 v146, s[22:23]
	s_waitcnt lgkmcnt(11)
	ds_read_b128 v[204:207], v164 offset:49152
	ds_read_b128 v[208:211], v164 offset:50176
	ds_read_b128 v[212:215], v164 offset:51200
	ds_read_b128 v[216:219], v164 offset:52224
	s_waitcnt lgkmcnt(0)
	s_barrier
	v_mfma_f32_16x16x32_bf16 v[140:143], v[48:51], v[154:157], v[140:143]
	v_mfma_f32_16x16x32_bf16 v[136:139], v[64:67], v[154:157], v[136:139]
	v_mfma_f32_16x16x32_bf16 v[124:127], v[48:51], v[180:183], v[124:127]
	v_mfma_f32_16x16x32_bf16 v[120:123], v[64:67], v[180:183], v[120:123]
	v_mfma_f32_16x16x32_bf16 v[108:111], v[48:51], v[188:191], v[108:111]
	v_mfma_f32_16x16x32_bf16 v[104:107], v[64:67], v[188:191], v[104:107]
	v_mfma_f32_16x16x32_bf16 v[92:95], v[48:51], v[196:199], v[92:95]
	v_mfma_f32_16x16x32_bf16 v[88:91], v[64:67], v[196:199], v[88:91]
	v_mfma_f32_16x16x32_bf16 v[140:143], v[52:55], v[158:161], v[140:143]
	v_mfma_f32_16x16x32_bf16 v[136:139], v[68:71], v[158:161], v[136:139]
	v_mfma_f32_16x16x32_bf16 v[124:127], v[52:55], v[184:187], v[124:127]
	v_mfma_f32_16x16x32_bf16 v[120:123], v[68:71], v[184:187], v[120:123]
	v_mfma_f32_16x16x32_bf16 v[108:111], v[52:55], v[192:195], v[108:111]
	v_mfma_f32_16x16x32_bf16 v[104:107], v[68:71], v[192:195], v[104:107]
	v_mfma_f32_16x16x32_bf16 v[92:95], v[52:55], v[200:203], v[92:95]
	v_mfma_f32_16x16x32_bf16 v[88:91], v[68:71], v[200:203], v[88:91]
	v_mfma_f32_16x16x32_bf16 v[132:135], v[204:207], v[154:157], v[132:135]
	v_mfma_f32_16x16x32_bf16 v[128:131], v[212:215], v[154:157], v[128:131]
	v_mfma_f32_16x16x32_bf16 v[116:119], v[204:207], v[180:183], v[116:119]
	v_mfma_f32_16x16x32_bf16 v[112:115], v[212:215], v[180:183], v[112:115]
	v_mfma_f32_16x16x32_bf16 v[100:103], v[204:207], v[188:191], v[100:103]
	v_mfma_f32_16x16x32_bf16 v[96:99], v[212:215], v[188:191], v[96:99]
	v_mfma_f32_16x16x32_bf16 v[84:87], v[204:207], v[196:199], v[84:87]
	v_mfma_f32_16x16x32_bf16 v[80:83], v[212:215], v[196:199], v[80:83]
	v_mfma_f32_16x16x32_bf16 v[132:135], v[208:211], v[158:161], v[132:135]
	v_mfma_f32_16x16x32_bf16 v[128:131], v[216:219], v[158:161], v[128:131]
	v_mfma_f32_16x16x32_bf16 v[116:119], v[208:211], v[184:187], v[116:119]
	v_mfma_f32_16x16x32_bf16 v[112:115], v[216:219], v[184:187], v[112:115]
	v_mfma_f32_16x16x32_bf16 v[100:103], v[208:211], v[192:195], v[100:103]
	v_mfma_f32_16x16x32_bf16 v[96:99], v[216:219], v[192:195], v[96:99]
	v_mfma_f32_16x16x32_bf16 v[84:87], v[208:211], v[200:203], v[84:87]
	v_mfma_f32_16x16x32_bf16 v[80:83], v[216:219], v[200:203], v[80:83]
	s_barrier
	s_add_i32 m0, s36, 0x18000
	ds_read_b128 v[154:157], v165 offset:49152
	global_load_lds_dwordx4 v168, s[98:99]
	s_add_i32 m0, s36, 0x1a000
	ds_read_b128 v[158:161], v165 offset:50176
	global_load_lds_dwordx4 v148, s[98:99]
	s_mov_b32 m0, s45
	ds_read_b128 v[180:183], v165 offset:51200
	ds_read_b128 v[184:187], v165 offset:52224
	ds_read_b128 v[188:191], v165 offset:53248
	ds_read_b128 v[192:195], v165 offset:54272
	ds_read_b128 v[196:199], v165 offset:55296
	global_load_lds_dwordx4 v144, s[100:101]
	s_mov_b32 m0, s46
	ds_read_b128 v[200:203], v165 offset:56320
	global_load_lds_dwordx4 v146, s[100:101]
	s_add_i32 m0, s36, 0x1c000
	s_add_u32 s2, s2, 0x40080
	s_addc_u32 s3, s3, 0
	global_load_lds_dwordx4 v168, s[2:3]
	s_add_i32 m0, s36, 0x1e000
	s_add_i32 s52, s52, 2
	global_load_lds_dwordx4 v148, s[2:3]
	s_waitcnt lgkmcnt(0)
	s_waitcnt vmcnt(6)
	s_barrier
	v_mfma_f32_16x16x32_bf16 v[76:79], v[48:51], v[154:157], v[76:79]
	v_mfma_f32_16x16x32_bf16 v[72:75], v[64:67], v[154:157], v[72:75]
	v_mfma_f32_16x16x32_bf16 v[60:63], v[48:51], v[180:183], v[60:63]
	v_mfma_f32_16x16x32_bf16 v[56:59], v[64:67], v[180:183], v[56:59]
	v_mfma_f32_16x16x32_bf16 v[44:47], v[48:51], v[188:191], v[44:47]
	v_mfma_f32_16x16x32_bf16 v[40:43], v[64:67], v[188:191], v[40:43]
	v_mfma_f32_16x16x32_bf16 v[12:15], v[48:51], v[196:199], v[12:15]
	v_mfma_f32_16x16x32_bf16 v[8:11], v[64:67], v[196:199], v[8:11]
	v_mfma_f32_16x16x32_bf16 v[76:79], v[52:55], v[158:161], v[76:79]
	v_mfma_f32_16x16x32_bf16 v[72:75], v[68:71], v[158:161], v[72:75]
	v_mfma_f32_16x16x32_bf16 v[60:63], v[52:55], v[184:187], v[60:63]
	v_mfma_f32_16x16x32_bf16 v[56:59], v[68:71], v[184:187], v[56:59]
	v_mfma_f32_16x16x32_bf16 v[44:47], v[52:55], v[192:195], v[44:47]
	v_mfma_f32_16x16x32_bf16 v[40:43], v[68:71], v[192:195], v[40:43]
	v_mfma_f32_16x16x32_bf16 v[12:15], v[52:55], v[200:203], v[12:15]
	v_mfma_f32_16x16x32_bf16 v[8:11], v[68:71], v[200:203], v[8:11]
	v_mfma_f32_16x16x32_bf16 v[24:27], v[204:207], v[154:157], v[24:27]
	v_mfma_f32_16x16x32_bf16 v[68:71], v[208:211], v[158:161], v[24:27]
	v_mfma_f32_16x16x32_bf16 v[24:27], v[212:215], v[154:157], v[28:31]
	v_mfma_f32_16x16x32_bf16 v[64:67], v[216:219], v[158:161], v[24:27]
	v_mfma_f32_16x16x32_bf16 v[24:27], v[204:207], v[180:183], v[32:35]
	v_mfma_f32_16x16x32_bf16 v[52:55], v[208:211], v[184:187], v[24:27]
	v_mfma_f32_16x16x32_bf16 v[24:27], v[212:215], v[180:183], v[36:39]
	v_mfma_f32_16x16x32_bf16 v[20:23], v[204:207], v[188:191], v[20:23]
	v_mfma_f32_16x16x32_bf16 v[16:19], v[212:215], v[188:191], v[16:19]
	v_mfma_f32_16x16x32_bf16 v[4:7], v[204:207], v[196:199], v[4:7]
	v_mfma_f32_16x16x32_bf16 v[0:3], v[212:215], v[196:199], v[0:3]
	v_mfma_f32_16x16x32_bf16 v[48:51], v[216:219], v[184:187], v[24:27]
	v_mfma_f32_16x16x32_bf16 v[20:23], v[208:211], v[192:195], v[20:23]
	v_mfma_f32_16x16x32_bf16 v[16:19], v[216:219], v[192:195], v[16:19]
	v_mfma_f32_16x16x32_bf16 v[4:7], v[208:211], v[200:203], v[4:7]
	v_mfma_f32_16x16x32_bf16 v[0:3], v[216:219], v[200:203], v[0:3]
	s_add_u32 s20, s20, 0x100
	s_addc_u32 s21, s21, 0
	s_add_u32 s50, s50, 0x100
	s_addc_u32 s51, s51, 0
	s_cmp_gt_u32 s52, 13
	s_barrier
	s_cbranch_scc0 .LBB0_123
	s_lshl_b32 s2, s6, 8
	s_add_i32 s3, s2, s43
	s_lshl_b32 s2, s8, 8
	s_cmp_gt_i32 s8, 3
	s_cselect_b64 s[20:21], -1, 0
	s_and_b64 s[22:23], s[20:21], exec
	s_mov_b32 s7, 0x8982000
	s_cselect_b32 s7, s7, 0x7182000
	s_add_u32 s22, s26, s7
	s_addc_u32 s23, s25, 0
	s_add_i32 s7, s6, -16
	v_mov_b32_e32 v160, v163
	v_mov_b32_e32 v24, v162
	s_lshr_b32 s7, s7, 3
	s_add_i32 s96, s7, 1
	v_add_u32_e32 v154, s3, v24
	s_lshl_b64 s[50:51], s[96:97], 11
	v_ashrrev_i32_e32 v155, 31, v154
	s_cmp_gt_i32 s6, 15
	v_lshl_add_u64 v[156:157], v[154:155], 2, s[10:11]
	s_cselect_b32 s7, s51, 0
	s_cselect_b32 s6, s50, 0
	global_load_dword v166, v[156:157], off
	global_load_dword v191, v[156:157], off offset:64
	global_load_dword v192, v[156:157], off offset:128
	global_load_dword v193, v[156:157], off offset:192
	global_load_dword v194, v[156:157], off offset:512
	global_load_dword v195, v[156:157], off offset:576
	global_load_dword v196, v[156:157], off offset:640
	global_load_dword v197, v[156:157], off offset:704
	s_lshl_b64 s[6:7], s[6:7], 2
	s_add_u32 s9, s41, s6
	s_addc_u32 s13, s42, s7
	s_ashr_i32 s3, s2, 31
	s_lshl_b64 s[6:7], s[2:3], 2
	s_add_u32 s3, s9, s6
	s_addc_u32 s7, s13, s7
	v_lshlrev_b32_e32 v158, 3, v160
	s_add_u32 s6, s3, s49
	s_addc_u32 s7, s7, 0
	v_ashrrev_i32_e32 v159, 31, v158
	v_lshl_add_u64 v[24:25], v[158:159], 2, s[6:7]
	global_load_dwordx4 v[36:39], v[24:25], off
	global_load_dwordx4 v[32:35], v[24:25], off offset:16
	global_load_dwordx4 v[28:31], v[24:25], off offset:512
	s_nop 0
	global_load_dwordx4 v[24:27], v[24:25], off offset:528
	s_and_b32 s2, s2, 0x300
	s_or_b32 s2, s2, s44
	v_add_u32_e32 v158, s2, v158
	v_cmp_eq_u32_e64 s[6:7], 0, v160
	v_lshlrev_b64 v[160:161], 11, v[154:155]
	s_cmp_lt_i32 s8, 4
	s_waitcnt vmcnt(0)
	v_ashrrev_i32_e32 v159, 31, v158
	v_lshl_add_u64 v[158:159], v[158:159], 1, s[22:23]
	v_lshl_add_u64 v[160:161], v[158:159], 0, v[160:161]
	v_lshl_add_u64 v[156:157], v[154:155], 2, s[0:1]
	s_and_b64 s[6:7], s[6:7], s[20:21]
	s_mov_b64 s[2:3], 0x8000
	s_mov_b64 s[50:51], 0x28000
	v_mov_b32_e32 v180, 0xc0135761
	v_mov_b32_e32 v181, 0xc0135761
	v_mov_b32_e32 v182, 0xbdd2d3e7
	v_mov_b32_e32 v183, 0xbdd2d3e7
	v_fmamk_f32 v166, v166, 0x3a800000, v225
	v_fmamk_f32 v190, v191, 0x3a800000, v225
	v_fmamk_f32 v192, v192, 0x3a800000, v225
	v_fmamk_f32 v188, v193, 0x3a800000, v225
	v_fmamk_f32 v194, v194, 0x3a800000, v225
	v_fmamk_f32 v186, v195, 0x3a800000, v225
	v_fmamk_f32 v196, v196, 0x3a800000, v225
	v_fmamk_f32 v184, v197, 0x3a800000, v225
	v_rsq_f32_e32 v166, v166
	v_rsq_f32_e32 v190, v190
	v_rsq_f32_e32 v192, v192
	v_rsq_f32_e32 v188, v188
	v_rsq_f32_e32 v194, v194
	v_rsq_f32_e32 v186, v186
	v_rsq_f32_e32 v196, v196
	v_rsq_f32_e32 v184, v184
	v_pk_fma_f32 v[140:141], v[140:141], v[166:167], v[36:37] op_sel_hi:[1,0,1]
	v_pk_fma_f32 v[142:143], v[142:143], v[166:167], v[38:39] op_sel_hi:[1,0,1]
	v_pk_fma_f32 v[136:137], v[136:137], v[166:167], v[32:33] op_sel_hi:[1,0,1]
	v_pk_fma_f32 v[138:139], v[138:139], v[166:167], v[34:35] op_sel_hi:[1,0,1]
	v_pk_fma_f32 v[132:133], v[132:133], v[166:167], v[28:29] op_sel_hi:[1,0,1]
	v_pk_fma_f32 v[134:135], v[134:135], v[166:167], v[30:31] op_sel_hi:[1,0,1]
	v_pk_fma_f32 v[128:129], v[128:129], v[166:167], v[24:25] op_sel_hi:[1,0,1]
	v_pk_fma_f32 v[130:131], v[130:131], v[166:167], v[26:27] op_sel_hi:[1,0,1]
	v_pk_fma_f32 v[124:125], v[124:125], v[190:191], v[36:37] op_sel_hi:[1,0,1]
	v_pk_fma_f32 v[126:127], v[126:127], v[190:191], v[38:39] op_sel_hi:[1,0,1]
	v_pk_fma_f32 v[120:121], v[120:121], v[190:191], v[32:33] op_sel_hi:[1,0,1]
	v_pk_fma_f32 v[122:123], v[122:123], v[190:191], v[34:35] op_sel_hi:[1,0,1]
	v_pk_fma_f32 v[116:117], v[116:117], v[190:191], v[28:29] op_sel_hi:[1,0,1]
	v_pk_fma_f32 v[118:119], v[118:119], v[190:191], v[30:31] op_sel_hi:[1,0,1]
	v_pk_fma_f32 v[112:113], v[112:113], v[190:191], v[24:25] op_sel_hi:[1,0,1]
	v_pk_fma_f32 v[114:115], v[114:115], v[190:191], v[26:27] op_sel_hi:[1,0,1]
	v_pk_fma_f32 v[108:109], v[108:109], v[192:193], v[36:37] op_sel_hi:[1,0,1]
	v_pk_fma_f32 v[110:111], v[110:111], v[192:193], v[38:39] op_sel_hi:[1,0,1]
	v_pk_fma_f32 v[104:105], v[104:105], v[192:193], v[32:33] op_sel_hi:[1,0,1]
	v_pk_fma_f32 v[106:107], v[106:107], v[192:193], v[34:35] op_sel_hi:[1,0,1]
	v_pk_fma_f32 v[100:101], v[100:101], v[192:193], v[28:29] op_sel_hi:[1,0,1]
	v_pk_fma_f32 v[102:103], v[102:103], v[192:193], v[30:31] op_sel_hi:[1,0,1]
	v_pk_fma_f32 v[96:97], v[96:97], v[192:193], v[24:25] op_sel_hi:[1,0,1]
	v_pk_fma_f32 v[98:99], v[98:99], v[192:193], v[26:27] op_sel_hi:[1,0,1]
	v_pk_fma_f32 v[92:93], v[92:93], v[188:189], v[36:37] op_sel_hi:[1,0,1]
	v_pk_fma_f32 v[94:95], v[94:95], v[188:189], v[38:39] op_sel_hi:[1,0,1]
	v_pk_fma_f32 v[88:89], v[88:89], v[188:189], v[32:33] op_sel_hi:[1,0,1]
	v_pk_fma_f32 v[90:91], v[90:91], v[188:189], v[34:35] op_sel_hi:[1,0,1]
	v_pk_fma_f32 v[84:85], v[84:85], v[188:189], v[28:29] op_sel_hi:[1,0,1]
	v_pk_fma_f32 v[86:87], v[86:87], v[188:189], v[30:31] op_sel_hi:[1,0,1]
	v_pk_fma_f32 v[80:81], v[80:81], v[188:189], v[24:25] op_sel_hi:[1,0,1]
	v_pk_fma_f32 v[82:83], v[82:83], v[188:189], v[26:27] op_sel_hi:[1,0,1]
	v_pk_fma_f32 v[76:77], v[76:77], v[194:195], v[36:37] op_sel_hi:[1,0,1]
	v_pk_fma_f32 v[78:79], v[78:79], v[194:195], v[38:39] op_sel_hi:[1,0,1]
	v_pk_fma_f32 v[72:73], v[72:73], v[194:195], v[32:33] op_sel_hi:[1,0,1]
	v_pk_fma_f32 v[74:75], v[74:75], v[194:195], v[34:35] op_sel_hi:[1,0,1]
	v_pk_fma_f32 v[68:69], v[68:69], v[194:195], v[28:29] op_sel_hi:[1,0,1]
	v_pk_fma_f32 v[70:71], v[70:71], v[194:195], v[30:31] op_sel_hi:[1,0,1]
	v_pk_fma_f32 v[64:65], v[64:65], v[194:195], v[24:25] op_sel_hi:[1,0,1]
	v_pk_fma_f32 v[66:67], v[66:67], v[194:195], v[26:27] op_sel_hi:[1,0,1]
	v_pk_fma_f32 v[60:61], v[60:61], v[186:187], v[36:37] op_sel_hi:[1,0,1]
	v_pk_fma_f32 v[62:63], v[62:63], v[186:187], v[38:39] op_sel_hi:[1,0,1]
	v_pk_fma_f32 v[56:57], v[56:57], v[186:187], v[32:33] op_sel_hi:[1,0,1]
	v_pk_fma_f32 v[58:59], v[58:59], v[186:187], v[34:35] op_sel_hi:[1,0,1]
	v_pk_fma_f32 v[52:53], v[52:53], v[186:187], v[28:29] op_sel_hi:[1,0,1]
	v_pk_fma_f32 v[54:55], v[54:55], v[186:187], v[30:31] op_sel_hi:[1,0,1]
	v_pk_fma_f32 v[48:49], v[48:49], v[186:187], v[24:25] op_sel_hi:[1,0,1]
	v_pk_fma_f32 v[50:51], v[50:51], v[186:187], v[26:27] op_sel_hi:[1,0,1]
	v_pk_fma_f32 v[44:45], v[44:45], v[196:197], v[36:37] op_sel_hi:[1,0,1]
	v_pk_fma_f32 v[46:47], v[46:47], v[196:197], v[38:39] op_sel_hi:[1,0,1]
	v_pk_fma_f32 v[40:41], v[40:41], v[196:197], v[32:33] op_sel_hi:[1,0,1]
	v_pk_fma_f32 v[42:43], v[42:43], v[196:197], v[34:35] op_sel_hi:[1,0,1]
	v_pk_fma_f32 v[20:21], v[20:21], v[196:197], v[28:29] op_sel_hi:[1,0,1]
	v_pk_fma_f32 v[22:23], v[22:23], v[196:197], v[30:31] op_sel_hi:[1,0,1]
	v_pk_fma_f32 v[16:17], v[16:17], v[196:197], v[24:25] op_sel_hi:[1,0,1]
	v_pk_fma_f32 v[18:19], v[18:19], v[196:197], v[26:27] op_sel_hi:[1,0,1]
	v_pk_fma_f32 v[12:13], v[12:13], v[184:185], v[36:37] op_sel_hi:[1,0,1]
	v_pk_fma_f32 v[14:15], v[14:15], v[184:185], v[38:39] op_sel_hi:[1,0,1]
	v_pk_fma_f32 v[8:9], v[8:9], v[184:185], v[32:33] op_sel_hi:[1,0,1]
	v_pk_fma_f32 v[10:11], v[10:11], v[184:185], v[34:35] op_sel_hi:[1,0,1]
	v_pk_fma_f32 v[4:5], v[4:5], v[184:185], v[28:29] op_sel_hi:[1,0,1]
	v_pk_fma_f32 v[6:7], v[6:7], v[184:185], v[30:31] op_sel_hi:[1,0,1]
	v_pk_fma_f32 v[0:1], v[0:1], v[184:185], v[24:25] op_sel_hi:[1,0,1]
	v_pk_fma_f32 v[2:3], v[2:3], v[184:185], v[26:27] op_sel_hi:[1,0,1]
	v_pk_mul_f32 v[24:25], v[140:141], v[140:141]
	v_pk_mul_f32 v[26:27], v[142:143], v[142:143]
	v_pk_mul_f32 v[28:29], v[136:137], v[136:137]
	v_pk_mul_f32 v[30:31], v[138:139], v[138:139]
	v_pk_mul_f32 v[32:33], v[132:133], v[132:133]
	v_pk_mul_f32 v[34:35], v[134:135], v[134:135]
	v_pk_mul_f32 v[36:37], v[128:129], v[128:129]
	v_pk_mul_f32 v[38:39], v[130:131], v[130:131]
	v_pk_fma_f32 v[24:25], v[24:25], v[182:183], v[180:181]
	v_pk_fma_f32 v[26:27], v[26:27], v[182:183], v[180:181]
	v_pk_fma_f32 v[28:29], v[28:29], v[182:183], v[180:181]
	v_pk_fma_f32 v[30:31], v[30:31], v[182:183], v[180:181]
	v_pk_fma_f32 v[32:33], v[32:33], v[182:183], v[180:181]
	v_pk_fma_f32 v[34:35], v[34:35], v[182:183], v[180:181]
	v_pk_fma_f32 v[36:37], v[36:37], v[182:183], v[180:181]
	v_pk_fma_f32 v[38:39], v[38:39], v[182:183], v[180:181]
	v_pk_mul_f32 v[24:25], v[24:25], v[140:141]
	v_pk_mul_f32 v[26:27], v[26:27], v[142:143]
	v_pk_mul_f32 v[28:29], v[28:29], v[136:137]
	v_pk_mul_f32 v[30:31], v[30:31], v[138:139]
	v_pk_mul_f32 v[32:33], v[32:33], v[132:133]
	v_pk_mul_f32 v[34:35], v[34:35], v[134:135]
	v_pk_mul_f32 v[36:37], v[36:37], v[128:129]
	v_pk_mul_f32 v[38:39], v[38:39], v[130:131]
	v_exp_f32_e32 v24, v24
	v_exp_f32_e32 v25, v25
	v_exp_f32_e32 v26, v26
	v_exp_f32_e32 v27, v27
	v_exp_f32_e32 v28, v28
	v_exp_f32_e32 v29, v29
	v_exp_f32_e32 v30, v30
	v_exp_f32_e32 v31, v31
	v_exp_f32_e32 v32, v32
	v_exp_f32_e32 v33, v33
	v_exp_f32_e32 v34, v34
	v_exp_f32_e32 v35, v35
	v_exp_f32_e32 v36, v36
	v_exp_f32_e32 v37, v37
	v_exp_f32_e32 v38, v38
	v_exp_f32_e32 v39, v39
	v_pk_add_f32 v[24:25], v[24:25], 1.0 op_sel_hi:[1,0]
	v_pk_add_f32 v[26:27], v[26:27], 1.0 op_sel_hi:[1,0]
	v_pk_add_f32 v[28:29], v[28:29], 1.0 op_sel_hi:[1,0]
	v_pk_add_f32 v[30:31], v[30:31], 1.0 op_sel_hi:[1,0]
	v_pk_add_f32 v[32:33], v[32:33], 1.0 op_sel_hi:[1,0]
	v_pk_add_f32 v[34:35], v[34:35], 1.0 op_sel_hi:[1,0]
	v_pk_add_f32 v[36:37], v[36:37], 1.0 op_sel_hi:[1,0]
	v_pk_add_f32 v[38:39], v[38:39], 1.0 op_sel_hi:[1,0]
	v_rcp_f32_e32 v24, v24
	v_rcp_f32_e32 v25, v25
	v_rcp_f32_e32 v26, v26
	v_rcp_f32_e32 v27, v27
	v_rcp_f32_e32 v28, v28
	v_rcp_f32_e32 v29, v29
	v_rcp_f32_e32 v30, v30
	v_rcp_f32_e32 v31, v31
	v_rcp_f32_e32 v32, v32
	v_rcp_f32_e32 v33, v33
	v_rcp_f32_e32 v34, v34
	v_rcp_f32_e32 v35, v35
	v_rcp_f32_e32 v36, v36
	v_rcp_f32_e32 v37, v37
	v_rcp_f32_e32 v38, v38
	v_rcp_f32_e32 v39, v39
	v_pk_mul_f32 v[140:141], v[140:141], v[24:25]
	v_pk_mul_f32 v[142:143], v[142:143], v[26:27]
	v_pk_mul_f32 v[136:137], v[136:137], v[28:29]
	v_pk_mul_f32 v[138:139], v[138:139], v[30:31]
	v_pk_mul_f32 v[132:133], v[132:133], v[32:33]
	v_pk_mul_f32 v[134:135], v[134:135], v[34:35]
	v_pk_mul_f32 v[128:129], v[128:129], v[36:37]
	v_pk_mul_f32 v[130:131], v[130:131], v[38:39]
	v_cvt_pk_bf16_f32 v24, v140, v141
	v_cvt_pk_bf16_f32 v25, v142, v143
	v_cvt_pk_bf16_f32 v26, v136, v137
	v_cvt_pk_bf16_f32 v27, v138, v139
	v_cvt_pk_bf16_f32 v28, v132, v133
	v_cvt_pk_bf16_f32 v29, v134, v135
	v_cvt_pk_bf16_f32 v30, v128, v129
	v_cvt_pk_bf16_f32 v31, v130, v131
	global_store_dwordx4 v[160:161], v[24:27], off
	global_store_dwordx4 v[160:161], v[28:31], off offset:256
	s_and_b64 vcc, exec, s[20:21]
	s_cbranch_vccz .Lio_skip_0
	v_pk_mul_f32 v[32:33], v[140:141], v[140:141]
	v_pk_fma_f32 v[32:33], v[142:143], v[142:143], v[32:33]
	v_pk_fma_f32 v[32:33], v[136:137], v[136:137], v[32:33]
	v_pk_fma_f32 v[32:33], v[138:139], v[138:139], v[32:33]
	v_pk_fma_f32 v[32:33], v[132:133], v[132:133], v[32:33]
	v_pk_fma_f32 v[32:33], v[134:135], v[134:135], v[32:33]
	v_pk_fma_f32 v[32:33], v[128:129], v[128:129], v[32:33]
	v_pk_fma_f32 v[32:33], v[130:131], v[130:131], v[32:33]
	s_nop 0
	v_add_f32_e32 v32, v32, v33
	v_mov_b32_e32 v33, v32
	s_nop 1
	v_permlane16_swap_b32_e32 v32, v33
	v_add_f32_e32 v32, v32, v33
	v_mov_b32_e32 v33, v32
	s_nop 1
	v_permlane32_swap_b32_e32 v32, v33
	s_and_saveexec_b64 vcc, s[6:7]
	v_add_f32_e32 v32, v32, v33
	global_atomic_add_f32 v[156:157], v32, off
	s_mov_b64 exec, vcc

.Lie_done_b:
.LBB0_354:
	s_ashr_i32 s31, s30, 31
	v_cmp_lt_i64_e32 vcc, s[8:9], v[170:171]
	s_lshl_b64 s[8:9], s[30:31], 19
	s_add_u32 s34, s52, s8
	s_addc_u32 s35, s53, s9
	s_and_b64 s[8:9], vcc, exec
	s_cselect_b32 s1, s35, s7
	s_cselect_b32 s31, s34, s6
	s_ashr_i32 s29, s28, 31
	s_lshl_b64 s[8:9], s[28:29], 19
	s_add_u32 s36, s43, s8
	s_addc_u32 s37, s42, s9
	s_and_b64 s[8:9], vcc, exec
	s_cselect_b32 s29, s37, s3
	s_cselect_b32 s38, s36, s2
	s_add_u32 s6, s6, 0x40080
	s_addc_u32 s7, s7, 0
	s_add_u32 s39, s2, 0x100
	s_addc_u32 s40, s3, 0
	s_mov_b32 s41, -2
	s_add_u32 s2, s6, 0xfffc0080
	s_addc_u32 s3, s7, -1
	ds_read_b128 v[128:131], v208
	ds_read_b128 v[132:135], v208 offset:1024
	ds_read_b128 v[136:139], v208 offset:2048
	ds_read_b128 v[140:143], v208 offset:3072
	s_cmp_eq_u32 s41, 12
	s_cselect_b32 s9, s1, s3
	s_cselect_b32 s8, s31, s2
	s_cselect_b32 s3, s29, s40
	s_cselect_b32 s2, s38, s39
	s_add_i32 m0, s21, 0xc000
	ds_read_b128 v[144:147], v209
	ds_read_b128 v[148:151], v209 offset:1024
	ds_read_b128 v[152:155], v209 offset:2048
	ds_read_b128 v[156:159], v209 offset:3072
	ds_read_b128 v[180:183], v209 offset:4096
	ds_read_b128 v[184:187], v209 offset:5120
	ds_read_b128 v[188:191], v209 offset:6144
	global_load_lds_dwordx4 v164, s[6:7]
	s_add_i32 m0, s21, 0xe000
	ds_read_b128 v[192:195], v209 offset:7168
	global_load_lds_dwordx4 v166, s[6:7]
	s_waitcnt lgkmcnt(11)
	ds_read_b128 v[196:199], v208 offset:16384
	ds_read_b128 v[200:203], v208 offset:17408
	ds_read_b128 v[210:213], v208 offset:18432
	ds_read_b128 v[214:217], v208 offset:19456
	s_waitcnt lgkmcnt(0)
	s_barrier
	v_mfma_f32_16x16x32_bf16 v[124:127], v[128:131], v[144:147], 0
	v_mfma_f32_16x16x32_bf16 v[120:123], v[136:139], v[144:147], 0
	v_mfma_f32_16x16x32_bf16 v[116:119], v[128:131], v[152:155], 0
	v_mfma_f32_16x16x32_bf16 v[112:115], v[136:139], v[152:155], 0
	v_mfma_f32_16x16x32_bf16 v[100:103], v[128:131], v[180:183], 0
	v_mfma_f32_16x16x32_bf16 v[96:99], v[136:139], v[180:183], 0
	v_mfma_f32_16x16x32_bf16 v[84:87], v[128:131], v[188:191], 0
	v_mfma_f32_16x16x32_bf16 v[80:83], v[136:139], v[188:191], 0
	v_mfma_f32_16x16x32_bf16 v[124:127], v[132:135], v[148:151], v[124:127]
	v_mfma_f32_16x16x32_bf16 v[120:123], v[140:143], v[148:151], v[120:123]
	v_mfma_f32_16x16x32_bf16 v[116:119], v[132:135], v[156:159], v[116:119]
	v_mfma_f32_16x16x32_bf16 v[112:115], v[140:143], v[156:159], v[112:115]
	v_mfma_f32_16x16x32_bf16 v[100:103], v[132:135], v[184:187], v[100:103]
	v_mfma_f32_16x16x32_bf16 v[96:99], v[140:143], v[184:187], v[96:99]
	v_mfma_f32_16x16x32_bf16 v[84:87], v[132:135], v[192:195], v[84:87]
	v_mfma_f32_16x16x32_bf16 v[80:83], v[140:143], v[192:195], v[80:83]
	v_mfma_f32_16x16x32_bf16 v[108:111], v[196:199], v[144:147], 0
	v_mfma_f32_16x16x32_bf16 v[104:107], v[210:213], v[144:147], 0
	v_mfma_f32_16x16x32_bf16 v[92:95], v[196:199], v[152:155], 0
	v_mfma_f32_16x16x32_bf16 v[88:91], v[210:213], v[152:155], 0
	v_mfma_f32_16x16x32_bf16 v[76:79], v[196:199], v[180:183], 0
	v_mfma_f32_16x16x32_bf16 v[72:75], v[210:213], v[180:183], 0
	v_mfma_f32_16x16x32_bf16 v[68:71], v[196:199], v[188:191], 0
	v_mfma_f32_16x16x32_bf16 v[64:67], v[210:213], v[188:191], 0
	v_mfma_f32_16x16x32_bf16 v[108:111], v[200:203], v[148:151], v[108:111]
	v_mfma_f32_16x16x32_bf16 v[104:107], v[214:217], v[148:151], v[104:107]
	v_mfma_f32_16x16x32_bf16 v[92:95], v[200:203], v[156:159], v[92:95]
	v_mfma_f32_16x16x32_bf16 v[88:91], v[214:217], v[156:159], v[88:91]
	v_mfma_f32_16x16x32_bf16 v[76:79], v[200:203], v[184:187], v[76:79]
	v_mfma_f32_16x16x32_bf16 v[72:75], v[214:217], v[184:187], v[72:75]
	v_mfma_f32_16x16x32_bf16 v[68:71], v[200:203], v[192:195], v[68:71]
	v_mfma_f32_16x16x32_bf16 v[64:67], v[214:217], v[192:195], v[64:67]
	s_barrier
	s_add_u32 s98, s2, 0x80
	s_addc_u32 s99, s3, 0
	s_add_i32 m0, s54, 0x10000
	ds_read_b128 v[144:147], v209 offset:16384
	global_load_lds_dwordx4 v160, s[2:3]
	s_add_i32 m0, s54, 0x12000
	ds_read_b128 v[148:151], v209 offset:17408
	global_load_lds_dwordx4 v162, s[2:3]
	s_mov_b32 m0, s21
	s_add_u32 s100, s8, 0x80
	s_addc_u32 s101, s9, 0
	ds_read_b128 v[152:155], v209 offset:18432
	ds_read_b128 v[156:159], v209 offset:19456
	ds_read_b128 v[180:183], v209 offset:20480
	ds_read_b128 v[184:187], v209 offset:21504
	ds_read_b128 v[188:191], v209 offset:22528
	global_load_lds_dwordx4 v160, s[8:9]
	s_mov_b32 m0, s55
	ds_read_b128 v[192:195], v209 offset:23552
	global_load_lds_dwordx4 v162, s[8:9]
	s_add_i32 m0, s54, 0x14000
	s_add_u32 s64, s2, 0x40000
	s_addc_u32 s65, s3, 0
	global_load_lds_dwordx4 v160, s[64:65]
	s_add_i32 m0, s54, 0x16000
	s_add_u32 s8, s8, 0x40000
	s_addc_u32 s9, s9, 0
	global_load_lds_dwordx4 v162, s[64:65]
	s_waitcnt lgkmcnt(0)
	s_waitcnt vmcnt(6)
	s_barrier
	v_mfma_f32_16x16x32_bf16 v[60:63], v[128:131], v[144:147], 0
	v_mfma_f32_16x16x32_bf16 v[56:59], v[136:139], v[144:147], 0
	v_mfma_f32_16x16x32_bf16 v[52:55], v[128:131], v[152:155], 0
	v_mfma_f32_16x16x32_bf16 v[48:51], v[136:139], v[152:155], 0
	v_mfma_f32_16x16x32_bf16 v[36:39], v[128:131], v[180:183], 0
	v_mfma_f32_16x16x32_bf16 v[32:35], v[136:139], v[180:183], 0
	v_mfma_f32_16x16x32_bf16 v[20:23], v[128:131], v[188:191], 0
	v_mfma_f32_16x16x32_bf16 v[16:19], v[136:139], v[188:191], 0
	v_mfma_f32_16x16x32_bf16 v[60:63], v[132:135], v[148:151], v[60:63]
	v_mfma_f32_16x16x32_bf16 v[56:59], v[140:143], v[148:151], v[56:59]
	v_mfma_f32_16x16x32_bf16 v[52:55], v[132:135], v[156:159], v[52:55]
	v_mfma_f32_16x16x32_bf16 v[48:51], v[140:143], v[156:159], v[48:51]
	v_mfma_f32_16x16x32_bf16 v[36:39], v[132:135], v[184:187], v[36:39]
	v_mfma_f32_16x16x32_bf16 v[32:35], v[140:143], v[184:187], v[32:35]
	v_mfma_f32_16x16x32_bf16 v[20:23], v[132:135], v[192:195], v[20:23]
	v_mfma_f32_16x16x32_bf16 v[16:19], v[140:143], v[192:195], v[16:19]
	v_mfma_f32_16x16x32_bf16 v[44:47], v[196:199], v[144:147], 0
	v_mfma_f32_16x16x32_bf16 v[40:43], v[210:213], v[144:147], 0
	v_mfma_f32_16x16x32_bf16 v[28:31], v[196:199], v[152:155], 0
	v_mfma_f32_16x16x32_bf16 v[24:27], v[210:213], v[152:155], 0
	v_mfma_f32_16x16x32_bf16 v[12:15], v[196:199], v[180:183], 0
	v_mfma_f32_16x16x32_bf16 v[8:11], v[210:213], v[180:183], 0
	v_mfma_f32_16x16x32_bf16 v[4:7], v[196:199], v[188:191], 0
	v_mfma_f32_16x16x32_bf16 v[0:3], v[210:213], v[188:191], 0
	v_mfma_f32_16x16x32_bf16 v[44:47], v[200:203], v[148:151], v[44:47]
	v_mfma_f32_16x16x32_bf16 v[40:43], v[214:217], v[148:151], v[40:43]
	v_mfma_f32_16x16x32_bf16 v[28:31], v[200:203], v[156:159], v[28:31]
	v_mfma_f32_16x16x32_bf16 v[24:27], v[214:217], v[156:159], v[24:27]
	v_mfma_f32_16x16x32_bf16 v[12:15], v[200:203], v[184:187], v[12:15]
	v_mfma_f32_16x16x32_bf16 v[8:11], v[214:217], v[184:187], v[8:11]
	v_mfma_f32_16x16x32_bf16 v[4:7], v[200:203], v[192:195], v[4:7]
	v_mfma_f32_16x16x32_bf16 v[0:3], v[214:217], v[192:195], v[0:3]
	s_barrier
	ds_read_b128 v[128:131], v208 offset:32768
	ds_read_b128 v[132:135], v208 offset:33792
	ds_read_b128 v[136:139], v208 offset:34816
	ds_read_b128 v[140:143], v208 offset:35840
	s_mov_b32 m0, s56
	ds_read_b128 v[144:147], v209 offset:32768
	ds_read_b128 v[148:151], v209 offset:33792
	ds_read_b128 v[152:155], v209 offset:34816
	ds_read_b128 v[156:159], v209 offset:35840
	ds_read_b128 v[180:183], v209 offset:36864
	ds_read_b128 v[184:187], v209 offset:37888
	ds_read_b128 v[188:191], v209 offset:38912
	global_load_lds_dwordx4 v160, s[8:9]
	s_mov_b32 m0, s57
	ds_read_b128 v[192:195], v209 offset:39936
	global_load_lds_dwordx4 v162, s[8:9]
	s_waitcnt lgkmcnt(11)
	ds_read_b128 v[196:199], v208 offset:49152
	ds_read_b128 v[200:203], v208 offset:50176
	ds_read_b128 v[210:213], v208 offset:51200
	ds_read_b128 v[214:217], v208 offset:52224
	s_waitcnt lgkmcnt(0)
	s_barrier
	v_mfma_f32_16x16x32_bf16 v[124:127], v[128:131], v[144:147], v[124:127]
	v_mfma_f32_16x16x32_bf16 v[120:123], v[136:139], v[144:147], v[120:123]
	v_mfma_f32_16x16x32_bf16 v[116:119], v[128:131], v[152:155], v[116:119]
	v_mfma_f32_16x16x32_bf16 v[112:115], v[136:139], v[152:155], v[112:115]
	v_mfma_f32_16x16x32_bf16 v[100:103], v[128:131], v[180:183], v[100:103]
	v_mfma_f32_16x16x32_bf16 v[96:99], v[136:139], v[180:183], v[96:99]
	v_mfma_f32_16x16x32_bf16 v[84:87], v[128:131], v[188:191], v[84:87]
	v_mfma_f32_16x16x32_bf16 v[80:83], v[136:139], v[188:191], v[80:83]
	v_mfma_f32_16x16x32_bf16 v[124:127], v[132:135], v[148:151], v[124:127]
	v_mfma_f32_16x16x32_bf16 v[120:123], v[140:143], v[148:151], v[120:123]
	v_mfma_f32_16x16x32_bf16 v[116:119], v[132:135], v[156:159], v[116:119]
	v_mfma_f32_16x16x32_bf16 v[112:115], v[140:143], v[156:159], v[112:115]
	v_mfma_f32_16x16x32_bf16 v[100:103], v[132:135], v[184:187], v[100:103]
	v_mfma_f32_16x16x32_bf16 v[96:99], v[140:143], v[184:187], v[96:99]
	v_mfma_f32_16x16x32_bf16 v[84:87], v[132:135], v[192:195], v[84:87]
	v_mfma_f32_16x16x32_bf16 v[80:83], v[140:143], v[192:195], v[80:83]
	v_mfma_f32_16x16x32_bf16 v[108:111], v[196:199], v[144:147], v[108:111]
	v_mfma_f32_16x16x32_bf16 v[104:107], v[210:213], v[144:147], v[104:107]
	v_mfma_f32_16x16x32_bf16 v[92:95], v[196:199], v[152:155], v[92:95]
	v_mfma_f32_16x16x32_bf16 v[88:91], v[210:213], v[152:155], v[88:91]
	v_mfma_f32_16x16x32_bf16 v[76:79], v[196:199], v[180:183], v[76:79]
	v_mfma_f32_16x16x32_bf16 v[72:75], v[210:213], v[180:183], v[72:75]
	v_mfma_f32_16x16x32_bf16 v[68:71], v[196:199], v[188:191], v[68:71]
	v_mfma_f32_16x16x32_bf16 v[64:67], v[210:213], v[188:191], v[64:67]
	v_mfma_f32_16x16x32_bf16 v[108:111], v[200:203], v[148:151], v[108:111]
	v_mfma_f32_16x16x32_bf16 v[104:107], v[214:217], v[148:151], v[104:107]
	v_mfma_f32_16x16x32_bf16 v[92:95], v[200:203], v[156:159], v[92:95]
	v_mfma_f32_16x16x32_bf16 v[88:91], v[214:217], v[156:159], v[88:91]
	v_mfma_f32_16x16x32_bf16 v[76:79], v[200:203], v[184:187], v[76:79]
	v_mfma_f32_16x16x32_bf16 v[72:75], v[214:217], v[184:187], v[72:75]
	v_mfma_f32_16x16x32_bf16 v[68:71], v[200:203], v[192:195], v[68:71]
	v_mfma_f32_16x16x32_bf16 v[64:67], v[214:217], v[192:195], v[64:67]
	s_barrier
	s_add_i32 m0, s54, 0x18000
	ds_read_b128 v[144:147], v209 offset:49152
	global_load_lds_dwordx4 v160, s[98:99]
	s_add_i32 m0, s54, 0x1a000
	ds_read_b128 v[148:151], v209 offset:50176
	global_load_lds_dwordx4 v162, s[98:99]
	s_mov_b32 m0, s60
	ds_read_b128 v[152:155], v209 offset:51200
	ds_read_b128 v[156:159], v209 offset:52224
	ds_read_b128 v[180:183], v209 offset:53248
	ds_read_b128 v[184:187], v209 offset:54272
	ds_read_b128 v[188:191], v209 offset:55296
	global_load_lds_dwordx4 v160, s[100:101]
	s_mov_b32 m0, s61
	ds_read_b128 v[192:195], v209 offset:56320
	global_load_lds_dwordx4 v162, s[100:101]
	s_add_i32 m0, s54, 0x1c000
	s_add_u32 s2, s2, 0x40080
	s_addc_u32 s3, s3, 0
	global_load_lds_dwordx4 v160, s[2:3]
	s_add_i32 m0, s54, 0x1e000
	s_add_i32 s41, s41, 2
	global_load_lds_dwordx4 v162, s[2:3]
	s_waitcnt lgkmcnt(0)
	s_waitcnt vmcnt(6)
	s_barrier
	v_mfma_f32_16x16x32_bf16 v[60:63], v[128:131], v[144:147], v[60:63]
	v_mfma_f32_16x16x32_bf16 v[56:59], v[136:139], v[144:147], v[56:59]
	v_mfma_f32_16x16x32_bf16 v[52:55], v[128:131], v[152:155], v[52:55]
	v_mfma_f32_16x16x32_bf16 v[48:51], v[136:139], v[152:155], v[48:51]
	v_mfma_f32_16x16x32_bf16 v[36:39], v[128:131], v[180:183], v[36:39]
	v_mfma_f32_16x16x32_bf16 v[32:35], v[136:139], v[180:183], v[32:35]
	v_mfma_f32_16x16x32_bf16 v[20:23], v[128:131], v[188:191], v[20:23]
	v_mfma_f32_16x16x32_bf16 v[16:19], v[136:139], v[188:191], v[16:19]
	v_mfma_f32_16x16x32_bf16 v[60:63], v[132:135], v[148:151], v[60:63]
	v_mfma_f32_16x16x32_bf16 v[56:59], v[140:143], v[148:151], v[56:59]
	v_mfma_f32_16x16x32_bf16 v[52:55], v[132:135], v[156:159], v[52:55]
	v_mfma_f32_16x16x32_bf16 v[48:51], v[140:143], v[156:159], v[48:51]
	v_mfma_f32_16x16x32_bf16 v[36:39], v[132:135], v[184:187], v[36:39]
	v_mfma_f32_16x16x32_bf16 v[32:35], v[140:143], v[184:187], v[32:35]
	v_mfma_f32_16x16x32_bf16 v[20:23], v[132:135], v[192:195], v[20:23]
	v_mfma_f32_16x16x32_bf16 v[16:19], v[140:143], v[192:195], v[16:19]
	v_mfma_f32_16x16x32_bf16 v[44:47], v[196:199], v[144:147], v[44:47]
	v_mfma_f32_16x16x32_bf16 v[40:43], v[210:213], v[144:147], v[40:43]
	v_mfma_f32_16x16x32_bf16 v[28:31], v[196:199], v[152:155], v[28:31]
	v_mfma_f32_16x16x32_bf16 v[24:27], v[210:213], v[152:155], v[24:27]
	v_mfma_f32_16x16x32_bf16 v[12:15], v[196:199], v[180:183], v[12:15]
	v_mfma_f32_16x16x32_bf16 v[8:11], v[210:213], v[180:183], v[8:11]
	v_mfma_f32_16x16x32_bf16 v[4:7], v[196:199], v[188:191], v[4:7]
	v_mfma_f32_16x16x32_bf16 v[0:3], v[210:213], v[188:191], v[0:3]
	v_mfma_f32_16x16x32_bf16 v[44:47], v[200:203], v[148:151], v[44:47]
	v_mfma_f32_16x16x32_bf16 v[40:43], v[214:217], v[148:151], v[40:43]
	v_mfma_f32_16x16x32_bf16 v[28:31], v[200:203], v[156:159], v[28:31]
	v_mfma_f32_16x16x32_bf16 v[24:27], v[214:217], v[156:159], v[24:27]
	v_mfma_f32_16x16x32_bf16 v[12:15], v[200:203], v[184:187], v[12:15]
	v_mfma_f32_16x16x32_bf16 v[8:11], v[214:217], v[184:187], v[8:11]
	v_mfma_f32_16x16x32_bf16 v[4:7], v[200:203], v[192:195], v[4:7]
	v_mfma_f32_16x16x32_bf16 v[0:3], v[214:217], v[192:195], v[0:3]
	s_add_u32 s6, s6, 0x100
	s_addc_u32 s7, s7, 0
	s_add_u32 s39, s39, 0x100
	s_addc_u32 s40, s40, 0
	s_cmp_gt_u32 s41, 13
	s_barrier
.LBB0_355:
	s_add_u32 s2, s6, 0xfffc0080
	s_addc_u32 s3, s7, -1
	ds_read_b128 v[128:131], v208
	ds_read_b128 v[132:135], v208 offset:1024
	ds_read_b128 v[136:139], v208 offset:2048
	ds_read_b128 v[140:143], v208 offset:3072
	s_cmp_eq_u32 s41, 12
	s_cselect_b32 s9, s1, s3
	s_cselect_b32 s8, s31, s2
	s_cselect_b32 s3, s29, s40
	s_cselect_b32 s2, s38, s39
	s_add_i32 m0, s21, 0xc000
	ds_read_b128 v[144:147], v209
	ds_read_b128 v[148:151], v209 offset:1024
	ds_read_b128 v[152:155], v209 offset:2048
	ds_read_b128 v[156:159], v209 offset:3072
	ds_read_b128 v[180:183], v209 offset:4096
	ds_read_b128 v[184:187], v209 offset:5120
	ds_read_b128 v[188:191], v209 offset:6144
	global_load_lds_dwordx4 v164, s[6:7]
	s_add_i32 m0, s21, 0xe000
	ds_read_b128 v[192:195], v209 offset:7168
	global_load_lds_dwordx4 v166, s[6:7]
	s_waitcnt lgkmcnt(11)
	ds_read_b128 v[196:199], v208 offset:16384
	ds_read_b128 v[200:203], v208 offset:17408
	ds_read_b128 v[210:213], v208 offset:18432
	ds_read_b128 v[214:217], v208 offset:19456
	s_waitcnt lgkmcnt(0)
	s_barrier
	v_mfma_f32_16x16x32_bf16 v[124:127], v[128:131], v[144:147], v[124:127]
	v_mfma_f32_16x16x32_bf16 v[120:123], v[136:139], v[144:147], v[120:123]
	v_mfma_f32_16x16x32_bf16 v[116:119], v[128:131], v[152:155], v[116:119]
	v_mfma_f32_16x16x32_bf16 v[112:115], v[136:139], v[152:155], v[112:115]
	v_mfma_f32_16x16x32_bf16 v[100:103], v[128:131], v[180:183], v[100:103]
	v_mfma_f32_16x16x32_bf16 v[96:99], v[136:139], v[180:183], v[96:99]
	v_mfma_f32_16x16x32_bf16 v[84:87], v[128:131], v[188:191], v[84:87]
	v_mfma_f32_16x16x32_bf16 v[80:83], v[136:139], v[188:191], v[80:83]
	v_mfma_f32_16x16x32_bf16 v[124:127], v[132:135], v[148:151], v[124:127]
	v_mfma_f32_16x16x32_bf16 v[120:123], v[140:143], v[148:151], v[120:123]
	v_mfma_f32_16x16x32_bf16 v[116:119], v[132:135], v[156:159], v[116:119]
	v_mfma_f32_16x16x32_bf16 v[112:115], v[140:143], v[156:159], v[112:115]
	v_mfma_f32_16x16x32_bf16 v[100:103], v[132:135], v[184:187], v[100:103]
	v_mfma_f32_16x16x32_bf16 v[96:99], v[140:143], v[184:187], v[96:99]
	v_mfma_f32_16x16x32_bf16 v[84:87], v[132:135], v[192:195], v[84:87]
	v_mfma_f32_16x16x32_bf16 v[80:83], v[140:143], v[192:195], v[80:83]
	v_mfma_f32_16x16x32_bf16 v[108:111], v[196:199], v[144:147], v[108:111]
	v_mfma_f32_16x16x32_bf16 v[104:107], v[210:213], v[144:147], v[104:107]
	v_mfma_f32_16x16x32_bf16 v[92:95], v[196:199], v[152:155], v[92:95]
	v_mfma_f32_16x16x32_bf16 v[88:91], v[210:213], v[152:155], v[88:91]
	v_mfma_f32_16x16x32_bf16 v[76:79], v[196:199], v[180:183], v[76:79]
	v_mfma_f32_16x16x32_bf16 v[72:75], v[210:213], v[180:183], v[72:75]
	v_mfma_f32_16x16x32_bf16 v[68:71], v[196:199], v[188:191], v[68:71]
	v_mfma_f32_16x16x32_bf16 v[64:67], v[210:213], v[188:191], v[64:67]
	v_mfma_f32_16x16x32_bf16 v[108:111], v[200:203], v[148:151], v[108:111]
	v_mfma_f32_16x16x32_bf16 v[104:107], v[214:217], v[148:151], v[104:107]
	v_mfma_f32_16x16x32_bf16 v[92:95], v[200:203], v[156:159], v[92:95]
	v_mfma_f32_16x16x32_bf16 v[88:91], v[214:217], v[156:159], v[88:91]
	v_mfma_f32_16x16x32_bf16 v[76:79], v[200:203], v[184:187], v[76:79]
	v_mfma_f32_16x16x32_bf16 v[72:75], v[214:217], v[184:187], v[72:75]
	v_mfma_f32_16x16x32_bf16 v[68:71], v[200:203], v[192:195], v[68:71]
	v_mfma_f32_16x16x32_bf16 v[64:67], v[214:217], v[192:195], v[64:67]
	s_barrier
	s_add_u32 s98, s2, 0x80
	s_addc_u32 s99, s3, 0
	s_add_i32 m0, s54, 0x10000
	ds_read_b128 v[144:147], v209 offset:16384
	global_load_lds_dwordx4 v160, s[2:3]
	s_add_i32 m0, s54, 0x12000
	ds_read_b128 v[148:151], v209 offset:17408
	global_load_lds_dwordx4 v162, s[2:3]
	s_mov_b32 m0, s21
	s_add_u32 s100, s8, 0x80
	s_addc_u32 s101, s9, 0
	ds_read_b128 v[152:155], v209 offset:18432
	ds_read_b128 v[156:159], v209 offset:19456
	ds_read_b128 v[180:183], v209 offset:20480
	ds_read_b128 v[184:187], v209 offset:21504
	ds_read_b128 v[188:191], v209 offset:22528
	global_load_lds_dwordx4 v160, s[8:9]
	s_mov_b32 m0, s55
	ds_read_b128 v[192:195], v209 offset:23552
	global_load_lds_dwordx4 v162, s[8:9]
	s_add_i32 m0, s54, 0x14000
	s_add_u32 s64, s2, 0x40000
	s_addc_u32 s65, s3, 0
	global_load_lds_dwordx4 v160, s[64:65]
	s_add_i32 m0, s54, 0x16000
	s_add_u32 s8, s8, 0x40000
	s_addc_u32 s9, s9, 0
	global_load_lds_dwordx4 v162, s[64:65]
	s_waitcnt lgkmcnt(0)
	s_waitcnt vmcnt(6)
	s_barrier
	v_mfma_f32_16x16x32_bf16 v[60:63], v[128:131], v[144:147], v[60:63]
	v_mfma_f32_16x16x32_bf16 v[56:59], v[136:139], v[144:147], v[56:59]
	v_mfma_f32_16x16x32_bf16 v[52:55], v[128:131], v[152:155], v[52:55]
	v_mfma_f32_16x16x32_bf16 v[48:51], v[136:139], v[152:155], v[48:51]
	v_mfma_f32_16x16x32_bf16 v[36:39], v[128:131], v[180:183], v[36:39]
	v_mfma_f32_16x16x32_bf16 v[32:35], v[136:139], v[180:183], v[32:35]
	v_mfma_f32_16x16x32_bf16 v[20:23], v[128:131], v[188:191], v[20:23]
	v_mfma_f32_16x16x32_bf16 v[16:19], v[136:139], v[188:191], v[16:19]
	v_mfma_f32_16x16x32_bf16 v[60:63], v[132:135], v[148:151], v[60:63]
	v_mfma_f32_16x16x32_bf16 v[56:59], v[140:143], v[148:151], v[56:59]
	v_mfma_f32_16x16x32_bf16 v[52:55], v[132:135], v[156:159], v[52:55]
	v_mfma_f32_16x16x32_bf16 v[48:51], v[140:143], v[156:159], v[48:51]
	v_mfma_f32_16x16x32_bf16 v[36:39], v[132:135], v[184:187], v[36:39]
	v_mfma_f32_16x16x32_bf16 v[32:35], v[140:143], v[184:187], v[32:35]
	v_mfma_f32_16x16x32_bf16 v[20:23], v[132:135], v[192:195], v[20:23]
	v_mfma_f32_16x16x32_bf16 v[16:19], v[140:143], v[192:195], v[16:19]
	v_mfma_f32_16x16x32_bf16 v[44:47], v[196:199], v[144:147], v[44:47]
	v_mfma_f32_16x16x32_bf16 v[40:43], v[210:213], v[144:147], v[40:43]
	v_mfma_f32_16x16x32_bf16 v[28:31], v[196:199], v[152:155], v[28:31]
	v_mfma_f32_16x16x32_bf16 v[24:27], v[210:213], v[152:155], v[24:27]
	v_mfma_f32_16x16x32_bf16 v[12:15], v[196:199], v[180:183], v[12:15]
	v_mfma_f32_16x16x32_bf16 v[8:11], v[210:213], v[180:183], v[8:11]
	v_mfma_f32_16x16x32_bf16 v[4:7], v[196:199], v[188:191], v[4:7]
	v_mfma_f32_16x16x32_bf16 v[0:3], v[210:213], v[188:191], v[0:3]
	v_mfma_f32_16x16x32_bf16 v[44:47], v[200:203], v[148:151], v[44:47]
	v_mfma_f32_16x16x32_bf16 v[40:43], v[214:217], v[148:151], v[40:43]
	v_mfma_f32_16x16x32_bf16 v[28:31], v[200:203], v[156:159], v[28:31]
	v_mfma_f32_16x16x32_bf16 v[24:27], v[214:217], v[156:159], v[24:27]
	v_mfma_f32_16x16x32_bf16 v[12:15], v[200:203], v[184:187], v[12:15]
	v_mfma_f32_16x16x32_bf16 v[8:11], v[214:217], v[184:187], v[8:11]
	v_mfma_f32_16x16x32_bf16 v[4:7], v[200:203], v[192:195], v[4:7]
	v_mfma_f32_16x16x32_bf16 v[0:3], v[214:217], v[192:195], v[0:3]
	s_barrier
	ds_read_b128 v[128:131], v208 offset:32768
	ds_read_b128 v[132:135], v208 offset:33792
	ds_read_b128 v[136:139], v208 offset:34816
	ds_read_b128 v[140:143], v208 offset:35840
	s_mov_b32 m0, s56
	ds_read_b128 v[144:147], v209 offset:32768
	ds_read_b128 v[148:151], v209 offset:33792
	ds_read_b128 v[152:155], v209 offset:34816
	ds_read_b128 v[156:159], v209 offset:35840
	ds_read_b128 v[180:183], v209 offset:36864
	ds_read_b128 v[184:187], v209 offset:37888
	ds_read_b128 v[188:191], v209 offset:38912
	global_load_lds_dwordx4 v160, s[8:9]
	s_mov_b32 m0, s57
	ds_read_b128 v[192:195], v209 offset:39936
	global_load_lds_dwordx4 v162, s[8:9]
	s_waitcnt lgkmcnt(11)
	ds_read_b128 v[196:199], v208 offset:49152
	ds_read_b128 v[200:203], v208 offset:50176
	ds_read_b128 v[210:213], v208 offset:51200
	ds_read_b128 v[214:217], v208 offset:52224
	s_waitcnt lgkmcnt(0)
	s_barrier
	v_mfma_f32_16x16x32_bf16 v[124:127], v[128:131], v[144:147], v[124:127]
	v_mfma_f32_16x16x32_bf16 v[120:123], v[136:139], v[144:147], v[120:123]
	v_mfma_f32_16x16x32_bf16 v[116:119], v[128:131], v[152:155], v[116:119]
	v_mfma_f32_16x16x32_bf16 v[112:115], v[136:139], v[152:155], v[112:115]
	v_mfma_f32_16x16x32_bf16 v[100:103], v[128:131], v[180:183], v[100:103]
	v_mfma_f32_16x16x32_bf16 v[96:99], v[136:139], v[180:183], v[96:99]
	v_mfma_f32_16x16x32_bf16 v[84:87], v[128:131], v[188:191], v[84:87]
	v_mfma_f32_16x16x32_bf16 v[80:83], v[136:139], v[188:191], v[80:83]
	v_mfma_f32_16x16x32_bf16 v[124:127], v[132:135], v[148:151], v[124:127]
	v_mfma_f32_16x16x32_bf16 v[120:123], v[140:143], v[148:151], v[120:123]
	v_mfma_f32_16x16x32_bf16 v[116:119], v[132:135], v[156:159], v[116:119]
	v_mfma_f32_16x16x32_bf16 v[112:115], v[140:143], v[156:159], v[112:115]
	v_mfma_f32_16x16x32_bf16 v[100:103], v[132:135], v[184:187], v[100:103]
	v_mfma_f32_16x16x32_bf16 v[96:99], v[140:143], v[184:187], v[96:99]
	v_mfma_f32_16x16x32_bf16 v[84:87], v[132:135], v[192:195], v[84:87]
	v_mfma_f32_16x16x32_bf16 v[80:83], v[140:143], v[192:195], v[80:83]
	v_mfma_f32_16x16x32_bf16 v[108:111], v[196:199], v[144:147], v[108:111]
	v_mfma_f32_16x16x32_bf16 v[104:107], v[210:213], v[144:147], v[104:107]
	v_mfma_f32_16x16x32_bf16 v[92:95], v[196:199], v[152:155], v[92:95]
	v_mfma_f32_16x16x32_bf16 v[88:91], v[210:213], v[152:155], v[88:91]
	v_mfma_f32_16x16x32_bf16 v[76:79], v[196:199], v[180:183], v[76:79]
	v_mfma_f32_16x16x32_bf16 v[72:75], v[210:213], v[180:183], v[72:75]
	v_mfma_f32_16x16x32_bf16 v[68:71], v[196:199], v[188:191], v[68:71]
	v_mfma_f32_16x16x32_bf16 v[64:67], v[210:213], v[188:191], v[64:67]
	v_mfma_f32_16x16x32_bf16 v[108:111], v[200:203], v[148:151], v[108:111]
	v_mfma_f32_16x16x32_bf16 v[104:107], v[214:217], v[148:151], v[104:107]
	v_mfma_f32_16x16x32_bf16 v[92:95], v[200:203], v[156:159], v[92:95]
	v_mfma_f32_16x16x32_bf16 v[88:91], v[214:217], v[156:159], v[88:91]
	v_mfma_f32_16x16x32_bf16 v[76:79], v[200:203], v[184:187], v[76:79]
	v_mfma_f32_16x16x32_bf16 v[72:75], v[214:217], v[184:187], v[72:75]
	v_mfma_f32_16x16x32_bf16 v[68:71], v[200:203], v[192:195], v[68:71]
	v_mfma_f32_16x16x32_bf16 v[64:67], v[214:217], v[192:195], v[64:67]
	s_barrier
	s_add_i32 m0, s54, 0x18000
	ds_read_b128 v[144:147], v209 offset:49152
	global_load_lds_dwordx4 v160, s[98:99]
	s_add_i32 m0, s54, 0x1a000
	ds_read_b128 v[148:151], v209 offset:50176
	global_load_lds_dwordx4 v162, s[98:99]
	s_mov_b32 m0, s60
	ds_read_b128 v[152:155], v209 offset:51200
	ds_read_b128 v[156:159], v209 offset:52224
	ds_read_b128 v[180:183], v209 offset:53248
	ds_read_b128 v[184:187], v209 offset:54272
	ds_read_b128 v[188:191], v209 offset:55296
	global_load_lds_dwordx4 v160, s[100:101]
	s_mov_b32 m0, s61
	ds_read_b128 v[192:195], v209 offset:56320
	global_load_lds_dwordx4 v162, s[100:101]
	s_add_i32 m0, s54, 0x1c000
	s_add_u32 s2, s2, 0x40080
	s_addc_u32 s3, s3, 0
	global_load_lds_dwordx4 v160, s[2:3]
	s_add_i32 m0, s54, 0x1e000
	s_add_i32 s41, s41, 2
	global_load_lds_dwordx4 v162, s[2:3]
	s_waitcnt lgkmcnt(0)
	s_waitcnt vmcnt(6)
	s_barrier
	v_mfma_f32_16x16x32_bf16 v[60:63], v[128:131], v[144:147], v[60:63]
	v_mfma_f32_16x16x32_bf16 v[56:59], v[136:139], v[144:147], v[56:59]
	v_mfma_f32_16x16x32_bf16 v[52:55], v[128:131], v[152:155], v[52:55]
	v_mfma_f32_16x16x32_bf16 v[48:51], v[136:139], v[152:155], v[48:51]
	v_mfma_f32_16x16x32_bf16 v[36:39], v[128:131], v[180:183], v[36:39]
	v_mfma_f32_16x16x32_bf16 v[32:35], v[136:139], v[180:183], v[32:35]
	v_mfma_f32_16x16x32_bf16 v[20:23], v[128:131], v[188:191], v[20:23]
	v_mfma_f32_16x16x32_bf16 v[16:19], v[136:139], v[188:191], v[16:19]
	v_mfma_f32_16x16x32_bf16 v[60:63], v[132:135], v[148:151], v[60:63]
	v_mfma_f32_16x16x32_bf16 v[56:59], v[140:143], v[148:151], v[56:59]
	v_mfma_f32_16x16x32_bf16 v[52:55], v[132:135], v[156:159], v[52:55]
	v_mfma_f32_16x16x32_bf16 v[48:51], v[140:143], v[156:159], v[48:51]
	v_mfma_f32_16x16x32_bf16 v[36:39], v[132:135], v[184:187], v[36:39]
	v_mfma_f32_16x16x32_bf16 v[32:35], v[140:143], v[184:187], v[32:35]
	v_mfma_f32_16x16x32_bf16 v[20:23], v[132:135], v[192:195], v[20:23]
	v_mfma_f32_16x16x32_bf16 v[16:19], v[140:143], v[192:195], v[16:19]
	v_mfma_f32_16x16x32_bf16 v[44:47], v[196:199], v[144:147], v[44:47]
	v_mfma_f32_16x16x32_bf16 v[40:43], v[210:213], v[144:147], v[40:43]
	v_mfma_f32_16x16x32_bf16 v[28:31], v[196:199], v[152:155], v[28:31]
	v_mfma_f32_16x16x32_bf16 v[24:27], v[210:213], v[152:155], v[24:27]
	v_mfma_f32_16x16x32_bf16 v[12:15], v[196:199], v[180:183], v[12:15]
	v_mfma_f32_16x16x32_bf16 v[8:11], v[210:213], v[180:183], v[8:11]
	v_mfma_f32_16x16x32_bf16 v[4:7], v[196:199], v[188:191], v[4:7]
	v_mfma_f32_16x16x32_bf16 v[0:3], v[210:213], v[188:191], v[0:3]
	v_mfma_f32_16x16x32_bf16 v[44:47], v[200:203], v[148:151], v[44:47]
	v_mfma_f32_16x16x32_bf16 v[40:43], v[214:217], v[148:151], v[40:43]
	v_mfma_f32_16x16x32_bf16 v[28:31], v[200:203], v[156:159], v[28:31]
	v_mfma_f32_16x16x32_bf16 v[24:27], v[214:217], v[156:159], v[24:27]
	v_mfma_f32_16x16x32_bf16 v[12:15], v[200:203], v[184:187], v[12:15]
	v_mfma_f32_16x16x32_bf16 v[8:11], v[214:217], v[184:187], v[8:11]
	v_mfma_f32_16x16x32_bf16 v[4:7], v[200:203], v[192:195], v[4:7]
	v_mfma_f32_16x16x32_bf16 v[0:3], v[214:217], v[192:195], v[0:3]
	s_add_u32 s6, s6, 0x100
	s_addc_u32 s7, s7, 0
	s_add_u32 s39, s39, 0x100
	s_addc_u32 s40, s40, 0
	s_cmp_gt_u32 s41, 13
	s_barrier
	s_cbranch_scc0 .LBB0_355
	s_lshl_b32 s1, s0, 8
	v_mov_b32_e32 v211, v206
	v_mov_b32_e32 v210, v207
	s_add_i32 s1, s1, s59
	s_cmp_lt_i32 s20, 3
	v_add_u32_e32 v180, s1, v211
	s_mov_b64 s[2:3], -1
	s_cbranch_scc0 .LBB0_490
	s_cmp_gt_i32 s0, 15
	s_cselect_b64 s[2:3], -1, 0
	s_cmp_lt_i32 s0, 16
	s_cselect_b64 s[38:39], -1, 0
	s_cmp_eq_u32 s20, 2
	s_cselect_b64 s[8:9], -1, 0
	s_cmp_lg_u32 s20, 2
	s_cselect_b64 s[0:1], -1, 0
	s_and_b64 s[40:41], s[8:9], s[22:23]
	v_lshlrev_b32_e32 v182, 2, v210
	s_mov_b64 s[6:7], -1
	s_and_b64 vcc, exec, s[40:41]
	v_ashrrev_i32_e32 v183, 31, v182
	s_cbranch_vccnz .LBB0_447
	s_and_b64 s[6:7], s[8:9], exec
	s_cselect_b32 s6, s46, s44
	s_cselect_b32 s7, s47, s45
	v_mov_b32_e32 v128, s7
	v_mov_b32_e32 v129, s6
	v_lshl_add_u64 v[128:129], v[182:183], 2, v[128:129]
	global_load_dwordx4 v[140:143], v[128:129], off
	global_load_dwordx4 v[136:139], v[128:129], off offset:64
	global_load_dwordx4 v[132:135], v[128:129], off offset:128
	s_nop 0
	global_load_dwordx4 v[128:131], v[128:129], off offset:192
	v_mul_f32_e32 v144, v125, v125
	v_mul_f32_e32 v145, v127, v127
	v_fmac_f32_e32 v144, v124, v124
	v_fmac_f32_e32 v145, v126, v126
	v_add_f32_e32 v144, v144, v145
	v_mul_f32_e32 v145, v121, v121
	v_mul_f32_e32 v146, v123, v123
	v_fmac_f32_e32 v145, v120, v120
	v_fmac_f32_e32 v146, v122, v122
	v_add_f32_e32 v145, v145, v146
	v_add_f32_e32 v144, v144, v145
	v_mul_f32_e32 v145, v109, v109
	v_mul_f32_e32 v146, v111, v111
	v_fmac_f32_e32 v145, v108, v108
	v_fmac_f32_e32 v146, v110, v110
	v_add_f32_e32 v145, v145, v146
	v_add_f32_e32 v144, v144, v145
	v_mul_f32_e32 v145, v105, v105
	v_mul_f32_e32 v146, v107, v107
	v_fmac_f32_e32 v145, v104, v104
	v_fmac_f32_e32 v146, v106, v106
	v_add_f32_e32 v145, v145, v146
	v_add_f32_e32 v144, v144, v145
	v_mov_b32_e32 v145, v144
	s_nop 1
	v_permlane16_swap_b32_e32 v144, v145
	v_add_f32_e32 v144, v144, v145
	v_mov_b32_e32 v145, v144
	s_nop 1
	v_permlane32_swap_b32_e32 v144, v145
	v_add_f32_e32 v144, v144, v145
	v_fmamk_f32 v144, v144, 0x3c800000, v225
	v_cmp_gt_f32_e32 vcc, s93, v144
	v_mul_f32_e32 v145, 0x4b800000, v144
	v_and_b32_e32 v202, 63, v211
	v_cndmask_b32_e32 v144, v144, v145, vcc
	v_rsq_f32_e32 v144, v144
	v_cndmask_b32_e64 v168, 0, 1, s[2:3]
	v_cmp_ne_u32_e64 s[6:7], 1, v168
	v_lshlrev_b32_e32 v186, 7, v202
	v_mul_f32_e32 v145, 0x45800000, v144
	v_cndmask_b32_e32 v152, v144, v145, vcc
	v_pk_mul_f32 v[144:145], v[124:125], v[152:153] op_sel_hi:[1,0]
	v_pk_mul_f32 v[146:147], v[126:127], v[152:153] op_sel_hi:[1,0]
	v_pk_mul_f32 v[148:149], v[108:109], v[152:153] op_sel_hi:[1,0]
	v_pk_mul_f32 v[150:151], v[110:111], v[152:153] op_sel_hi:[1,0]
	v_pk_mul_f32 v[184:185], v[104:105], v[152:153] op_sel_hi:[1,0]
	s_andn2_b64 vcc, exec, s[2:3]
	s_waitcnt vmcnt(0)
	v_pk_mul_f32 v[158:159], v[142:143], v[146:147]
	v_pk_mul_f32 v[156:157], v[140:141], v[144:145]
	v_pk_mul_f32 v[144:145], v[120:121], v[152:153] op_sel_hi:[1,0]
	v_pk_mul_f32 v[146:147], v[122:123], v[152:153] op_sel_hi:[1,0]
	v_pk_mul_f32 v[152:153], v[106:107], v[152:153] op_sel_hi:[1,0]
	v_pk_mul_f32 v[146:147], v[138:139], v[146:147]
	v_pk_mul_f32 v[144:145], v[136:137], v[144:145]
	v_pk_mul_f32 v[150:151], v[134:135], v[150:151]
	v_pk_mul_f32 v[148:149], v[132:133], v[148:149]
	v_pk_mul_f32 v[154:155], v[130:131], v[152:153]
	v_pk_mul_f32 v[152:153], v[128:129], v[184:185]
	v_lshl_add_u64 v[184:185], v[182:183], 3, s[18:19]
	s_cbranch_vccnz .LBB0_360
	v_lshlrev_b32_e32 v168, 1, v180
	v_and_b32_e32 v168, 0xf80, v168
	v_lshl_add_u64 v[188:189], v[184:185], 0, v[168:169]
	global_load_dwordx4 v[190:193], v[188:189], off offset:16
	global_load_dwordx4 v[194:197], v[188:189], off
	v_mov_b32_e32 v187, v169
	s_waitcnt vmcnt(0)
	v_mul_f32_e32 v198, v158, v190
	v_mov_b32_e32 v188, v194
	v_mov_b32_e32 v189, v196
	v_mov_b32_e32 v196, v195
	v_mul_f32_e32 v200, v146, v191
	v_mul_f32_e32 v204, v146, v190
	v_mul_f32_e32 v212, v158, v191
	v_mov_b32_e32 v146, v159
	v_mov_b32_e32 v158, v147
	v_pk_mul_f32 v[194:195], v[144:145], v[196:197]
	v_pk_mul_f32 v[144:145], v[144:145], v[188:189]
	v_pk_mul_f32 v[190:191], v[146:147], v[192:193]
	v_pk_mul_f32 v[146:147], v[158:159], v[192:193]
	v_lshl_add_u64 v[192:193], v[184:185], 0, v[186:187]
	v_mov_b32_e32 v199, v190
	v_mov_b32_e32 v201, v191
	v_pk_fma_f32 v[190:191], v[156:157], v[188:189], v[194:195] neg_lo:[0,0,1] neg_hi:[0,0,1]
	v_pk_fma_f32 v[144:145], v[156:157], v[196:197], v[144:145]
	global_load_dwordx4 v[156:159], v[192:193], off offset:16
	s_nop 0
	global_load_dwordx4 v[192:195], v[192:193], off
	v_pk_add_f32 v[188:189], v[198:199], v[200:201] neg_lo:[0,1] neg_hi:[0,1]
	v_mov_b32_e32 v213, v147
	v_mov_b32_e32 v205, v146
	v_pk_add_f32 v[146:147], v[212:213], v[204:205]
	s_waitcnt vmcnt(0)
	v_mul_f32_e32 v198, v150, v156
	v_mul_f32_e32 v200, v154, v157
	v_mul_f32_e32 v156, v154, v156
	v_mov_b32_e32 v154, v151
	v_mov_b32_e32 v197, v194
	v_mov_b32_e32 v194, v193
	v_mul_f32_e32 v204, v150, v157
	v_pk_mul_f32 v[212:213], v[154:155], v[158:159]
	v_mov_b32_e32 v150, v155
	v_mov_b32_e32 v196, v192
	v_pk_mul_f32 v[192:193], v[152:153], v[194:195]
	v_mov_b32_e32 v199, v212
	v_mov_b32_e32 v201, v213
	v_pk_mul_f32 v[150:151], v[150:151], v[158:159]
	v_pk_mul_f32 v[152:153], v[152:153], v[196:197]
	v_pk_fma_f32 v[192:193], v[148:149], v[196:197], v[192:193] neg_lo:[0,0,1] neg_hi:[0,0,1]
	v_pk_add_f32 v[196:197], v[198:199], v[200:201] neg_lo:[0,1] neg_hi:[0,1]
	v_mov_b32_e32 v205, v151
	v_mov_b32_e32 v157, v150
	v_pk_fma_f32 v[152:153], v[148:149], v[194:195], v[152:153]
	v_pk_add_f32 v[154:155], v[204:205], v[156:157]
	v_mov_b32_e32 v148, v192
	v_mov_b32_e32 v149, v193
	v_mov_b32_e32 v150, v196
	v_mov_b32_e32 v151, v197
	v_mov_b32_e32 v156, v190
	v_mov_b32_e32 v157, v191
	v_mov_b32_e32 v158, v188
	v_mov_b32_e32 v159, v189

.LBB0_677:
	s_ashr_i32 s23, s22, 31
	v_cmp_lt_i64_e32 vcc, s[24:25], v[174:175]
	s_lshl_b64 s[24:25], s[22:23], 19
	s_add_u32 s24, s36, s24
	s_addc_u32 s25, s37, s25
	s_and_b64 s[26:27], vcc, exec
	s_cselect_b32 s1, s25, s9
	s_cselect_b32 s7, s24, s8
	s_ashr_i32 s21, s20, 31
	s_lshl_b64 s[26:27], s[20:21], 19
	s_add_u32 s26, s38, s26
	s_addc_u32 s27, s39, s27
	s_and_b64 s[28:29], vcc, exec
	s_cselect_b32 s21, s27, s3
	s_cselect_b32 s23, s26, s2
	s_add_u32 s8, s8, 0x40080
	s_addc_u32 s9, s9, 0
	s_add_u32 s56, s2, 0x100
	s_addc_u32 s57, s3, 0
	s_mov_b32 s58, -2
	s_add_u32 s2, s8, 0xfffc0080
	s_addc_u32 s3, s9, -1
	ds_read_b128 v[48:51], v206
	ds_read_b128 v[52:55], v206 offset:1024
	ds_read_b128 v[60:63], v206 offset:2048
	ds_read_b128 v[68:71], v206 offset:3072
	s_cmp_eq_u32 s58, 12
	s_cselect_b32 s29, s1, s3
	s_cselect_b32 s28, s7, s2
	s_cselect_b32 s3, s21, s57
	s_cselect_b32 s2, s23, s56
	s_add_i32 m0, s41, 0xc000
	ds_read_b128 v[72:75], v207
	ds_read_b128 v[76:79], v207 offset:1024
	ds_read_b128 v[80:83], v207 offset:2048
	ds_read_b128 v[84:87], v207 offset:3072
	ds_read_b128 v[160:163], v207 offset:4096
	ds_read_b128 v[164:167], v207 offset:5120
	ds_read_b128 v[192:195], v207 offset:6144
	global_load_lds_dwordx4 v188, s[8:9]
	s_add_i32 m0, s41, 0xe000
	ds_read_b128 v[196:199], v207 offset:7168
	global_load_lds_dwordx4 v190, s[8:9]
	s_waitcnt lgkmcnt(11)
	ds_read_b128 v[200:203], v206 offset:16384
	ds_read_b128 v[208:211], v206 offset:17408
	ds_read_b128 v[212:215], v206 offset:18432
	ds_read_b128 v[216:219], v206 offset:19456
	s_waitcnt lgkmcnt(0)
	s_barrier
	v_mfma_f32_16x16x32_bf16 v[156:159], v[48:51], v[72:75], 0
	v_mfma_f32_16x16x32_bf16 v[152:155], v[60:63], v[72:75], 0
	v_mfma_f32_16x16x32_bf16 v[140:143], v[48:51], v[80:83], 0
	v_mfma_f32_16x16x32_bf16 v[136:139], v[60:63], v[80:83], 0
	v_mfma_f32_16x16x32_bf16 v[124:127], v[48:51], v[160:163], 0
	v_mfma_f32_16x16x32_bf16 v[120:123], v[60:63], v[160:163], 0
	v_mfma_f32_16x16x32_bf16 v[108:111], v[48:51], v[192:195], 0
	v_mfma_f32_16x16x32_bf16 v[104:107], v[60:63], v[192:195], 0
	v_mfma_f32_16x16x32_bf16 v[156:159], v[52:55], v[76:79], v[156:159]
	v_mfma_f32_16x16x32_bf16 v[152:155], v[68:71], v[76:79], v[152:155]
	v_mfma_f32_16x16x32_bf16 v[140:143], v[52:55], v[84:87], v[140:143]
	v_mfma_f32_16x16x32_bf16 v[136:139], v[68:71], v[84:87], v[136:139]
	v_mfma_f32_16x16x32_bf16 v[124:127], v[52:55], v[164:167], v[124:127]
	v_mfma_f32_16x16x32_bf16 v[120:123], v[68:71], v[164:167], v[120:123]
	v_mfma_f32_16x16x32_bf16 v[108:111], v[52:55], v[196:199], v[108:111]
	v_mfma_f32_16x16x32_bf16 v[104:107], v[68:71], v[196:199], v[104:107]
	v_mfma_f32_16x16x32_bf16 v[148:151], v[200:203], v[72:75], 0
	v_mfma_f32_16x16x32_bf16 v[72:75], v[212:215], v[72:75], 0
	v_mfma_f32_16x16x32_bf16 v[148:151], v[208:211], v[76:79], v[148:151]
	v_mfma_f32_16x16x32_bf16 v[72:75], v[216:219], v[76:79], v[72:75]
	v_mfma_f32_16x16x32_bf16 v[76:79], v[200:203], v[80:83], 0
	v_mfma_f32_16x16x32_bf16 v[80:83], v[212:215], v[80:83], 0
	v_mfma_f32_16x16x32_bf16 v[112:115], v[212:215], v[160:163], 0
	v_mfma_f32_16x16x32_bf16 v[100:103], v[200:203], v[192:195], 0
	v_mfma_f32_16x16x32_bf16 v[96:99], v[212:215], v[192:195], 0
	v_mfma_f32_16x16x32_bf16 v[76:79], v[208:211], v[84:87], v[76:79]
	v_mfma_f32_16x16x32_bf16 v[80:83], v[216:219], v[84:87], v[80:83]
	v_mfma_f32_16x16x32_bf16 v[84:87], v[200:203], v[160:163], 0
	v_mfma_f32_16x16x32_bf16 v[112:115], v[216:219], v[164:167], v[112:115]
	v_mfma_f32_16x16x32_bf16 v[100:103], v[208:211], v[196:199], v[100:103]
	v_mfma_f32_16x16x32_bf16 v[96:99], v[216:219], v[196:199], v[96:99]
	v_mfma_f32_16x16x32_bf16 v[84:87], v[208:211], v[164:167], v[84:87]
	s_barrier
	s_add_u32 s98, s2, 0x80
	s_addc_u32 s99, s3, 0
	s_add_i32 m0, s40, 0x10000
	ds_read_b128 v[116:119], v207 offset:16384
	global_load_lds_dwordx4 v182, s[2:3]
	s_add_i32 m0, s40, 0x12000
	ds_read_b128 v[128:131], v207 offset:17408
	global_load_lds_dwordx4 v186, s[2:3]
	s_mov_b32 m0, s41
	s_add_u32 s100, s28, 0x80
	s_addc_u32 s101, s29, 0
	ds_read_b128 v[132:135], v207 offset:18432
	ds_read_b128 v[144:147], v207 offset:19456
	ds_read_b128 v[160:163], v207 offset:20480
	ds_read_b128 v[164:167], v207 offset:21504
	ds_read_b128 v[192:195], v207 offset:22528
	global_load_lds_dwordx4 v180, s[28:29]
	s_mov_b32 m0, s42
	ds_read_b128 v[196:199], v207 offset:23552
	global_load_lds_dwordx4 v184, s[28:29]
	s_add_i32 m0, s40, 0x14000
	s_add_u32 s60, s2, 0x40000
	s_addc_u32 s61, s3, 0
	global_load_lds_dwordx4 v182, s[60:61]
	s_add_i32 m0, s40, 0x16000
	s_add_u32 s28, s28, 0x40000
	s_addc_u32 s29, s29, 0
	global_load_lds_dwordx4 v186, s[60:61]
	s_waitcnt lgkmcnt(0)
	s_waitcnt vmcnt(6)
	s_barrier
	v_mfma_f32_16x16x32_bf16 v[92:95], v[48:51], v[116:119], 0
	v_mfma_f32_16x16x32_bf16 v[88:91], v[60:63], v[116:119], 0
	v_mfma_f32_16x16x32_bf16 v[44:47], v[48:51], v[132:135], 0
	v_mfma_f32_16x16x32_bf16 v[40:43], v[60:63], v[132:135], 0
	v_mfma_f32_16x16x32_bf16 v[28:31], v[48:51], v[160:163], 0
	v_mfma_f32_16x16x32_bf16 v[24:27], v[60:63], v[160:163], 0
	v_mfma_f32_16x16x32_bf16 v[12:15], v[48:51], v[192:195], 0
	v_mfma_f32_16x16x32_bf16 v[8:11], v[60:63], v[192:195], 0
	v_mfma_f32_16x16x32_bf16 v[92:95], v[52:55], v[128:131], v[92:95]
	v_mfma_f32_16x16x32_bf16 v[88:91], v[68:71], v[128:131], v[88:91]
	v_mfma_f32_16x16x32_bf16 v[44:47], v[52:55], v[144:147], v[44:47]
	v_mfma_f32_16x16x32_bf16 v[40:43], v[68:71], v[144:147], v[40:43]
	v_mfma_f32_16x16x32_bf16 v[28:31], v[52:55], v[164:167], v[28:31]
	v_mfma_f32_16x16x32_bf16 v[24:27], v[68:71], v[164:167], v[24:27]
	v_mfma_f32_16x16x32_bf16 v[12:15], v[52:55], v[196:199], v[12:15]
	v_mfma_f32_16x16x32_bf16 v[8:11], v[68:71], v[196:199], v[8:11]
	v_mfma_f32_16x16x32_bf16 v[36:39], v[200:203], v[132:135], 0
	v_mfma_f32_16x16x32_bf16 v[32:35], v[212:215], v[132:135], 0
	v_mfma_f32_16x16x32_bf16 v[20:23], v[200:203], v[160:163], 0
	v_mfma_f32_16x16x32_bf16 v[16:19], v[212:215], v[160:163], 0
	v_mfma_f32_16x16x32_bf16 v[4:7], v[200:203], v[192:195], 0
	v_mfma_f32_16x16x32_bf16 v[0:3], v[212:215], v[192:195], 0
	v_mfma_f32_16x16x32_bf16 v[48:51], v[200:203], v[116:119], 0
	v_mfma_f32_16x16x32_bf16 v[52:55], v[212:215], v[116:119], 0
	v_mfma_f32_16x16x32_bf16 v[36:39], v[208:211], v[144:147], v[36:39]
	v_mfma_f32_16x16x32_bf16 v[32:35], v[216:219], v[144:147], v[32:35]
	v_mfma_f32_16x16x32_bf16 v[20:23], v[208:211], v[164:167], v[20:23]
	v_mfma_f32_16x16x32_bf16 v[16:19], v[216:219], v[164:167], v[16:19]
	v_mfma_f32_16x16x32_bf16 v[4:7], v[208:211], v[196:199], v[4:7]
	v_mfma_f32_16x16x32_bf16 v[0:3], v[216:219], v[196:199], v[0:3]
	v_mfma_f32_16x16x32_bf16 v[48:51], v[208:211], v[128:131], v[48:51]
	v_mfma_f32_16x16x32_bf16 v[52:55], v[216:219], v[128:131], v[52:55]
	s_barrier
	ds_read_b128 v[56:59], v206 offset:32768
	ds_read_b128 v[60:63], v206 offset:33792
	ds_read_b128 v[64:67], v206 offset:34816
	ds_read_b128 v[68:71], v206 offset:35840
	s_mov_b32 m0, s43
	ds_read_b128 v[116:119], v207 offset:32768
	ds_read_b128 v[128:131], v207 offset:33792
	ds_read_b128 v[160:163], v207 offset:34816
	ds_read_b128 v[164:167], v207 offset:35840
	ds_read_b128 v[192:195], v207 offset:36864
	ds_read_b128 v[196:199], v207 offset:37888
	ds_read_b128 v[200:203], v207 offset:38912
	global_load_lds_dwordx4 v180, s[28:29]
	s_mov_b32 m0, s44
	ds_read_b128 v[208:211], v207 offset:39936
	global_load_lds_dwordx4 v184, s[28:29]
	s_waitcnt lgkmcnt(11)
	ds_read_b128 v[212:215], v206 offset:49152
	ds_read_b128 v[216:219], v206 offset:50176
	ds_read_b128 v[220:223], v206 offset:51200
	ds_read_b128 v[236:239], v206 offset:52224
	s_waitcnt lgkmcnt(0)
	s_barrier
	v_mfma_f32_16x16x32_bf16 v[132:135], v[56:59], v[116:119], v[156:159]
	v_mfma_f32_16x16x32_bf16 v[156:159], v[60:63], v[128:131], v[132:135]
	v_mfma_f32_16x16x32_bf16 v[132:135], v[64:67], v[116:119], v[152:155]
	v_mfma_f32_16x16x32_bf16 v[152:155], v[68:71], v[128:131], v[132:135]
	v_mfma_f32_16x16x32_bf16 v[132:135], v[56:59], v[160:163], v[140:143]
	v_mfma_f32_16x16x32_bf16 v[140:143], v[60:63], v[164:167], v[132:135]
	v_mfma_f32_16x16x32_bf16 v[132:135], v[64:67], v[160:163], v[136:139]
	v_mfma_f32_16x16x32_bf16 v[124:127], v[56:59], v[192:195], v[124:127]
	v_mfma_f32_16x16x32_bf16 v[120:123], v[64:67], v[192:195], v[120:123]
	v_mfma_f32_16x16x32_bf16 v[108:111], v[56:59], v[200:203], v[108:111]
	v_mfma_f32_16x16x32_bf16 v[104:107], v[64:67], v[200:203], v[104:107]
	v_mfma_f32_16x16x32_bf16 v[136:139], v[68:71], v[164:167], v[132:135]
	v_mfma_f32_16x16x32_bf16 v[124:127], v[60:63], v[196:199], v[124:127]
	v_mfma_f32_16x16x32_bf16 v[120:123], v[68:71], v[196:199], v[120:123]
	v_mfma_f32_16x16x32_bf16 v[108:111], v[60:63], v[208:211], v[108:111]
	v_mfma_f32_16x16x32_bf16 v[104:107], v[68:71], v[208:211], v[104:107]
	v_mfma_f32_16x16x32_bf16 v[72:75], v[220:223], v[116:119], v[72:75]
	v_mfma_f32_16x16x32_bf16 v[132:135], v[212:215], v[116:119], v[148:151]
	v_mfma_f32_16x16x32_bf16 v[144:147], v[236:239], v[128:131], v[72:75]
	v_mfma_f32_16x16x32_bf16 v[72:75], v[212:215], v[160:163], v[76:79]
	v_mfma_f32_16x16x32_bf16 v[148:151], v[216:219], v[128:131], v[132:135]
	v_mfma_f32_16x16x32_bf16 v[132:135], v[216:219], v[164:167], v[72:75]
	v_mfma_f32_16x16x32_bf16 v[72:75], v[220:223], v[160:163], v[80:83]
	v_mfma_f32_16x16x32_bf16 v[128:131], v[236:239], v[164:167], v[72:75]
	v_mfma_f32_16x16x32_bf16 v[72:75], v[212:215], v[192:195], v[84:87]
	v_mfma_f32_16x16x32_bf16 v[116:119], v[216:219], v[196:199], v[72:75]
	v_mfma_f32_16x16x32_bf16 v[72:75], v[220:223], v[192:195], v[112:115]
	v_mfma_f32_16x16x32_bf16 v[112:115], v[236:239], v[196:199], v[72:75]
	v_mfma_f32_16x16x32_bf16 v[72:75], v[212:215], v[200:203], v[100:103]
	v_mfma_f32_16x16x32_bf16 v[100:103], v[216:219], v[208:211], v[72:75]
	v_mfma_f32_16x16x32_bf16 v[72:75], v[220:223], v[200:203], v[96:99]
	v_mfma_f32_16x16x32_bf16 v[96:99], v[236:239], v[208:211], v[72:75]
	s_barrier
	s_add_i32 m0, s40, 0x18000
	ds_read_b128 v[72:75], v207 offset:49152
	global_load_lds_dwordx4 v182, s[98:99]
	s_add_i32 m0, s40, 0x1a000
	ds_read_b128 v[76:79], v207 offset:50176
	global_load_lds_dwordx4 v186, s[98:99]
	s_mov_b32 m0, s53
	s_nop 2
	ds_read_b128 v[80:83], v207 offset:51200
	ds_read_b128 v[84:87], v207 offset:52224
	ds_read_b128 v[160:163], v207 offset:53248
	ds_read_b128 v[164:167], v207 offset:54272
	ds_read_b128 v[192:195], v207 offset:55296
	global_load_lds_dwordx4 v180, s[100:101]
	s_mov_b32 m0, s54
	ds_read_b128 v[196:199], v207 offset:56320
	global_load_lds_dwordx4 v184, s[100:101]
	s_add_i32 m0, s40, 0x1c000
	s_add_u32 s2, s2, 0x40080
	s_addc_u32 s3, s3, 0
	global_load_lds_dwordx4 v182, s[2:3]
	s_add_i32 m0, s40, 0x1e000
	s_add_i32 s58, s58, 2
	global_load_lds_dwordx4 v186, s[2:3]
	s_waitcnt lgkmcnt(0)
	s_waitcnt vmcnt(6)
	s_barrier
	v_mfma_f32_16x16x32_bf16 v[92:95], v[56:59], v[72:75], v[92:95]
	v_mfma_f32_16x16x32_bf16 v[88:91], v[64:67], v[72:75], v[88:91]
	v_mfma_f32_16x16x32_bf16 v[44:47], v[56:59], v[80:83], v[44:47]
	v_mfma_f32_16x16x32_bf16 v[40:43], v[64:67], v[80:83], v[40:43]
	v_mfma_f32_16x16x32_bf16 v[28:31], v[56:59], v[160:163], v[28:31]
	v_mfma_f32_16x16x32_bf16 v[24:27], v[64:67], v[160:163], v[24:27]
	v_mfma_f32_16x16x32_bf16 v[12:15], v[56:59], v[192:195], v[12:15]
	v_mfma_f32_16x16x32_bf16 v[8:11], v[64:67], v[192:195], v[8:11]
	v_mfma_f32_16x16x32_bf16 v[92:95], v[60:63], v[76:79], v[92:95]
	v_mfma_f32_16x16x32_bf16 v[88:91], v[68:71], v[76:79], v[88:91]
	v_mfma_f32_16x16x32_bf16 v[44:47], v[60:63], v[84:87], v[44:47]
	v_mfma_f32_16x16x32_bf16 v[40:43], v[68:71], v[84:87], v[40:43]
	v_mfma_f32_16x16x32_bf16 v[28:31], v[60:63], v[164:167], v[28:31]
	v_mfma_f32_16x16x32_bf16 v[24:27], v[68:71], v[164:167], v[24:27]
	v_mfma_f32_16x16x32_bf16 v[12:15], v[60:63], v[196:199], v[12:15]
	v_mfma_f32_16x16x32_bf16 v[8:11], v[68:71], v[196:199], v[8:11]
	v_mfma_f32_16x16x32_bf16 v[48:51], v[212:215], v[72:75], v[48:51]
	v_mfma_f32_16x16x32_bf16 v[64:67], v[216:219], v[76:79], v[48:51]
	v_mfma_f32_16x16x32_bf16 v[48:51], v[220:223], v[72:75], v[52:55]
	v_mfma_f32_16x16x32_bf16 v[36:39], v[212:215], v[80:83], v[36:39]
	v_mfma_f32_16x16x32_bf16 v[32:35], v[220:223], v[80:83], v[32:35]
	v_mfma_f32_16x16x32_bf16 v[20:23], v[212:215], v[160:163], v[20:23]
	v_mfma_f32_16x16x32_bf16 v[16:19], v[220:223], v[160:163], v[16:19]
	v_mfma_f32_16x16x32_bf16 v[4:7], v[212:215], v[192:195], v[4:7]
	v_mfma_f32_16x16x32_bf16 v[0:3], v[220:223], v[192:195], v[0:3]
	v_mfma_f32_16x16x32_bf16 v[56:59], v[236:239], v[76:79], v[48:51]
	v_mfma_f32_16x16x32_bf16 v[36:39], v[216:219], v[84:87], v[36:39]
	v_mfma_f32_16x16x32_bf16 v[32:35], v[236:239], v[84:87], v[32:35]
	v_mfma_f32_16x16x32_bf16 v[20:23], v[216:219], v[164:167], v[20:23]
	v_mfma_f32_16x16x32_bf16 v[16:19], v[236:239], v[164:167], v[16:19]
	v_mfma_f32_16x16x32_bf16 v[4:7], v[216:219], v[196:199], v[4:7]
	v_mfma_f32_16x16x32_bf16 v[0:3], v[236:239], v[196:199], v[0:3]
	s_add_u32 s8, s8, 0x100
	s_addc_u32 s9, s9, 0
	s_add_u32 s56, s56, 0x100
	s_addc_u32 s57, s57, 0
	s_cmp_gt_u32 s58, 13
	s_barrier
.LBB0_678:
	s_add_u32 s2, s8, 0xfffc0080
	s_addc_u32 s3, s9, -1
	ds_read_b128 v[48:51], v206
	ds_read_b128 v[52:55], v206 offset:1024
	ds_read_b128 v[60:63], v206 offset:2048
	ds_read_b128 v[68:71], v206 offset:3072
	s_cmp_eq_u32 s58, 12
	s_cselect_b32 s29, s1, s3
	s_cselect_b32 s28, s7, s2
	s_cselect_b32 s3, s21, s57
	s_cselect_b32 s2, s23, s56
	s_add_i32 m0, s41, 0xc000
	ds_read_b128 v[72:75], v207
	ds_read_b128 v[76:79], v207 offset:1024
	ds_read_b128 v[80:83], v207 offset:2048
	ds_read_b128 v[84:87], v207 offset:3072
	ds_read_b128 v[160:163], v207 offset:4096
	ds_read_b128 v[164:167], v207 offset:5120
	ds_read_b128 v[192:195], v207 offset:6144
	global_load_lds_dwordx4 v188, s[8:9]
	s_add_i32 m0, s41, 0xe000
	ds_read_b128 v[196:199], v207 offset:7168
	global_load_lds_dwordx4 v190, s[8:9]
	s_waitcnt lgkmcnt(11)
	ds_read_b128 v[200:203], v206 offset:16384
	ds_read_b128 v[208:211], v206 offset:17408
	ds_read_b128 v[212:215], v206 offset:18432
	ds_read_b128 v[216:219], v206 offset:19456
	s_waitcnt lgkmcnt(0)
	s_barrier
	v_mfma_f32_16x16x32_bf16 v[156:159], v[48:51], v[72:75], v[156:159]
	v_mfma_f32_16x16x32_bf16 v[152:155], v[60:63], v[72:75], v[152:155]
	v_mfma_f32_16x16x32_bf16 v[140:143], v[48:51], v[80:83], v[140:143]
	v_mfma_f32_16x16x32_bf16 v[136:139], v[60:63], v[80:83], v[136:139]
	v_mfma_f32_16x16x32_bf16 v[124:127], v[48:51], v[160:163], v[124:127]
	v_mfma_f32_16x16x32_bf16 v[120:123], v[60:63], v[160:163], v[120:123]
	v_mfma_f32_16x16x32_bf16 v[108:111], v[48:51], v[192:195], v[108:111]
	v_mfma_f32_16x16x32_bf16 v[104:107], v[60:63], v[192:195], v[104:107]
	v_mfma_f32_16x16x32_bf16 v[156:159], v[52:55], v[76:79], v[156:159]
	v_mfma_f32_16x16x32_bf16 v[152:155], v[68:71], v[76:79], v[152:155]
	v_mfma_f32_16x16x32_bf16 v[140:143], v[52:55], v[84:87], v[140:143]
	v_mfma_f32_16x16x32_bf16 v[136:139], v[68:71], v[84:87], v[136:139]
	v_mfma_f32_16x16x32_bf16 v[124:127], v[52:55], v[164:167], v[124:127]
	v_mfma_f32_16x16x32_bf16 v[120:123], v[68:71], v[164:167], v[120:123]
	v_mfma_f32_16x16x32_bf16 v[108:111], v[52:55], v[196:199], v[108:111]
	v_mfma_f32_16x16x32_bf16 v[104:107], v[68:71], v[196:199], v[104:107]
	v_mfma_f32_16x16x32_bf16 v[148:151], v[200:203], v[72:75], v[148:151]
	v_mfma_f32_16x16x32_bf16 v[72:75], v[212:215], v[72:75], v[144:147]
	v_mfma_f32_16x16x32_bf16 v[148:151], v[208:211], v[76:79], v[148:151]
	v_mfma_f32_16x16x32_bf16 v[72:75], v[216:219], v[76:79], v[72:75]
	v_mfma_f32_16x16x32_bf16 v[76:79], v[200:203], v[80:83], v[132:135]
	v_mfma_f32_16x16x32_bf16 v[80:83], v[212:215], v[80:83], v[128:131]
	v_mfma_f32_16x16x32_bf16 v[112:115], v[212:215], v[160:163], v[112:115]
	v_mfma_f32_16x16x32_bf16 v[100:103], v[200:203], v[192:195], v[100:103]
	v_mfma_f32_16x16x32_bf16 v[96:99], v[212:215], v[192:195], v[96:99]
	v_mfma_f32_16x16x32_bf16 v[76:79], v[208:211], v[84:87], v[76:79]
	v_mfma_f32_16x16x32_bf16 v[80:83], v[216:219], v[84:87], v[80:83]
	v_mfma_f32_16x16x32_bf16 v[84:87], v[200:203], v[160:163], v[116:119]
	v_mfma_f32_16x16x32_bf16 v[112:115], v[216:219], v[164:167], v[112:115]
	v_mfma_f32_16x16x32_bf16 v[100:103], v[208:211], v[196:199], v[100:103]
	v_mfma_f32_16x16x32_bf16 v[96:99], v[216:219], v[196:199], v[96:99]
	v_mfma_f32_16x16x32_bf16 v[84:87], v[208:211], v[164:167], v[84:87]
	s_barrier
	s_add_u32 s98, s2, 0x80
	s_addc_u32 s99, s3, 0
	s_add_i32 m0, s40, 0x10000
	ds_read_b128 v[116:119], v207 offset:16384
	global_load_lds_dwordx4 v182, s[2:3]
	s_add_i32 m0, s40, 0x12000
	ds_read_b128 v[128:131], v207 offset:17408
	global_load_lds_dwordx4 v186, s[2:3]
	s_mov_b32 m0, s41
	s_add_u32 s100, s28, 0x80
	s_addc_u32 s101, s29, 0
	ds_read_b128 v[132:135], v207 offset:18432
	ds_read_b128 v[144:147], v207 offset:19456
	ds_read_b128 v[160:163], v207 offset:20480
	ds_read_b128 v[164:167], v207 offset:21504
	ds_read_b128 v[192:195], v207 offset:22528
	global_load_lds_dwordx4 v180, s[28:29]
	s_mov_b32 m0, s42
	ds_read_b128 v[196:199], v207 offset:23552
	global_load_lds_dwordx4 v184, s[28:29]
	s_add_i32 m0, s40, 0x14000
	s_add_u32 s60, s2, 0x40000
	s_addc_u32 s61, s3, 0
	global_load_lds_dwordx4 v182, s[60:61]
	s_add_i32 m0, s40, 0x16000
	s_add_u32 s28, s28, 0x40000
	s_addc_u32 s29, s29, 0
	global_load_lds_dwordx4 v186, s[60:61]
	s_waitcnt lgkmcnt(0)
	s_waitcnt vmcnt(6)
	s_barrier
	v_mfma_f32_16x16x32_bf16 v[92:95], v[48:51], v[116:119], v[92:95]
	v_mfma_f32_16x16x32_bf16 v[88:91], v[60:63], v[116:119], v[88:91]
	v_mfma_f32_16x16x32_bf16 v[44:47], v[48:51], v[132:135], v[44:47]
	v_mfma_f32_16x16x32_bf16 v[40:43], v[60:63], v[132:135], v[40:43]
	v_mfma_f32_16x16x32_bf16 v[28:31], v[48:51], v[160:163], v[28:31]
	v_mfma_f32_16x16x32_bf16 v[24:27], v[60:63], v[160:163], v[24:27]
	v_mfma_f32_16x16x32_bf16 v[12:15], v[48:51], v[192:195], v[12:15]
	v_mfma_f32_16x16x32_bf16 v[8:11], v[60:63], v[192:195], v[8:11]
	v_mfma_f32_16x16x32_bf16 v[92:95], v[52:55], v[128:131], v[92:95]
	v_mfma_f32_16x16x32_bf16 v[88:91], v[68:71], v[128:131], v[88:91]
	v_mfma_f32_16x16x32_bf16 v[44:47], v[52:55], v[144:147], v[44:47]
	v_mfma_f32_16x16x32_bf16 v[40:43], v[68:71], v[144:147], v[40:43]
	v_mfma_f32_16x16x32_bf16 v[28:31], v[52:55], v[164:167], v[28:31]
	v_mfma_f32_16x16x32_bf16 v[24:27], v[68:71], v[164:167], v[24:27]
	v_mfma_f32_16x16x32_bf16 v[12:15], v[52:55], v[196:199], v[12:15]
	v_mfma_f32_16x16x32_bf16 v[8:11], v[68:71], v[196:199], v[8:11]
	v_mfma_f32_16x16x32_bf16 v[36:39], v[200:203], v[132:135], v[36:39]
	v_mfma_f32_16x16x32_bf16 v[32:35], v[212:215], v[132:135], v[32:35]
	v_mfma_f32_16x16x32_bf16 v[20:23], v[200:203], v[160:163], v[20:23]
	v_mfma_f32_16x16x32_bf16 v[16:19], v[212:215], v[160:163], v[16:19]
	v_mfma_f32_16x16x32_bf16 v[4:7], v[200:203], v[192:195], v[4:7]
	v_mfma_f32_16x16x32_bf16 v[0:3], v[212:215], v[192:195], v[0:3]
	v_mfma_f32_16x16x32_bf16 v[48:51], v[200:203], v[116:119], v[64:67]
	v_mfma_f32_16x16x32_bf16 v[52:55], v[212:215], v[116:119], v[56:59]
	v_mfma_f32_16x16x32_bf16 v[36:39], v[208:211], v[144:147], v[36:39]
	v_mfma_f32_16x16x32_bf16 v[32:35], v[216:219], v[144:147], v[32:35]
	v_mfma_f32_16x16x32_bf16 v[20:23], v[208:211], v[164:167], v[20:23]
	v_mfma_f32_16x16x32_bf16 v[16:19], v[216:219], v[164:167], v[16:19]
	v_mfma_f32_16x16x32_bf16 v[4:7], v[208:211], v[196:199], v[4:7]
	v_mfma_f32_16x16x32_bf16 v[0:3], v[216:219], v[196:199], v[0:3]
	v_mfma_f32_16x16x32_bf16 v[48:51], v[208:211], v[128:131], v[48:51]
	v_mfma_f32_16x16x32_bf16 v[52:55], v[216:219], v[128:131], v[52:55]
	s_barrier
	ds_read_b128 v[56:59], v206 offset:32768
	ds_read_b128 v[60:63], v206 offset:33792
	ds_read_b128 v[64:67], v206 offset:34816
	ds_read_b128 v[68:71], v206 offset:35840
	s_mov_b32 m0, s43
	ds_read_b128 v[116:119], v207 offset:32768
	ds_read_b128 v[128:131], v207 offset:33792
	ds_read_b128 v[160:163], v207 offset:34816
	ds_read_b128 v[164:167], v207 offset:35840
	ds_read_b128 v[192:195], v207 offset:36864
	ds_read_b128 v[196:199], v207 offset:37888
	ds_read_b128 v[200:203], v207 offset:38912
	global_load_lds_dwordx4 v180, s[28:29]
	s_mov_b32 m0, s44
	ds_read_b128 v[208:211], v207 offset:39936
	global_load_lds_dwordx4 v184, s[28:29]
	s_waitcnt lgkmcnt(11)
	ds_read_b128 v[212:215], v206 offset:49152
	ds_read_b128 v[216:219], v206 offset:50176
	ds_read_b128 v[220:223], v206 offset:51200
	ds_read_b128 v[236:239], v206 offset:52224
	s_waitcnt lgkmcnt(0)
	s_barrier
	v_mfma_f32_16x16x32_bf16 v[132:135], v[56:59], v[116:119], v[156:159]
	v_mfma_f32_16x16x32_bf16 v[156:159], v[60:63], v[128:131], v[132:135]
	v_mfma_f32_16x16x32_bf16 v[132:135], v[64:67], v[116:119], v[152:155]
	v_mfma_f32_16x16x32_bf16 v[152:155], v[68:71], v[128:131], v[132:135]
	v_mfma_f32_16x16x32_bf16 v[132:135], v[56:59], v[160:163], v[140:143]
	v_mfma_f32_16x16x32_bf16 v[140:143], v[60:63], v[164:167], v[132:135]
	v_mfma_f32_16x16x32_bf16 v[132:135], v[64:67], v[160:163], v[136:139]
	v_mfma_f32_16x16x32_bf16 v[124:127], v[56:59], v[192:195], v[124:127]
	v_mfma_f32_16x16x32_bf16 v[120:123], v[64:67], v[192:195], v[120:123]
	v_mfma_f32_16x16x32_bf16 v[108:111], v[56:59], v[200:203], v[108:111]
	v_mfma_f32_16x16x32_bf16 v[104:107], v[64:67], v[200:203], v[104:107]
	v_mfma_f32_16x16x32_bf16 v[136:139], v[68:71], v[164:167], v[132:135]
	v_mfma_f32_16x16x32_bf16 v[124:127], v[60:63], v[196:199], v[124:127]
	v_mfma_f32_16x16x32_bf16 v[120:123], v[68:71], v[196:199], v[120:123]
	v_mfma_f32_16x16x32_bf16 v[108:111], v[60:63], v[208:211], v[108:111]
	v_mfma_f32_16x16x32_bf16 v[104:107], v[68:71], v[208:211], v[104:107]
	v_mfma_f32_16x16x32_bf16 v[72:75], v[220:223], v[116:119], v[72:75]
	v_mfma_f32_16x16x32_bf16 v[132:135], v[212:215], v[116:119], v[148:151]
	v_mfma_f32_16x16x32_bf16 v[144:147], v[236:239], v[128:131], v[72:75]
	v_mfma_f32_16x16x32_bf16 v[72:75], v[212:215], v[160:163], v[76:79]
	v_mfma_f32_16x16x32_bf16 v[148:151], v[216:219], v[128:131], v[132:135]
	v_mfma_f32_16x16x32_bf16 v[132:135], v[216:219], v[164:167], v[72:75]
	v_mfma_f32_16x16x32_bf16 v[72:75], v[220:223], v[160:163], v[80:83]
	v_mfma_f32_16x16x32_bf16 v[128:131], v[236:239], v[164:167], v[72:75]
	v_mfma_f32_16x16x32_bf16 v[72:75], v[212:215], v[192:195], v[84:87]
	v_mfma_f32_16x16x32_bf16 v[116:119], v[216:219], v[196:199], v[72:75]
	v_mfma_f32_16x16x32_bf16 v[72:75], v[220:223], v[192:195], v[112:115]
	v_mfma_f32_16x16x32_bf16 v[112:115], v[236:239], v[196:199], v[72:75]
	v_mfma_f32_16x16x32_bf16 v[72:75], v[212:215], v[200:203], v[100:103]
	v_mfma_f32_16x16x32_bf16 v[100:103], v[216:219], v[208:211], v[72:75]
	v_mfma_f32_16x16x32_bf16 v[72:75], v[220:223], v[200:203], v[96:99]
	v_mfma_f32_16x16x32_bf16 v[96:99], v[236:239], v[208:211], v[72:75]
	s_barrier
	s_add_i32 m0, s40, 0x18000
	ds_read_b128 v[72:75], v207 offset:49152
	global_load_lds_dwordx4 v182, s[98:99]
	s_add_i32 m0, s40, 0x1a000
	ds_read_b128 v[76:79], v207 offset:50176
	global_load_lds_dwordx4 v186, s[98:99]
	s_mov_b32 m0, s53
	s_nop 2
	ds_read_b128 v[80:83], v207 offset:51200
	ds_read_b128 v[84:87], v207 offset:52224
	ds_read_b128 v[160:163], v207 offset:53248
	ds_read_b128 v[164:167], v207 offset:54272
	ds_read_b128 v[192:195], v207 offset:55296
	global_load_lds_dwordx4 v180, s[100:101]
	s_mov_b32 m0, s54
	ds_read_b128 v[196:199], v207 offset:56320
	global_load_lds_dwordx4 v184, s[100:101]
	s_add_i32 m0, s40, 0x1c000
	s_add_u32 s2, s2, 0x40080
	s_addc_u32 s3, s3, 0
	global_load_lds_dwordx4 v182, s[2:3]
	s_add_i32 m0, s40, 0x1e000
	s_add_i32 s58, s58, 2
	global_load_lds_dwordx4 v186, s[2:3]
	s_waitcnt lgkmcnt(0)
	s_waitcnt vmcnt(6)
	s_barrier
	v_mfma_f32_16x16x32_bf16 v[92:95], v[56:59], v[72:75], v[92:95]
	v_mfma_f32_16x16x32_bf16 v[88:91], v[64:67], v[72:75], v[88:91]
	v_mfma_f32_16x16x32_bf16 v[44:47], v[56:59], v[80:83], v[44:47]
	v_mfma_f32_16x16x32_bf16 v[40:43], v[64:67], v[80:83], v[40:43]
	v_mfma_f32_16x16x32_bf16 v[28:31], v[56:59], v[160:163], v[28:31]
	v_mfma_f32_16x16x32_bf16 v[24:27], v[64:67], v[160:163], v[24:27]
	v_mfma_f32_16x16x32_bf16 v[12:15], v[56:59], v[192:195], v[12:15]
	v_mfma_f32_16x16x32_bf16 v[8:11], v[64:67], v[192:195], v[8:11]
	v_mfma_f32_16x16x32_bf16 v[92:95], v[60:63], v[76:79], v[92:95]
	v_mfma_f32_16x16x32_bf16 v[88:91], v[68:71], v[76:79], v[88:91]
	v_mfma_f32_16x16x32_bf16 v[44:47], v[60:63], v[84:87], v[44:47]
	v_mfma_f32_16x16x32_bf16 v[40:43], v[68:71], v[84:87], v[40:43]
	v_mfma_f32_16x16x32_bf16 v[28:31], v[60:63], v[164:167], v[28:31]
	v_mfma_f32_16x16x32_bf16 v[24:27], v[68:71], v[164:167], v[24:27]
	v_mfma_f32_16x16x32_bf16 v[12:15], v[60:63], v[196:199], v[12:15]
	v_mfma_f32_16x16x32_bf16 v[8:11], v[68:71], v[196:199], v[8:11]
	v_mfma_f32_16x16x32_bf16 v[48:51], v[212:215], v[72:75], v[48:51]
	v_mfma_f32_16x16x32_bf16 v[64:67], v[216:219], v[76:79], v[48:51]
	v_mfma_f32_16x16x32_bf16 v[48:51], v[220:223], v[72:75], v[52:55]
	v_mfma_f32_16x16x32_bf16 v[36:39], v[212:215], v[80:83], v[36:39]
	v_mfma_f32_16x16x32_bf16 v[32:35], v[220:223], v[80:83], v[32:35]
	v_mfma_f32_16x16x32_bf16 v[20:23], v[212:215], v[160:163], v[20:23]
	v_mfma_f32_16x16x32_bf16 v[16:19], v[220:223], v[160:163], v[16:19]
	v_mfma_f32_16x16x32_bf16 v[4:7], v[212:215], v[192:195], v[4:7]
	v_mfma_f32_16x16x32_bf16 v[0:3], v[220:223], v[192:195], v[0:3]
	v_mfma_f32_16x16x32_bf16 v[56:59], v[236:239], v[76:79], v[48:51]
	v_mfma_f32_16x16x32_bf16 v[36:39], v[216:219], v[84:87], v[36:39]
	v_mfma_f32_16x16x32_bf16 v[32:35], v[236:239], v[84:87], v[32:35]
	v_mfma_f32_16x16x32_bf16 v[20:23], v[216:219], v[164:167], v[20:23]
	v_mfma_f32_16x16x32_bf16 v[16:19], v[236:239], v[164:167], v[16:19]
	v_mfma_f32_16x16x32_bf16 v[4:7], v[216:219], v[196:199], v[4:7]
	v_mfma_f32_16x16x32_bf16 v[0:3], v[236:239], v[196:199], v[0:3]
	s_add_u32 s8, s8, 0x100
	s_addc_u32 s9, s9, 0
	s_add_u32 s56, s56, 0x100
	s_addc_u32 s57, s57, 0
	s_cmp_gt_u32 s58, 13
	s_barrier
	s_cbranch_scc0 .LBB0_678
	s_lshl_b32 s1, s0, 8
	s_add_i32 s2, s1, s51
	s_lshl_b32 s1, s6, 8
	v_mov_b32_e32 v160, v205
	v_mov_b32_e32 v208, v204
	s_or_b32 s1, s1, s52
	s_nop 0
	v_lshl_add_u32 v192, v208, 3, s1
	s_add_i32 s1, s0, -16
	s_lshr_b32 s1, s1, 3
	s_add_i32 s1, s1, 1
	s_cmp_gt_i32 s0, 15
	s_cselect_b32 s3, s1, 0
	s_mul_i32 s96, s3, 0x1800
	s_lshl_b64 s[0:1], s[96:97], 2
	s_add_u32 s0, s45, s0
	v_ashrrev_i32_e32 v193, 31, v192
	s_addc_u32 s1, s46, s1
	v_lshlrev_b64 v[196:197], 2, v[192:193]
	s_lshl_b32 s96, s3, 10
	v_lshl_add_u64 v[48:49], s[0:1], 0, v[196:197]
	s_lshl_b64 s[0:1], s[96:97], 2
	s_add_u32 s0, s49, s0
	s_addc_u32 s1, s50, s1
	v_lshl_add_u64 v[52:53], s[0:1], 0, v[196:197]
	global_load_dwordx4 v[80:83], v[48:49], off offset:16
	global_load_dwordx4 v[84:87], v[48:49], off
	global_load_dwordx4 v[72:75], v[52:53], off offset:16
	global_load_dwordx4 v[76:79], v[52:53], off
	global_load_dwordx4 v[60:63], v[48:49], off offset:528
	global_load_dwordx4 v[68:71], v[48:49], off offset:512
	s_nop 0
	global_load_dwordx4 v[48:51], v[52:53], off offset:528
	s_nop 0
	global_load_dwordx4 v[52:55], v[52:53], off offset:512
	v_add_u32_e32 v194, s2, v160
	v_ashrrev_i32_e32 v195, 31, v194
	v_lshlrev_b64 v[160:161], 10, v[194:195]
	v_lshl_add_u64 v[198:199], v[160:161], 0, v[192:193]
	v_cndmask_b32_e64 v160, 0, 1, s[74:75]
	v_cmp_gt_i32_e64 s[0:1], s71, v194
	v_cmp_ne_u32_e64 s[6:7], 1, v160
	s_andn2_b64 vcc, exec, s[74:75]
	s_mov_b64 s[2:3], -1
	s_cbranch_vccnz .LBB0_681
	v_lshl_add_u64 v[160:161], v[198:199], 1, s[14:15]
	v_mov_b32_e32 v222, v160
	v_mov_b32_e32 v223, v161
	global_load_dwordx4 v[210:213], v[222:223], off
	global_load_dwordx4 v[214:217], v[222:223], off offset:256
	s_mov_b64 s[80:81], 0x8000
	v_lshl_add_u64 v[222:223], v[222:223], 0, s[80:81]
	global_load_dwordx4 v[218:221], v[222:223], off
	global_load_dwordx4 v[236:239], v[222:223], off offset:256
	s_mov_b64 s[2:3], 0
	s_waitcnt vmcnt(3)
	v_lshlrev_b32_e32 v164, 16, v210
	v_and_b32_e32 v165, 0xffff0000, v210
	v_lshlrev_b32_e32 v166, 16, v211
	v_and_b32_e32 v167, 0xffff0000, v211
	v_lshlrev_b32_e32 v160, 16, v212
	v_and_b32_e32 v161, 0xffff0000, v212
	v_lshlrev_b32_e32 v162, 16, v213
	v_and_b32_e32 v163, 0xffff0000, v213
	s_mov_b64 s[80:81], 0x8000
	v_lshl_add_u64 v[222:223], v[222:223], 0, s[80:81]
	global_load_dwordx4 v[210:213], v[222:223], off

.LBB0_879:
	s_ashr_i32 s39, s38, 31
	v_cmp_lt_i64_e32 vcc, s[12:13], v[178:179]
	s_lshl_b64 s[12:13], s[38:39], 19
	s_add_u32 s40, s49, s12
	s_addc_u32 s41, s50, s13
	s_lshl_b32 s84, s82, 18
	s_add_u32 s40, s40, s84
	s_addc_u32 s41, s41, 0
	s_and_b64 s[12:13], vcc, exec
	s_cselect_b32 s1, s41, s11
	s_cselect_b32 s9, s40, s10
	s_ashr_i32 s37, s36, 31
	s_lshl_b64 s[12:13], s[36:37], 19
	s_add_u32 s42, s51, s12
	s_addc_u32 s43, s52, s13
	s_and_b64 s[12:13], vcc, exec
	s_cselect_b32 s14, s43, s3
	s_cselect_b32 s15, s42, s2
	s_add_u32 s10, s10, 0x40080
	s_addc_u32 s11, s11, 0
	s_add_u32 s37, s2, 0x100
	s_addc_u32 s39, s3, 0
	s_mov_b32 s67, -2
	s_cmp_lg_u32 s83, 0
	s_cbranch_scc1 .Lup_half_peel
	s_add_u32 s2, s10, 0xfffc0080
	s_addc_u32 s3, s11, -1
	ds_read_b128 v[48:51], v237
	ds_read_b128 v[52:55], v237 offset:1024
	ds_read_b128 v[104:107], v237 offset:2048
	ds_read_b128 v[108:111], v237 offset:3072
	s_cmp_eq_u32 s67, 12
	s_cselect_b32 s13, s1, s3
	s_cselect_b32 s12, s9, s2
	s_cselect_b32 s3, s14, s39
	s_cselect_b32 s2, s15, s37
	s_add_i32 m0, s54, 0xc000
	ds_read_b128 v[112:115], v238
	ds_read_b128 v[116:119], v238 offset:1024
	ds_read_b128 v[120:123], v238 offset:2048
	ds_read_b128 v[156:159], v238 offset:3072
	ds_read_b128 v[160:163], v238 offset:4096
	ds_read_b128 v[164:167], v238 offset:5120
	ds_read_b128 v[190:193], v238 offset:6144
	global_load_lds_dwordx4 v186, s[10:11]
	s_add_i32 m0, s54, 0xe000
	ds_read_b128 v[194:197], v238 offset:7168
	global_load_lds_dwordx4 v188, s[10:11]
	s_waitcnt lgkmcnt(11)
	ds_read_b128 v[198:201], v237 offset:16384
	ds_read_b128 v[202:205], v237 offset:17408
	ds_read_b128 v[206:209], v237 offset:18432
	ds_read_b128 v[210:213], v237 offset:19456
	s_waitcnt lgkmcnt(0)
	s_barrier
	v_mfma_f32_16x16x32_bf16 v[152:155], v[48:51], v[112:115], 0
	v_mfma_f32_16x16x32_bf16 v[68:71], v[104:107], v[112:115], 0
	v_mfma_f32_16x16x32_bf16 v[148:151], v[48:51], v[120:123], 0
	v_mfma_f32_16x16x32_bf16 v[64:67], v[104:107], v[120:123], 0
	v_mfma_f32_16x16x32_bf16 v[136:139], v[48:51], v[160:163], 0
	v_mfma_f32_16x16x32_bf16 v[44:47], v[104:107], v[160:163], 0
	v_mfma_f32_16x16x32_bf16 v[128:131], v[48:51], v[190:193], 0
	v_mfma_f32_16x16x32_bf16 v[40:43], v[104:107], v[190:193], 0
	v_mfma_f32_16x16x32_bf16 v[152:155], v[52:55], v[116:119], v[152:155]
	v_mfma_f32_16x16x32_bf16 v[68:71], v[108:111], v[116:119], v[68:71]
	v_mfma_f32_16x16x32_bf16 v[148:151], v[52:55], v[156:159], v[148:151]
	v_mfma_f32_16x16x32_bf16 v[64:67], v[108:111], v[156:159], v[64:67]
	v_mfma_f32_16x16x32_bf16 v[136:139], v[52:55], v[164:167], v[136:139]
	v_mfma_f32_16x16x32_bf16 v[44:47], v[108:111], v[164:167], v[44:47]
	v_mfma_f32_16x16x32_bf16 v[128:131], v[52:55], v[194:197], v[128:131]
	v_mfma_f32_16x16x32_bf16 v[40:43], v[108:111], v[194:197], v[40:43]
	v_mfma_f32_16x16x32_bf16 v[144:147], v[198:201], v[112:115], 0
	v_mfma_f32_16x16x32_bf16 v[60:63], v[206:209], v[112:115], 0
	v_mfma_f32_16x16x32_bf16 v[56:59], v[206:209], v[120:123], 0
	v_mfma_f32_16x16x32_bf16 v[36:39], v[206:209], v[160:163], 0
	v_mfma_f32_16x16x32_bf16 v[32:35], v[206:209], v[190:193], 0
	v_mfma_f32_16x16x32_bf16 v[144:147], v[202:205], v[116:119], v[144:147]
	v_mfma_f32_16x16x32_bf16 v[60:63], v[210:213], v[116:119], v[60:63]
	v_mfma_f32_16x16x32_bf16 v[112:115], v[198:201], v[120:123], 0
	v_mfma_f32_16x16x32_bf16 v[56:59], v[210:213], v[156:159], v[56:59]
	v_mfma_f32_16x16x32_bf16 v[116:119], v[198:201], v[160:163], 0
	v_mfma_f32_16x16x32_bf16 v[36:39], v[210:213], v[164:167], v[36:39]
	v_mfma_f32_16x16x32_bf16 v[120:123], v[198:201], v[190:193], 0
	v_mfma_f32_16x16x32_bf16 v[32:35], v[210:213], v[194:197], v[32:35]
	v_mfma_f32_16x16x32_bf16 v[112:115], v[202:205], v[156:159], v[112:115]
	v_mfma_f32_16x16x32_bf16 v[116:119], v[202:205], v[164:167], v[116:119]
	v_mfma_f32_16x16x32_bf16 v[120:123], v[202:205], v[194:197], v[120:123]
	s_barrier
	s_add_u32 s98, s2, 0x80
	s_addc_u32 s99, s3, 0
	s_add_i32 m0, s53, 0x10000
	ds_read_b128 v[124:127], v238 offset:16384
	global_load_lds_dwordx4 v168, s[2:3]
	s_add_i32 m0, s53, 0x12000
	ds_read_b128 v[132:135], v238 offset:17408
	global_load_lds_dwordx4 v184, s[2:3]
	s_mov_b32 m0, s54
	s_add_u32 s100, s12, 0x80
	s_addc_u32 s101, s13, 0
	ds_read_b128 v[140:143], v238 offset:18432
	ds_read_b128 v[156:159], v238 offset:19456
	ds_read_b128 v[160:163], v238 offset:20480
	ds_read_b128 v[164:167], v238 offset:21504
	ds_read_b128 v[190:193], v238 offset:22528
	global_load_lds_dwordx4 v180, s[12:13]
	s_mov_b32 m0, s55
	ds_read_b128 v[194:197], v238 offset:23552
	global_load_lds_dwordx4 v182, s[12:13]
	s_add_i32 m0, s53, 0x14000
	s_add_u32 s68, s2, 0x40000
	s_addc_u32 s69, s3, 0
	global_load_lds_dwordx4 v168, s[68:69]
	s_add_i32 m0, s53, 0x16000
	s_add_u32 s12, s12, 0x40000
	s_addc_u32 s13, s13, 0
	global_load_lds_dwordx4 v184, s[68:69]
	s_waitcnt lgkmcnt(0)
	s_waitcnt vmcnt(6)
	s_barrier
	v_mfma_f32_16x16x32_bf16 v[100:103], v[48:51], v[124:127], 0
	v_mfma_f32_16x16x32_bf16 v[28:31], v[104:107], v[124:127], 0
	v_mfma_f32_16x16x32_bf16 v[96:99], v[48:51], v[140:143], 0
	v_mfma_f32_16x16x32_bf16 v[24:27], v[104:107], v[140:143], 0
	v_mfma_f32_16x16x32_bf16 v[84:87], v[48:51], v[160:163], 0
	v_mfma_f32_16x16x32_bf16 v[12:15], v[104:107], v[160:163], 0
	v_mfma_f32_16x16x32_bf16 v[8:11], v[104:107], v[190:193], 0
	v_mfma_f32_16x16x32_bf16 v[100:103], v[52:55], v[132:135], v[100:103]
	v_mfma_f32_16x16x32_bf16 v[28:31], v[108:111], v[132:135], v[28:31]
	v_mfma_f32_16x16x32_bf16 v[96:99], v[52:55], v[156:159], v[96:99]
	v_mfma_f32_16x16x32_bf16 v[24:27], v[108:111], v[156:159], v[24:27]
	v_mfma_f32_16x16x32_bf16 v[84:87], v[52:55], v[164:167], v[84:87]
	v_mfma_f32_16x16x32_bf16 v[12:15], v[108:111], v[164:167], v[12:15]
	v_mfma_f32_16x16x32_bf16 v[48:51], v[48:51], v[190:193], 0
	v_mfma_f32_16x16x32_bf16 v[8:11], v[108:111], v[194:197], v[8:11]
	v_mfma_f32_16x16x32_bf16 v[48:51], v[52:55], v[194:197], v[48:51]
	v_mfma_f32_16x16x32_bf16 v[76:79], v[198:201], v[140:143], 0
	v_mfma_f32_16x16x32_bf16 v[20:23], v[206:209], v[124:127], 0
	v_mfma_f32_16x16x32_bf16 v[88:91], v[202:205], v[156:159], v[76:79]
	v_mfma_f32_16x16x32_bf16 v[16:19], v[206:209], v[140:143], 0
	v_mfma_f32_16x16x32_bf16 v[76:79], v[198:201], v[160:163], 0
	v_mfma_f32_16x16x32_bf16 v[4:7], v[206:209], v[160:163], 0
	v_mfma_f32_16x16x32_bf16 v[72:75], v[198:201], v[190:193], 0
	v_mfma_f32_16x16x32_bf16 v[0:3], v[206:209], v[190:193], 0
	v_mfma_f32_16x16x32_bf16 v[52:55], v[198:201], v[124:127], 0
	v_mfma_f32_16x16x32_bf16 v[20:23], v[210:213], v[132:135], v[20:23]
	v_mfma_f32_16x16x32_bf16 v[16:19], v[210:213], v[156:159], v[16:19]
	v_mfma_f32_16x16x32_bf16 v[80:83], v[202:205], v[164:167], v[76:79]
	v_mfma_f32_16x16x32_bf16 v[4:7], v[210:213], v[164:167], v[4:7]
	v_mfma_f32_16x16x32_bf16 v[72:75], v[202:205], v[194:197], v[72:75]
	v_mfma_f32_16x16x32_bf16 v[0:3], v[210:213], v[194:197], v[0:3]
	v_mfma_f32_16x16x32_bf16 v[52:55], v[202:205], v[132:135], v[52:55]
	s_barrier
	ds_read_b128 v[76:79], v237 offset:32768
	ds_read_b128 v[92:95], v237 offset:33792
	ds_read_b128 v[104:107], v237 offset:34816
	ds_read_b128 v[108:111], v237 offset:35840
	s_mov_b32 m0, s56
	ds_read_b128 v[124:127], v238 offset:32768
	ds_read_b128 v[132:135], v238 offset:33792
	ds_read_b128 v[156:159], v238 offset:34816
	ds_read_b128 v[160:163], v238 offset:35840
	ds_read_b128 v[164:167], v238 offset:36864
	ds_read_b128 v[190:193], v238 offset:37888
	ds_read_b128 v[194:197], v238 offset:38912
	global_load_lds_dwordx4 v180, s[12:13]
	s_mov_b32 m0, s57
	ds_read_b128 v[198:201], v238 offset:39936
	global_load_lds_dwordx4 v182, s[12:13]
	s_waitcnt lgkmcnt(11)
	ds_read_b128 v[202:205], v237 offset:49152
	ds_read_b128 v[206:209], v237 offset:50176
	ds_read_b128 v[210:213], v237 offset:51200
	ds_read_b128 v[214:217], v237 offset:52224
	s_waitcnt lgkmcnt(0)
	s_barrier
	v_mfma_f32_16x16x32_bf16 v[140:143], v[76:79], v[124:127], v[152:155]
	v_mfma_f32_16x16x32_bf16 v[152:155], v[92:95], v[132:135], v[140:143]
	v_mfma_f32_16x16x32_bf16 v[68:71], v[104:107], v[124:127], v[68:71]
	v_mfma_f32_16x16x32_bf16 v[140:143], v[76:79], v[156:159], v[148:151]
	v_mfma_f32_16x16x32_bf16 v[64:67], v[104:107], v[156:159], v[64:67]
	v_mfma_f32_16x16x32_bf16 v[136:139], v[76:79], v[164:167], v[136:139]
	v_mfma_f32_16x16x32_bf16 v[44:47], v[104:107], v[164:167], v[44:47]
	v_mfma_f32_16x16x32_bf16 v[128:131], v[76:79], v[194:197], v[128:131]
	v_mfma_f32_16x16x32_bf16 v[40:43], v[104:107], v[194:197], v[40:43]
	v_mfma_f32_16x16x32_bf16 v[68:71], v[108:111], v[132:135], v[68:71]
	v_mfma_f32_16x16x32_bf16 v[148:151], v[92:95], v[160:163], v[140:143]
	v_mfma_f32_16x16x32_bf16 v[64:67], v[108:111], v[160:163], v[64:67]
	v_mfma_f32_16x16x32_bf16 v[136:139], v[92:95], v[190:193], v[136:139]
	v_mfma_f32_16x16x32_bf16 v[44:47], v[108:111], v[190:193], v[44:47]
	v_mfma_f32_16x16x32_bf16 v[128:131], v[92:95], v[198:201], v[128:131]
	v_mfma_f32_16x16x32_bf16 v[40:43], v[108:111], v[198:201], v[40:43]
	v_mfma_f32_16x16x32_bf16 v[140:143], v[202:205], v[124:127], v[144:147]
	v_mfma_f32_16x16x32_bf16 v[112:115], v[202:205], v[156:159], v[112:115]
	v_mfma_f32_16x16x32_bf16 v[144:147], v[206:209], v[132:135], v[140:143]
	v_mfma_f32_16x16x32_bf16 v[60:63], v[210:213], v[124:127], v[60:63]
	v_mfma_f32_16x16x32_bf16 v[140:143], v[206:209], v[160:163], v[112:115]
	v_mfma_f32_16x16x32_bf16 v[112:115], v[202:205], v[164:167], v[116:119]
	v_mfma_f32_16x16x32_bf16 v[60:63], v[214:217], v[132:135], v[60:63]
	v_mfma_f32_16x16x32_bf16 v[56:59], v[210:213], v[156:159], v[56:59]
	v_mfma_f32_16x16x32_bf16 v[132:135], v[206:209], v[190:193], v[112:115]
	v_mfma_f32_16x16x32_bf16 v[36:39], v[210:213], v[164:167], v[36:39]
	v_mfma_f32_16x16x32_bf16 v[112:115], v[202:205], v[194:197], v[120:123]
	v_mfma_f32_16x16x32_bf16 v[32:35], v[210:213], v[194:197], v[32:35]
	v_mfma_f32_16x16x32_bf16 v[56:59], v[214:217], v[160:163], v[56:59]
	v_mfma_f32_16x16x32_bf16 v[36:39], v[214:217], v[190:193], v[36:39]
	v_mfma_f32_16x16x32_bf16 v[124:127], v[206:209], v[198:201], v[112:115]
	v_mfma_f32_16x16x32_bf16 v[32:35], v[214:217], v[198:201], v[32:35]
	s_barrier
	s_add_i32 m0, s53, 0x18000
	ds_read_b128 v[112:115], v238 offset:49152
	global_load_lds_dwordx4 v168, s[98:99]
	s_add_i32 m0, s53, 0x1a000
	ds_read_b128 v[116:119], v238 offset:50176
	global_load_lds_dwordx4 v184, s[98:99]
	s_mov_b32 m0, s62
	ds_read_b128 v[120:123], v238 offset:51200
	ds_read_b128 v[156:159], v238 offset:52224
	ds_read_b128 v[160:163], v238 offset:53248
	ds_read_b128 v[164:167], v238 offset:54272
	ds_read_b128 v[190:193], v238 offset:55296
	global_load_lds_dwordx4 v180, s[100:101]
	s_mov_b32 m0, s63
	ds_read_b128 v[194:197], v238 offset:56320
	global_load_lds_dwordx4 v182, s[100:101]
	s_add_i32 m0, s53, 0x1c000
	s_add_u32 s2, s2, 0x40080
	s_addc_u32 s3, s3, 0
	global_load_lds_dwordx4 v168, s[2:3]
	s_add_i32 m0, s53, 0x1e000
	s_add_i32 s67, s67, 2
	global_load_lds_dwordx4 v184, s[2:3]
	s_waitcnt lgkmcnt(0)
	s_waitcnt vmcnt(6)
	s_barrier
	v_mfma_f32_16x16x32_bf16 v[100:103], v[76:79], v[112:115], v[100:103]
	v_mfma_f32_16x16x32_bf16 v[28:31], v[104:107], v[112:115], v[28:31]
	v_mfma_f32_16x16x32_bf16 v[96:99], v[76:79], v[120:123], v[96:99]
	v_mfma_f32_16x16x32_bf16 v[24:27], v[104:107], v[120:123], v[24:27]
	v_mfma_f32_16x16x32_bf16 v[84:87], v[76:79], v[160:163], v[84:87]
	v_mfma_f32_16x16x32_bf16 v[12:15], v[104:107], v[160:163], v[12:15]
	v_mfma_f32_16x16x32_bf16 v[48:51], v[76:79], v[190:193], v[48:51]
	v_mfma_f32_16x16x32_bf16 v[8:11], v[104:107], v[190:193], v[8:11]
	v_mfma_f32_16x16x32_bf16 v[100:103], v[92:95], v[116:119], v[100:103]
	v_mfma_f32_16x16x32_bf16 v[28:31], v[108:111], v[116:119], v[28:31]
	v_mfma_f32_16x16x32_bf16 v[96:99], v[92:95], v[156:159], v[96:99]
	v_mfma_f32_16x16x32_bf16 v[24:27], v[108:111], v[156:159], v[24:27]
	v_mfma_f32_16x16x32_bf16 v[84:87], v[92:95], v[164:167], v[84:87]
	v_mfma_f32_16x16x32_bf16 v[12:15], v[108:111], v[164:167], v[12:15]
	v_mfma_f32_16x16x32_bf16 v[76:79], v[92:95], v[194:197], v[48:51]
	v_mfma_f32_16x16x32_bf16 v[8:11], v[108:111], v[194:197], v[8:11]
	v_mfma_f32_16x16x32_bf16 v[48:51], v[202:205], v[112:115], v[52:55]
	v_mfma_f32_16x16x32_bf16 v[92:95], v[206:209], v[116:119], v[48:51]
	v_mfma_f32_16x16x32_bf16 v[48:51], v[202:205], v[120:123], v[88:91]
	v_mfma_f32_16x16x32_bf16 v[88:91], v[206:209], v[156:159], v[48:51]
	v_mfma_f32_16x16x32_bf16 v[48:51], v[202:205], v[160:163], v[80:83]
	v_mfma_f32_16x16x32_bf16 v[20:23], v[210:213], v[112:115], v[20:23]
	v_mfma_f32_16x16x32_bf16 v[16:19], v[210:213], v[120:123], v[16:19]
	v_mfma_f32_16x16x32_bf16 v[80:83], v[206:209], v[164:167], v[48:51]
	v_mfma_f32_16x16x32_bf16 v[4:7], v[210:213], v[160:163], v[4:7]
	v_mfma_f32_16x16x32_bf16 v[48:51], v[202:205], v[190:193], v[72:75]
	v_mfma_f32_16x16x32_bf16 v[0:3], v[210:213], v[190:193], v[0:3]
	v_mfma_f32_16x16x32_bf16 v[20:23], v[214:217], v[116:119], v[20:23]
	v_mfma_f32_16x16x32_bf16 v[16:19], v[214:217], v[156:159], v[16:19]
	v_mfma_f32_16x16x32_bf16 v[4:7], v[214:217], v[164:167], v[4:7]
	v_mfma_f32_16x16x32_bf16 v[72:75], v[206:209], v[194:197], v[48:51]
	v_mfma_f32_16x16x32_bf16 v[0:3], v[214:217], v[194:197], v[0:3]
	s_add_u32 s10, s10, 0x100
	s_addc_u32 s11, s11, 0
	s_add_u32 s37, s37, 0x100
	s_addc_u32 s39, s39, 0
	s_cmp_gt_u32 s67, 13
	s_barrier
.LBB0_880:
	s_add_u32 s2, s10, 0xfffc0080
	s_addc_u32 s3, s11, -1
	ds_read_b128 v[48:51], v237
	ds_read_b128 v[52:55], v237 offset:1024
	ds_read_b128 v[104:107], v237 offset:2048
	ds_read_b128 v[108:111], v237 offset:3072
	s_cmp_eq_u32 s67, 12
	s_cselect_b32 s13, s1, s3
	s_cselect_b32 s12, s9, s2
	s_cselect_b32 s3, s14, s39
	s_cselect_b32 s2, s15, s37
	s_add_i32 m0, s54, 0xc000
	ds_read_b128 v[112:115], v238
	ds_read_b128 v[116:119], v238 offset:1024
	ds_read_b128 v[120:123], v238 offset:2048
	ds_read_b128 v[156:159], v238 offset:3072
	ds_read_b128 v[160:163], v238 offset:4096
	ds_read_b128 v[164:167], v238 offset:5120
	ds_read_b128 v[190:193], v238 offset:6144
	global_load_lds_dwordx4 v186, s[10:11]
	s_add_i32 m0, s54, 0xe000
	ds_read_b128 v[194:197], v238 offset:7168
	global_load_lds_dwordx4 v188, s[10:11]
	s_waitcnt lgkmcnt(11)
	ds_read_b128 v[198:201], v237 offset:16384
	ds_read_b128 v[202:205], v237 offset:17408
	ds_read_b128 v[206:209], v237 offset:18432
	ds_read_b128 v[210:213], v237 offset:19456
	s_waitcnt lgkmcnt(0)
	s_barrier
	v_mfma_f32_16x16x32_bf16 v[152:155], v[48:51], v[112:115], v[152:155]
	v_mfma_f32_16x16x32_bf16 v[68:71], v[104:107], v[112:115], v[68:71]
	v_mfma_f32_16x16x32_bf16 v[148:151], v[48:51], v[120:123], v[148:151]
	v_mfma_f32_16x16x32_bf16 v[64:67], v[104:107], v[120:123], v[64:67]
	v_mfma_f32_16x16x32_bf16 v[136:139], v[48:51], v[160:163], v[136:139]
	v_mfma_f32_16x16x32_bf16 v[44:47], v[104:107], v[160:163], v[44:47]
	v_mfma_f32_16x16x32_bf16 v[128:131], v[48:51], v[190:193], v[128:131]
	v_mfma_f32_16x16x32_bf16 v[40:43], v[104:107], v[190:193], v[40:43]
	v_mfma_f32_16x16x32_bf16 v[152:155], v[52:55], v[116:119], v[152:155]
	v_mfma_f32_16x16x32_bf16 v[68:71], v[108:111], v[116:119], v[68:71]
	v_mfma_f32_16x16x32_bf16 v[148:151], v[52:55], v[156:159], v[148:151]
	v_mfma_f32_16x16x32_bf16 v[64:67], v[108:111], v[156:159], v[64:67]
	v_mfma_f32_16x16x32_bf16 v[136:139], v[52:55], v[164:167], v[136:139]
	v_mfma_f32_16x16x32_bf16 v[44:47], v[108:111], v[164:167], v[44:47]
	v_mfma_f32_16x16x32_bf16 v[128:131], v[52:55], v[194:197], v[128:131]
	v_mfma_f32_16x16x32_bf16 v[40:43], v[108:111], v[194:197], v[40:43]
	v_mfma_f32_16x16x32_bf16 v[144:147], v[198:201], v[112:115], v[144:147]
	v_mfma_f32_16x16x32_bf16 v[60:63], v[206:209], v[112:115], v[60:63]
	v_mfma_f32_16x16x32_bf16 v[56:59], v[206:209], v[120:123], v[56:59]
	v_mfma_f32_16x16x32_bf16 v[36:39], v[206:209], v[160:163], v[36:39]
	v_mfma_f32_16x16x32_bf16 v[32:35], v[206:209], v[190:193], v[32:35]
	v_mfma_f32_16x16x32_bf16 v[144:147], v[202:205], v[116:119], v[144:147]
	v_mfma_f32_16x16x32_bf16 v[60:63], v[210:213], v[116:119], v[60:63]
	v_mfma_f32_16x16x32_bf16 v[112:115], v[198:201], v[120:123], v[140:143]
	v_mfma_f32_16x16x32_bf16 v[56:59], v[210:213], v[156:159], v[56:59]
	v_mfma_f32_16x16x32_bf16 v[116:119], v[198:201], v[160:163], v[132:135]
	v_mfma_f32_16x16x32_bf16 v[36:39], v[210:213], v[164:167], v[36:39]
	v_mfma_f32_16x16x32_bf16 v[120:123], v[198:201], v[190:193], v[124:127]
	v_mfma_f32_16x16x32_bf16 v[32:35], v[210:213], v[194:197], v[32:35]
	v_mfma_f32_16x16x32_bf16 v[112:115], v[202:205], v[156:159], v[112:115]
	v_mfma_f32_16x16x32_bf16 v[116:119], v[202:205], v[164:167], v[116:119]
	v_mfma_f32_16x16x32_bf16 v[120:123], v[202:205], v[194:197], v[120:123]
	s_barrier
	s_add_u32 s98, s2, 0x80
	s_addc_u32 s99, s3, 0
	s_add_i32 m0, s53, 0x10000
	ds_read_b128 v[124:127], v238 offset:16384
	global_load_lds_dwordx4 v168, s[2:3]
	s_add_i32 m0, s53, 0x12000
	ds_read_b128 v[132:135], v238 offset:17408
	global_load_lds_dwordx4 v184, s[2:3]
	s_mov_b32 m0, s54
	s_add_u32 s100, s12, 0x80
	s_addc_u32 s101, s13, 0
	ds_read_b128 v[140:143], v238 offset:18432
	ds_read_b128 v[156:159], v238 offset:19456
	ds_read_b128 v[160:163], v238 offset:20480
	ds_read_b128 v[164:167], v238 offset:21504
	ds_read_b128 v[190:193], v238 offset:22528
	global_load_lds_dwordx4 v180, s[12:13]
	s_mov_b32 m0, s55
	ds_read_b128 v[194:197], v238 offset:23552
	global_load_lds_dwordx4 v182, s[12:13]
	s_add_i32 m0, s53, 0x14000
	s_add_u32 s68, s2, 0x40000
	s_addc_u32 s69, s3, 0
	global_load_lds_dwordx4 v168, s[68:69]
	s_add_i32 m0, s53, 0x16000
	s_add_u32 s12, s12, 0x40000
	s_addc_u32 s13, s13, 0
	global_load_lds_dwordx4 v184, s[68:69]
	s_waitcnt lgkmcnt(0)
	s_waitcnt vmcnt(6)
	s_barrier
	v_mfma_f32_16x16x32_bf16 v[100:103], v[48:51], v[124:127], v[100:103]
	v_mfma_f32_16x16x32_bf16 v[28:31], v[104:107], v[124:127], v[28:31]
	v_mfma_f32_16x16x32_bf16 v[96:99], v[48:51], v[140:143], v[96:99]
	v_mfma_f32_16x16x32_bf16 v[24:27], v[104:107], v[140:143], v[24:27]
	v_mfma_f32_16x16x32_bf16 v[84:87], v[48:51], v[160:163], v[84:87]
	v_mfma_f32_16x16x32_bf16 v[12:15], v[104:107], v[160:163], v[12:15]
	v_mfma_f32_16x16x32_bf16 v[8:11], v[104:107], v[190:193], v[8:11]
	v_mfma_f32_16x16x32_bf16 v[100:103], v[52:55], v[132:135], v[100:103]
	v_mfma_f32_16x16x32_bf16 v[28:31], v[108:111], v[132:135], v[28:31]
	v_mfma_f32_16x16x32_bf16 v[96:99], v[52:55], v[156:159], v[96:99]
	v_mfma_f32_16x16x32_bf16 v[24:27], v[108:111], v[156:159], v[24:27]
	v_mfma_f32_16x16x32_bf16 v[84:87], v[52:55], v[164:167], v[84:87]
	v_mfma_f32_16x16x32_bf16 v[12:15], v[108:111], v[164:167], v[12:15]
	v_mfma_f32_16x16x32_bf16 v[48:51], v[48:51], v[190:193], v[76:79]
	v_mfma_f32_16x16x32_bf16 v[8:11], v[108:111], v[194:197], v[8:11]
	v_mfma_f32_16x16x32_bf16 v[48:51], v[52:55], v[194:197], v[48:51]
	v_mfma_f32_16x16x32_bf16 v[76:79], v[198:201], v[140:143], v[88:91]
	v_mfma_f32_16x16x32_bf16 v[20:23], v[206:209], v[124:127], v[20:23]
	v_mfma_f32_16x16x32_bf16 v[88:91], v[202:205], v[156:159], v[76:79]
	v_mfma_f32_16x16x32_bf16 v[16:19], v[206:209], v[140:143], v[16:19]
	v_mfma_f32_16x16x32_bf16 v[76:79], v[198:201], v[160:163], v[80:83]
	v_mfma_f32_16x16x32_bf16 v[4:7], v[206:209], v[160:163], v[4:7]
	v_mfma_f32_16x16x32_bf16 v[72:75], v[198:201], v[190:193], v[72:75]
	v_mfma_f32_16x16x32_bf16 v[0:3], v[206:209], v[190:193], v[0:3]
	v_mfma_f32_16x16x32_bf16 v[52:55], v[198:201], v[124:127], v[92:95]
	v_mfma_f32_16x16x32_bf16 v[20:23], v[210:213], v[132:135], v[20:23]
	v_mfma_f32_16x16x32_bf16 v[16:19], v[210:213], v[156:159], v[16:19]
	v_mfma_f32_16x16x32_bf16 v[80:83], v[202:205], v[164:167], v[76:79]
	v_mfma_f32_16x16x32_bf16 v[4:7], v[210:213], v[164:167], v[4:7]
	v_mfma_f32_16x16x32_bf16 v[72:75], v[202:205], v[194:197], v[72:75]
	v_mfma_f32_16x16x32_bf16 v[0:3], v[210:213], v[194:197], v[0:3]
	v_mfma_f32_16x16x32_bf16 v[52:55], v[202:205], v[132:135], v[52:55]
	s_barrier
	ds_read_b128 v[76:79], v237 offset:32768
	ds_read_b128 v[92:95], v237 offset:33792
	ds_read_b128 v[104:107], v237 offset:34816
	ds_read_b128 v[108:111], v237 offset:35840
	s_mov_b32 m0, s56
	ds_read_b128 v[124:127], v238 offset:32768
	ds_read_b128 v[132:135], v238 offset:33792
	ds_read_b128 v[156:159], v238 offset:34816
	ds_read_b128 v[160:163], v238 offset:35840
	ds_read_b128 v[164:167], v238 offset:36864
	ds_read_b128 v[190:193], v238 offset:37888
	ds_read_b128 v[194:197], v238 offset:38912
	global_load_lds_dwordx4 v180, s[12:13]
	s_mov_b32 m0, s57
	ds_read_b128 v[198:201], v238 offset:39936
	global_load_lds_dwordx4 v182, s[12:13]
	s_waitcnt lgkmcnt(11)
	ds_read_b128 v[202:205], v237 offset:49152
	ds_read_b128 v[206:209], v237 offset:50176
	ds_read_b128 v[210:213], v237 offset:51200
	ds_read_b128 v[214:217], v237 offset:52224
	s_waitcnt lgkmcnt(0)
	s_barrier
	v_mfma_f32_16x16x32_bf16 v[140:143], v[76:79], v[124:127], v[152:155]
	v_mfma_f32_16x16x32_bf16 v[152:155], v[92:95], v[132:135], v[140:143]
	v_mfma_f32_16x16x32_bf16 v[68:71], v[104:107], v[124:127], v[68:71]
	v_mfma_f32_16x16x32_bf16 v[140:143], v[76:79], v[156:159], v[148:151]
	v_mfma_f32_16x16x32_bf16 v[64:67], v[104:107], v[156:159], v[64:67]
	v_mfma_f32_16x16x32_bf16 v[136:139], v[76:79], v[164:167], v[136:139]
	v_mfma_f32_16x16x32_bf16 v[44:47], v[104:107], v[164:167], v[44:47]
	v_mfma_f32_16x16x32_bf16 v[128:131], v[76:79], v[194:197], v[128:131]
	v_mfma_f32_16x16x32_bf16 v[40:43], v[104:107], v[194:197], v[40:43]
	v_mfma_f32_16x16x32_bf16 v[68:71], v[108:111], v[132:135], v[68:71]
	v_mfma_f32_16x16x32_bf16 v[148:151], v[92:95], v[160:163], v[140:143]
	v_mfma_f32_16x16x32_bf16 v[64:67], v[108:111], v[160:163], v[64:67]
	v_mfma_f32_16x16x32_bf16 v[136:139], v[92:95], v[190:193], v[136:139]
	v_mfma_f32_16x16x32_bf16 v[44:47], v[108:111], v[190:193], v[44:47]
	v_mfma_f32_16x16x32_bf16 v[128:131], v[92:95], v[198:201], v[128:131]
	v_mfma_f32_16x16x32_bf16 v[40:43], v[108:111], v[198:201], v[40:43]
	v_mfma_f32_16x16x32_bf16 v[140:143], v[202:205], v[124:127], v[144:147]
	v_mfma_f32_16x16x32_bf16 v[112:115], v[202:205], v[156:159], v[112:115]
	v_mfma_f32_16x16x32_bf16 v[144:147], v[206:209], v[132:135], v[140:143]
	v_mfma_f32_16x16x32_bf16 v[60:63], v[210:213], v[124:127], v[60:63]
	v_mfma_f32_16x16x32_bf16 v[140:143], v[206:209], v[160:163], v[112:115]
	v_mfma_f32_16x16x32_bf16 v[112:115], v[202:205], v[164:167], v[116:119]
	v_mfma_f32_16x16x32_bf16 v[60:63], v[214:217], v[132:135], v[60:63]
	v_mfma_f32_16x16x32_bf16 v[56:59], v[210:213], v[156:159], v[56:59]
	v_mfma_f32_16x16x32_bf16 v[132:135], v[206:209], v[190:193], v[112:115]
	v_mfma_f32_16x16x32_bf16 v[36:39], v[210:213], v[164:167], v[36:39]
	v_mfma_f32_16x16x32_bf16 v[112:115], v[202:205], v[194:197], v[120:123]
	v_mfma_f32_16x16x32_bf16 v[32:35], v[210:213], v[194:197], v[32:35]
	v_mfma_f32_16x16x32_bf16 v[56:59], v[214:217], v[160:163], v[56:59]
	v_mfma_f32_16x16x32_bf16 v[36:39], v[214:217], v[190:193], v[36:39]
	v_mfma_f32_16x16x32_bf16 v[124:127], v[206:209], v[198:201], v[112:115]
	v_mfma_f32_16x16x32_bf16 v[32:35], v[214:217], v[198:201], v[32:35]
	s_barrier
	s_add_i32 m0, s53, 0x18000
	ds_read_b128 v[112:115], v238 offset:49152
	global_load_lds_dwordx4 v168, s[98:99]
	s_add_i32 m0, s53, 0x1a000
	ds_read_b128 v[116:119], v238 offset:50176
	global_load_lds_dwordx4 v184, s[98:99]
	s_mov_b32 m0, s62
	ds_read_b128 v[120:123], v238 offset:51200
	ds_read_b128 v[156:159], v238 offset:52224
	ds_read_b128 v[160:163], v238 offset:53248
	ds_read_b128 v[164:167], v238 offset:54272
	ds_read_b128 v[190:193], v238 offset:55296
	global_load_lds_dwordx4 v180, s[100:101]
	s_mov_b32 m0, s63
	ds_read_b128 v[194:197], v238 offset:56320
	global_load_lds_dwordx4 v182, s[100:101]
	s_add_i32 m0, s53, 0x1c000
	s_add_u32 s2, s2, 0x40080
	s_addc_u32 s3, s3, 0
	global_load_lds_dwordx4 v168, s[2:3]
	s_add_i32 m0, s53, 0x1e000
	s_add_i32 s67, s67, 2
	global_load_lds_dwordx4 v184, s[2:3]
	s_waitcnt lgkmcnt(0)
	s_waitcnt vmcnt(6)
	s_barrier
	v_mfma_f32_16x16x32_bf16 v[100:103], v[76:79], v[112:115], v[100:103]
	v_mfma_f32_16x16x32_bf16 v[28:31], v[104:107], v[112:115], v[28:31]
	v_mfma_f32_16x16x32_bf16 v[96:99], v[76:79], v[120:123], v[96:99]
	v_mfma_f32_16x16x32_bf16 v[24:27], v[104:107], v[120:123], v[24:27]
	v_mfma_f32_16x16x32_bf16 v[84:87], v[76:79], v[160:163], v[84:87]
	v_mfma_f32_16x16x32_bf16 v[12:15], v[104:107], v[160:163], v[12:15]
	v_mfma_f32_16x16x32_bf16 v[48:51], v[76:79], v[190:193], v[48:51]
	v_mfma_f32_16x16x32_bf16 v[8:11], v[104:107], v[190:193], v[8:11]
	v_mfma_f32_16x16x32_bf16 v[100:103], v[92:95], v[116:119], v[100:103]
	v_mfma_f32_16x16x32_bf16 v[28:31], v[108:111], v[116:119], v[28:31]
	v_mfma_f32_16x16x32_bf16 v[96:99], v[92:95], v[156:159], v[96:99]
	v_mfma_f32_16x16x32_bf16 v[24:27], v[108:111], v[156:159], v[24:27]
	v_mfma_f32_16x16x32_bf16 v[84:87], v[92:95], v[164:167], v[84:87]
	v_mfma_f32_16x16x32_bf16 v[12:15], v[108:111], v[164:167], v[12:15]
	v_mfma_f32_16x16x32_bf16 v[76:79], v[92:95], v[194:197], v[48:51]
	v_mfma_f32_16x16x32_bf16 v[8:11], v[108:111], v[194:197], v[8:11]
	v_mfma_f32_16x16x32_bf16 v[48:51], v[202:205], v[112:115], v[52:55]
	v_mfma_f32_16x16x32_bf16 v[92:95], v[206:209], v[116:119], v[48:51]
	v_mfma_f32_16x16x32_bf16 v[48:51], v[202:205], v[120:123], v[88:91]
	v_mfma_f32_16x16x32_bf16 v[88:91], v[206:209], v[156:159], v[48:51]
	v_mfma_f32_16x16x32_bf16 v[48:51], v[202:205], v[160:163], v[80:83]
	v_mfma_f32_16x16x32_bf16 v[20:23], v[210:213], v[112:115], v[20:23]
	v_mfma_f32_16x16x32_bf16 v[16:19], v[210:213], v[120:123], v[16:19]
	v_mfma_f32_16x16x32_bf16 v[80:83], v[206:209], v[164:167], v[48:51]
	v_mfma_f32_16x16x32_bf16 v[4:7], v[210:213], v[160:163], v[4:7]
	v_mfma_f32_16x16x32_bf16 v[48:51], v[202:205], v[190:193], v[72:75]
	v_mfma_f32_16x16x32_bf16 v[0:3], v[210:213], v[190:193], v[0:3]
	v_mfma_f32_16x16x32_bf16 v[20:23], v[214:217], v[116:119], v[20:23]
	v_mfma_f32_16x16x32_bf16 v[16:19], v[214:217], v[156:159], v[16:19]
	v_mfma_f32_16x16x32_bf16 v[4:7], v[214:217], v[164:167], v[4:7]
	v_mfma_f32_16x16x32_bf16 v[72:75], v[206:209], v[194:197], v[48:51]
	v_mfma_f32_16x16x32_bf16 v[0:3], v[214:217], v[194:197], v[0:3]
	s_add_u32 s10, s10, 0x100
	s_addc_u32 s11, s11, 0
	s_add_u32 s37, s37, 0x100
	s_addc_u32 s39, s39, 0
	s_cmp_gt_u32 s67, 13
	s_barrier
	s_cbranch_scc0 .LBB0_880

.LBB0_1048:
	s_add_u32 s56, s2, 0x100
	s_addc_u32 s57, s3, 0
	s_mov_b32 s58, -2
	s_add_u32 s2, s24, 0x100
	s_addc_u32 s3, s25, 0
	ds_read_b128 v[40:43], v194
	ds_read_b128 v[44:47], v194 offset:1024
	ds_read_b128 v[48:51], v194 offset:2048
	ds_read_b128 v[52:55], v194 offset:3072
	s_cmp_eq_u32 s58, 40
	s_cselect_b32 s27, s1, s3
	s_cselect_b32 s26, s0, s2
	s_cselect_b32 s9, s23, s57
	s_cselect_b32 s8, s22, s56
	s_add_i32 m0, s37, 0xc000
	ds_read_b128 v[56:59], v195
	ds_read_b128 v[60:63], v195 offset:1024
	ds_read_b128 v[72:75], v195 offset:2048
	ds_read_b128 v[84:87], v195 offset:3072
	ds_read_b128 v[182:185], v195 offset:4096
	ds_read_b128 v[186:189], v195 offset:5120
	ds_read_b128 v[196:199], v195 offset:6144
	global_load_lds_dwordx4 v166, s[24:25]
	s_add_i32 m0, s37, 0xe000
	ds_read_b128 v[200:203], v195 offset:7168
	global_load_lds_dwordx4 v180, s[24:25]
	s_waitcnt lgkmcnt(11)
	ds_read_b128 v[204:207], v194 offset:16384
	ds_read_b128 v[208:211], v194 offset:17408
	ds_read_b128 v[212:215], v194 offset:18432
	ds_read_b128 v[216:219], v194 offset:19456
	s_waitcnt lgkmcnt(0)
	s_barrier
	v_mfma_f32_16x16x32_bf16 v[156:159], v[40:43], v[56:59], 0
	v_mfma_f32_16x16x32_bf16 v[152:155], v[48:51], v[56:59], 0
	v_mfma_f32_16x16x32_bf16 v[140:143], v[40:43], v[72:75], 0
	v_mfma_f32_16x16x32_bf16 v[136:139], v[48:51], v[72:75], 0
	v_mfma_f32_16x16x32_bf16 v[124:127], v[40:43], v[182:185], 0
	v_mfma_f32_16x16x32_bf16 v[120:123], v[48:51], v[182:185], 0
	v_mfma_f32_16x16x32_bf16 v[108:111], v[40:43], v[196:199], 0
	v_mfma_f32_16x16x32_bf16 v[104:107], v[48:51], v[196:199], 0
	v_mfma_f32_16x16x32_bf16 v[156:159], v[44:47], v[60:63], v[156:159]
	v_mfma_f32_16x16x32_bf16 v[152:155], v[52:55], v[60:63], v[152:155]
	v_mfma_f32_16x16x32_bf16 v[140:143], v[44:47], v[84:87], v[140:143]
	v_mfma_f32_16x16x32_bf16 v[136:139], v[52:55], v[84:87], v[136:139]
	v_mfma_f32_16x16x32_bf16 v[124:127], v[44:47], v[186:189], v[124:127]
	v_mfma_f32_16x16x32_bf16 v[120:123], v[52:55], v[186:189], v[120:123]
	v_mfma_f32_16x16x32_bf16 v[108:111], v[44:47], v[200:203], v[108:111]
	v_mfma_f32_16x16x32_bf16 v[104:107], v[52:55], v[200:203], v[104:107]
	v_mfma_f32_16x16x32_bf16 v[148:151], v[204:207], v[56:59], 0
	v_mfma_f32_16x16x32_bf16 v[56:59], v[212:215], v[56:59], 0
	v_mfma_f32_16x16x32_bf16 v[148:151], v[208:211], v[60:63], v[148:151]
	v_mfma_f32_16x16x32_bf16 v[56:59], v[216:219], v[60:63], v[56:59]
	v_mfma_f32_16x16x32_bf16 v[60:63], v[204:207], v[72:75], 0
	v_mfma_f32_16x16x32_bf16 v[72:75], v[212:215], v[72:75], 0
	v_mfma_f32_16x16x32_bf16 v[112:115], v[212:215], v[182:185], 0
	v_mfma_f32_16x16x32_bf16 v[100:103], v[204:207], v[196:199], 0
	v_mfma_f32_16x16x32_bf16 v[96:99], v[212:215], v[196:199], 0
	v_mfma_f32_16x16x32_bf16 v[60:63], v[208:211], v[84:87], v[60:63]
	v_mfma_f32_16x16x32_bf16 v[72:75], v[216:219], v[84:87], v[72:75]
	v_mfma_f32_16x16x32_bf16 v[84:87], v[204:207], v[182:185], 0
	v_mfma_f32_16x16x32_bf16 v[112:115], v[216:219], v[186:189], v[112:115]
	v_mfma_f32_16x16x32_bf16 v[100:103], v[208:211], v[200:203], v[100:103]
	v_mfma_f32_16x16x32_bf16 v[96:99], v[216:219], v[200:203], v[96:99]
	v_mfma_f32_16x16x32_bf16 v[84:87], v[208:211], v[186:189], v[84:87]
	s_barrier
	s_add_i32 m0, s36, 0x10000
	ds_read_b128 v[116:119], v195 offset:16384
	global_load_lds_dwordx4 v168, s[8:9]
	s_add_i32 m0, s36, 0x12000
	s_add_u32 s98, s8, 0x80
	s_addc_u32 s99, s9, 0
	global_load_lds_dwordx4 v164, s[8:9]
	s_mov_b32 m0, s37
	s_add_u32 s100, s26, 0x80
	s_addc_u32 s101, s27, 0
	ds_read_b128 v[128:131], v195 offset:17408
	ds_read_b128 v[132:135], v195 offset:18432
	ds_read_b128 v[144:147], v195 offset:19456
	ds_read_b128 v[182:185], v195 offset:20480
	ds_read_b128 v[186:189], v195 offset:21504
	ds_read_b128 v[196:199], v195 offset:22528
	global_load_lds_dwordx4 v160, s[26:27]
	s_mov_b32 m0, s38
	ds_read_b128 v[200:203], v195 offset:23552
	global_load_lds_dwordx4 v162, s[26:27]
	s_add_i32 m0, s36, 0x14000
	s_add_u32 s24, s8, 0xb0000
	s_addc_u32 s25, s9, 0
	global_load_lds_dwordx4 v168, s[24:25]
	s_add_i32 m0, s36, 0x16000
	s_nop 0
	global_load_lds_dwordx4 v164, s[24:25]
	s_waitcnt lgkmcnt(0)
	s_waitcnt vmcnt(6)
	s_barrier
	v_mfma_f32_16x16x32_bf16 v[92:95], v[40:43], v[116:119], 0
	v_mfma_f32_16x16x32_bf16 v[88:91], v[48:51], v[116:119], 0
	v_mfma_f32_16x16x32_bf16 v[68:71], v[40:43], v[132:135], 0
	v_mfma_f32_16x16x32_bf16 v[64:67], v[48:51], v[132:135], 0
	v_mfma_f32_16x16x32_bf16 v[28:31], v[40:43], v[182:185], 0
	v_mfma_f32_16x16x32_bf16 v[24:27], v[48:51], v[182:185], 0
	v_mfma_f32_16x16x32_bf16 v[12:15], v[40:43], v[196:199], 0
	v_mfma_f32_16x16x32_bf16 v[8:11], v[48:51], v[196:199], 0
	v_mfma_f32_16x16x32_bf16 v[92:95], v[44:47], v[128:131], v[92:95]
	v_mfma_f32_16x16x32_bf16 v[88:91], v[52:55], v[128:131], v[88:91]
	v_mfma_f32_16x16x32_bf16 v[68:71], v[44:47], v[144:147], v[68:71]
	v_mfma_f32_16x16x32_bf16 v[64:67], v[52:55], v[144:147], v[64:67]
	v_mfma_f32_16x16x32_bf16 v[28:31], v[44:47], v[186:189], v[28:31]
	v_mfma_f32_16x16x32_bf16 v[24:27], v[52:55], v[186:189], v[24:27]
	v_mfma_f32_16x16x32_bf16 v[12:15], v[44:47], v[200:203], v[12:15]
	v_mfma_f32_16x16x32_bf16 v[8:11], v[52:55], v[200:203], v[8:11]
	v_mfma_f32_16x16x32_bf16 v[36:39], v[204:207], v[132:135], 0
	v_mfma_f32_16x16x32_bf16 v[32:35], v[212:215], v[132:135], 0
	v_mfma_f32_16x16x32_bf16 v[20:23], v[204:207], v[182:185], 0
	v_mfma_f32_16x16x32_bf16 v[16:19], v[212:215], v[182:185], 0
	v_mfma_f32_16x16x32_bf16 v[4:7], v[204:207], v[196:199], 0
	v_mfma_f32_16x16x32_bf16 v[0:3], v[212:215], v[196:199], 0
	v_mfma_f32_16x16x32_bf16 v[40:43], v[204:207], v[116:119], 0
	v_mfma_f32_16x16x32_bf16 v[44:47], v[212:215], v[116:119], 0
	v_mfma_f32_16x16x32_bf16 v[36:39], v[208:211], v[144:147], v[36:39]
	v_mfma_f32_16x16x32_bf16 v[32:35], v[216:219], v[144:147], v[32:35]
	v_mfma_f32_16x16x32_bf16 v[20:23], v[208:211], v[186:189], v[20:23]
	v_mfma_f32_16x16x32_bf16 v[16:19], v[216:219], v[186:189], v[16:19]
	v_mfma_f32_16x16x32_bf16 v[4:7], v[208:211], v[200:203], v[4:7]
	v_mfma_f32_16x16x32_bf16 v[0:3], v[216:219], v[200:203], v[0:3]
	v_mfma_f32_16x16x32_bf16 v[40:43], v[208:211], v[128:131], v[40:43]
	v_mfma_f32_16x16x32_bf16 v[44:47], v[216:219], v[128:131], v[44:47]
	s_barrier
	ds_read_b128 v[48:51], v194 offset:32768
	ds_read_b128 v[52:55], v194 offset:33792
	ds_read_b128 v[76:79], v194 offset:34816
	ds_read_b128 v[80:83], v194 offset:35840
	s_add_u32 s24, s26, 0xb0000
	s_addc_u32 s25, s27, 0
	s_mov_b32 m0, s39
	ds_read_b128 v[116:119], v195 offset:32768
	ds_read_b128 v[128:131], v195 offset:33792
	ds_read_b128 v[182:185], v195 offset:34816
	ds_read_b128 v[186:189], v195 offset:35840
	ds_read_b128 v[196:199], v195 offset:36864
	ds_read_b128 v[200:203], v195 offset:37888
	ds_read_b128 v[204:207], v195 offset:38912
	global_load_lds_dwordx4 v160, s[24:25]
	s_mov_b32 m0, s40
	ds_read_b128 v[208:211], v195 offset:39936
	global_load_lds_dwordx4 v162, s[24:25]
	s_waitcnt lgkmcnt(11)
	ds_read_b128 v[212:215], v194 offset:49152
	ds_read_b128 v[216:219], v194 offset:50176
	ds_read_b128 v[220:223], v194 offset:51200
	ds_read_b128 v[236:239], v194 offset:52224
	s_waitcnt lgkmcnt(0)
	s_barrier
	v_mfma_f32_16x16x32_bf16 v[132:135], v[48:51], v[116:119], v[156:159]
	v_mfma_f32_16x16x32_bf16 v[156:159], v[52:55], v[128:131], v[132:135]
	v_mfma_f32_16x16x32_bf16 v[132:135], v[76:79], v[116:119], v[152:155]
	v_mfma_f32_16x16x32_bf16 v[152:155], v[80:83], v[128:131], v[132:135]
	v_mfma_f32_16x16x32_bf16 v[132:135], v[48:51], v[182:185], v[140:143]
	v_mfma_f32_16x16x32_bf16 v[140:143], v[52:55], v[186:189], v[132:135]
	v_mfma_f32_16x16x32_bf16 v[132:135], v[76:79], v[182:185], v[136:139]
	v_mfma_f32_16x16x32_bf16 v[124:127], v[48:51], v[196:199], v[124:127]
	v_mfma_f32_16x16x32_bf16 v[120:123], v[76:79], v[196:199], v[120:123]
	v_mfma_f32_16x16x32_bf16 v[108:111], v[48:51], v[204:207], v[108:111]
	v_mfma_f32_16x16x32_bf16 v[104:107], v[76:79], v[204:207], v[104:107]
	v_mfma_f32_16x16x32_bf16 v[136:139], v[80:83], v[186:189], v[132:135]
	v_mfma_f32_16x16x32_bf16 v[124:127], v[52:55], v[200:203], v[124:127]
	v_mfma_f32_16x16x32_bf16 v[120:123], v[80:83], v[200:203], v[120:123]
	v_mfma_f32_16x16x32_bf16 v[108:111], v[52:55], v[208:211], v[108:111]
	v_mfma_f32_16x16x32_bf16 v[104:107], v[80:83], v[208:211], v[104:107]
	v_mfma_f32_16x16x32_bf16 v[56:59], v[220:223], v[116:119], v[56:59]
	v_mfma_f32_16x16x32_bf16 v[132:135], v[212:215], v[116:119], v[148:151]
	v_mfma_f32_16x16x32_bf16 v[144:147], v[236:239], v[128:131], v[56:59]
	v_mfma_f32_16x16x32_bf16 v[56:59], v[212:215], v[182:185], v[60:63]
	v_mfma_f32_16x16x32_bf16 v[148:151], v[216:219], v[128:131], v[132:135]
	v_mfma_f32_16x16x32_bf16 v[132:135], v[216:219], v[186:189], v[56:59]
	v_mfma_f32_16x16x32_bf16 v[56:59], v[220:223], v[182:185], v[72:75]
	v_mfma_f32_16x16x32_bf16 v[128:131], v[236:239], v[186:189], v[56:59]
	v_mfma_f32_16x16x32_bf16 v[56:59], v[212:215], v[196:199], v[84:87]
	v_mfma_f32_16x16x32_bf16 v[116:119], v[216:219], v[200:203], v[56:59]
	v_mfma_f32_16x16x32_bf16 v[56:59], v[220:223], v[196:199], v[112:115]
	v_mfma_f32_16x16x32_bf16 v[112:115], v[236:239], v[200:203], v[56:59]
	v_mfma_f32_16x16x32_bf16 v[56:59], v[212:215], v[204:207], v[100:103]
	v_mfma_f32_16x16x32_bf16 v[100:103], v[216:219], v[208:211], v[56:59]
	v_mfma_f32_16x16x32_bf16 v[56:59], v[220:223], v[204:207], v[96:99]
	v_mfma_f32_16x16x32_bf16 v[96:99], v[236:239], v[208:211], v[56:59]
	s_barrier
	s_add_i32 m0, s36, 0x18000
	ds_read_b128 v[56:59], v195 offset:49152
	global_load_lds_dwordx4 v168, s[98:99]
	s_add_i32 m0, s36, 0x1a000
	ds_read_b128 v[60:63], v195 offset:50176
	global_load_lds_dwordx4 v164, s[98:99]
	s_mov_b32 m0, s47
	s_nop 2
	ds_read_b128 v[72:75], v195 offset:51200
	ds_read_b128 v[84:87], v195 offset:52224
	ds_read_b128 v[182:185], v195 offset:53248
	ds_read_b128 v[186:189], v195 offset:54272
	ds_read_b128 v[196:199], v195 offset:55296
	global_load_lds_dwordx4 v160, s[100:101]
	s_mov_b32 m0, s49
	ds_read_b128 v[200:203], v195 offset:56320
	global_load_lds_dwordx4 v162, s[100:101]
	s_add_i32 m0, s36, 0x1c000
	s_add_u32 s8, s8, 0xb0080
	s_addc_u32 s9, s9, 0
	global_load_lds_dwordx4 v168, s[8:9]
	s_add_i32 m0, s36, 0x1e000
	s_add_i32 s58, s58, 2
	global_load_lds_dwordx4 v164, s[8:9]
	s_waitcnt lgkmcnt(0)
	s_waitcnt vmcnt(6)
	s_barrier
	v_mfma_f32_16x16x32_bf16 v[92:95], v[48:51], v[56:59], v[92:95]
	v_mfma_f32_16x16x32_bf16 v[88:91], v[76:79], v[56:59], v[88:91]
	v_mfma_f32_16x16x32_bf16 v[68:71], v[48:51], v[72:75], v[68:71]
	v_mfma_f32_16x16x32_bf16 v[64:67], v[76:79], v[72:75], v[64:67]
	v_mfma_f32_16x16x32_bf16 v[28:31], v[48:51], v[182:185], v[28:31]
	v_mfma_f32_16x16x32_bf16 v[24:27], v[76:79], v[182:185], v[24:27]
	v_mfma_f32_16x16x32_bf16 v[12:15], v[48:51], v[196:199], v[12:15]
	v_mfma_f32_16x16x32_bf16 v[8:11], v[76:79], v[196:199], v[8:11]
	v_mfma_f32_16x16x32_bf16 v[92:95], v[52:55], v[60:63], v[92:95]
	v_mfma_f32_16x16x32_bf16 v[88:91], v[80:83], v[60:63], v[88:91]
	v_mfma_f32_16x16x32_bf16 v[68:71], v[52:55], v[84:87], v[68:71]
	v_mfma_f32_16x16x32_bf16 v[64:67], v[80:83], v[84:87], v[64:67]
	v_mfma_f32_16x16x32_bf16 v[28:31], v[52:55], v[186:189], v[28:31]
	v_mfma_f32_16x16x32_bf16 v[24:27], v[80:83], v[186:189], v[24:27]
	v_mfma_f32_16x16x32_bf16 v[12:15], v[52:55], v[200:203], v[12:15]
	v_mfma_f32_16x16x32_bf16 v[8:11], v[80:83], v[200:203], v[8:11]
	v_mfma_f32_16x16x32_bf16 v[40:43], v[212:215], v[56:59], v[40:43]
	v_mfma_f32_16x16x32_bf16 v[80:83], v[216:219], v[60:63], v[40:43]
	v_mfma_f32_16x16x32_bf16 v[40:43], v[220:223], v[56:59], v[44:47]
	v_mfma_f32_16x16x32_bf16 v[36:39], v[212:215], v[72:75], v[36:39]
	v_mfma_f32_16x16x32_bf16 v[32:35], v[220:223], v[72:75], v[32:35]
	v_mfma_f32_16x16x32_bf16 v[20:23], v[212:215], v[182:185], v[20:23]
	v_mfma_f32_16x16x32_bf16 v[16:19], v[220:223], v[182:185], v[16:19]
	v_mfma_f32_16x16x32_bf16 v[4:7], v[212:215], v[196:199], v[4:7]
	v_mfma_f32_16x16x32_bf16 v[0:3], v[220:223], v[196:199], v[0:3]
	v_mfma_f32_16x16x32_bf16 v[76:79], v[236:239], v[60:63], v[40:43]
	v_mfma_f32_16x16x32_bf16 v[36:39], v[216:219], v[84:87], v[36:39]
	v_mfma_f32_16x16x32_bf16 v[32:35], v[236:239], v[84:87], v[32:35]
	v_mfma_f32_16x16x32_bf16 v[20:23], v[216:219], v[186:189], v[20:23]
	v_mfma_f32_16x16x32_bf16 v[16:19], v[236:239], v[186:189], v[16:19]
	v_mfma_f32_16x16x32_bf16 v[4:7], v[216:219], v[200:203], v[4:7]
	v_mfma_f32_16x16x32_bf16 v[0:3], v[236:239], v[200:203], v[0:3]
	s_add_u32 s56, s56, 0x100
	s_addc_u32 s57, s57, 0
	s_cmp_gt_u32 s58, 41
	s_mov_b64 s[24:25], s[2:3]
	s_barrier
.LBB0_1049:
	s_add_u32 s2, s24, 0x100
	s_addc_u32 s3, s25, 0
	ds_read_b128 v[40:43], v194
	ds_read_b128 v[44:47], v194 offset:1024
	ds_read_b128 v[48:51], v194 offset:2048
	ds_read_b128 v[52:55], v194 offset:3072
	s_cmp_eq_u32 s58, 40
	s_cselect_b32 s27, s1, s3
	s_cselect_b32 s26, s0, s2
	s_cselect_b32 s9, s23, s57
	s_cselect_b32 s8, s22, s56
	s_add_i32 m0, s37, 0xc000
	ds_read_b128 v[56:59], v195
	ds_read_b128 v[60:63], v195 offset:1024
	ds_read_b128 v[72:75], v195 offset:2048
	ds_read_b128 v[84:87], v195 offset:3072
	ds_read_b128 v[182:185], v195 offset:4096
	ds_read_b128 v[186:189], v195 offset:5120
	ds_read_b128 v[196:199], v195 offset:6144
	global_load_lds_dwordx4 v166, s[24:25]
	s_add_i32 m0, s37, 0xe000
	ds_read_b128 v[200:203], v195 offset:7168
	global_load_lds_dwordx4 v180, s[24:25]
	s_waitcnt lgkmcnt(11)
	ds_read_b128 v[204:207], v194 offset:16384
	ds_read_b128 v[208:211], v194 offset:17408
	ds_read_b128 v[212:215], v194 offset:18432
	ds_read_b128 v[216:219], v194 offset:19456
	s_waitcnt lgkmcnt(0)
	s_barrier
	v_mfma_f32_16x16x32_bf16 v[156:159], v[40:43], v[56:59], v[156:159]
	v_mfma_f32_16x16x32_bf16 v[152:155], v[48:51], v[56:59], v[152:155]
	v_mfma_f32_16x16x32_bf16 v[140:143], v[40:43], v[72:75], v[140:143]
	v_mfma_f32_16x16x32_bf16 v[136:139], v[48:51], v[72:75], v[136:139]
	v_mfma_f32_16x16x32_bf16 v[124:127], v[40:43], v[182:185], v[124:127]
	v_mfma_f32_16x16x32_bf16 v[120:123], v[48:51], v[182:185], v[120:123]
	v_mfma_f32_16x16x32_bf16 v[108:111], v[40:43], v[196:199], v[108:111]
	v_mfma_f32_16x16x32_bf16 v[104:107], v[48:51], v[196:199], v[104:107]
	v_mfma_f32_16x16x32_bf16 v[156:159], v[44:47], v[60:63], v[156:159]
	v_mfma_f32_16x16x32_bf16 v[152:155], v[52:55], v[60:63], v[152:155]
	v_mfma_f32_16x16x32_bf16 v[140:143], v[44:47], v[84:87], v[140:143]
	v_mfma_f32_16x16x32_bf16 v[136:139], v[52:55], v[84:87], v[136:139]
	v_mfma_f32_16x16x32_bf16 v[124:127], v[44:47], v[186:189], v[124:127]
	v_mfma_f32_16x16x32_bf16 v[120:123], v[52:55], v[186:189], v[120:123]
	v_mfma_f32_16x16x32_bf16 v[108:111], v[44:47], v[200:203], v[108:111]
	v_mfma_f32_16x16x32_bf16 v[104:107], v[52:55], v[200:203], v[104:107]
	v_mfma_f32_16x16x32_bf16 v[148:151], v[204:207], v[56:59], v[148:151]
	v_mfma_f32_16x16x32_bf16 v[56:59], v[212:215], v[56:59], v[144:147]
	v_mfma_f32_16x16x32_bf16 v[148:151], v[208:211], v[60:63], v[148:151]
	v_mfma_f32_16x16x32_bf16 v[56:59], v[216:219], v[60:63], v[56:59]
	v_mfma_f32_16x16x32_bf16 v[60:63], v[204:207], v[72:75], v[132:135]
	v_mfma_f32_16x16x32_bf16 v[72:75], v[212:215], v[72:75], v[128:131]
	v_mfma_f32_16x16x32_bf16 v[112:115], v[212:215], v[182:185], v[112:115]
	v_mfma_f32_16x16x32_bf16 v[100:103], v[204:207], v[196:199], v[100:103]
	v_mfma_f32_16x16x32_bf16 v[96:99], v[212:215], v[196:199], v[96:99]
	v_mfma_f32_16x16x32_bf16 v[60:63], v[208:211], v[84:87], v[60:63]
	v_mfma_f32_16x16x32_bf16 v[72:75], v[216:219], v[84:87], v[72:75]
	v_mfma_f32_16x16x32_bf16 v[84:87], v[204:207], v[182:185], v[116:119]
	v_mfma_f32_16x16x32_bf16 v[112:115], v[216:219], v[186:189], v[112:115]
	v_mfma_f32_16x16x32_bf16 v[100:103], v[208:211], v[200:203], v[100:103]
	v_mfma_f32_16x16x32_bf16 v[96:99], v[216:219], v[200:203], v[96:99]
	v_mfma_f32_16x16x32_bf16 v[84:87], v[208:211], v[186:189], v[84:87]
	s_barrier
	s_add_i32 m0, s36, 0x10000
	ds_read_b128 v[116:119], v195 offset:16384
	global_load_lds_dwordx4 v168, s[8:9]
	s_add_i32 m0, s36, 0x12000
	s_add_u32 s98, s8, 0x80
	s_addc_u32 s99, s9, 0
	global_load_lds_dwordx4 v164, s[8:9]
	s_mov_b32 m0, s37
	s_add_u32 s100, s26, 0x80
	s_addc_u32 s101, s27, 0
	ds_read_b128 v[128:131], v195 offset:17408
	ds_read_b128 v[132:135], v195 offset:18432
	ds_read_b128 v[144:147], v195 offset:19456
	ds_read_b128 v[182:185], v195 offset:20480
	ds_read_b128 v[186:189], v195 offset:21504
	ds_read_b128 v[196:199], v195 offset:22528
	global_load_lds_dwordx4 v160, s[26:27]
	s_mov_b32 m0, s38
	ds_read_b128 v[200:203], v195 offset:23552
	global_load_lds_dwordx4 v162, s[26:27]
	s_add_i32 m0, s36, 0x14000
	s_add_u32 s24, s8, 0xb0000
	s_addc_u32 s25, s9, 0
	global_load_lds_dwordx4 v168, s[24:25]
	s_add_i32 m0, s36, 0x16000
	s_nop 0
	global_load_lds_dwordx4 v164, s[24:25]
	s_waitcnt lgkmcnt(0)
	s_waitcnt vmcnt(6)
	s_barrier
	v_mfma_f32_16x16x32_bf16 v[92:95], v[40:43], v[116:119], v[92:95]
	v_mfma_f32_16x16x32_bf16 v[88:91], v[48:51], v[116:119], v[88:91]
	v_mfma_f32_16x16x32_bf16 v[68:71], v[40:43], v[132:135], v[68:71]
	v_mfma_f32_16x16x32_bf16 v[64:67], v[48:51], v[132:135], v[64:67]
	v_mfma_f32_16x16x32_bf16 v[28:31], v[40:43], v[182:185], v[28:31]
	v_mfma_f32_16x16x32_bf16 v[24:27], v[48:51], v[182:185], v[24:27]
	v_mfma_f32_16x16x32_bf16 v[12:15], v[40:43], v[196:199], v[12:15]
	v_mfma_f32_16x16x32_bf16 v[8:11], v[48:51], v[196:199], v[8:11]
	v_mfma_f32_16x16x32_bf16 v[92:95], v[44:47], v[128:131], v[92:95]
	v_mfma_f32_16x16x32_bf16 v[88:91], v[52:55], v[128:131], v[88:91]
	v_mfma_f32_16x16x32_bf16 v[68:71], v[44:47], v[144:147], v[68:71]
	v_mfma_f32_16x16x32_bf16 v[64:67], v[52:55], v[144:147], v[64:67]
	v_mfma_f32_16x16x32_bf16 v[28:31], v[44:47], v[186:189], v[28:31]
	v_mfma_f32_16x16x32_bf16 v[24:27], v[52:55], v[186:189], v[24:27]
	v_mfma_f32_16x16x32_bf16 v[12:15], v[44:47], v[200:203], v[12:15]
	v_mfma_f32_16x16x32_bf16 v[8:11], v[52:55], v[200:203], v[8:11]
	v_mfma_f32_16x16x32_bf16 v[36:39], v[204:207], v[132:135], v[36:39]
	v_mfma_f32_16x16x32_bf16 v[32:35], v[212:215], v[132:135], v[32:35]
	v_mfma_f32_16x16x32_bf16 v[20:23], v[204:207], v[182:185], v[20:23]
	v_mfma_f32_16x16x32_bf16 v[16:19], v[212:215], v[182:185], v[16:19]
	v_mfma_f32_16x16x32_bf16 v[4:7], v[204:207], v[196:199], v[4:7]
	v_mfma_f32_16x16x32_bf16 v[0:3], v[212:215], v[196:199], v[0:3]
	v_mfma_f32_16x16x32_bf16 v[40:43], v[204:207], v[116:119], v[80:83]
	v_mfma_f32_16x16x32_bf16 v[44:47], v[212:215], v[116:119], v[76:79]
	v_mfma_f32_16x16x32_bf16 v[36:39], v[208:211], v[144:147], v[36:39]
	v_mfma_f32_16x16x32_bf16 v[32:35], v[216:219], v[144:147], v[32:35]
	v_mfma_f32_16x16x32_bf16 v[20:23], v[208:211], v[186:189], v[20:23]
	v_mfma_f32_16x16x32_bf16 v[16:19], v[216:219], v[186:189], v[16:19]
	v_mfma_f32_16x16x32_bf16 v[4:7], v[208:211], v[200:203], v[4:7]
	v_mfma_f32_16x16x32_bf16 v[0:3], v[216:219], v[200:203], v[0:3]
	v_mfma_f32_16x16x32_bf16 v[40:43], v[208:211], v[128:131], v[40:43]
	v_mfma_f32_16x16x32_bf16 v[44:47], v[216:219], v[128:131], v[44:47]
	s_barrier
	ds_read_b128 v[48:51], v194 offset:32768
	ds_read_b128 v[52:55], v194 offset:33792
	ds_read_b128 v[76:79], v194 offset:34816
	ds_read_b128 v[80:83], v194 offset:35840
	s_add_u32 s24, s26, 0xb0000
	s_addc_u32 s25, s27, 0
	s_mov_b32 m0, s39
	ds_read_b128 v[116:119], v195 offset:32768
	ds_read_b128 v[128:131], v195 offset:33792
	ds_read_b128 v[182:185], v195 offset:34816
	ds_read_b128 v[186:189], v195 offset:35840
	ds_read_b128 v[196:199], v195 offset:36864
	ds_read_b128 v[200:203], v195 offset:37888
	ds_read_b128 v[204:207], v195 offset:38912
	global_load_lds_dwordx4 v160, s[24:25]
	s_mov_b32 m0, s40
	ds_read_b128 v[208:211], v195 offset:39936
	global_load_lds_dwordx4 v162, s[24:25]
	s_waitcnt lgkmcnt(11)
	ds_read_b128 v[212:215], v194 offset:49152
	ds_read_b128 v[216:219], v194 offset:50176
	ds_read_b128 v[220:223], v194 offset:51200
	ds_read_b128 v[236:239], v194 offset:52224
	s_waitcnt lgkmcnt(0)
	s_barrier
	v_mfma_f32_16x16x32_bf16 v[132:135], v[48:51], v[116:119], v[156:159]
	v_mfma_f32_16x16x32_bf16 v[156:159], v[52:55], v[128:131], v[132:135]
	v_mfma_f32_16x16x32_bf16 v[132:135], v[76:79], v[116:119], v[152:155]
	v_mfma_f32_16x16x32_bf16 v[152:155], v[80:83], v[128:131], v[132:135]
	v_mfma_f32_16x16x32_bf16 v[132:135], v[48:51], v[182:185], v[140:143]
	v_mfma_f32_16x16x32_bf16 v[140:143], v[52:55], v[186:189], v[132:135]
	v_mfma_f32_16x16x32_bf16 v[132:135], v[76:79], v[182:185], v[136:139]
	v_mfma_f32_16x16x32_bf16 v[124:127], v[48:51], v[196:199], v[124:127]
	v_mfma_f32_16x16x32_bf16 v[120:123], v[76:79], v[196:199], v[120:123]
	v_mfma_f32_16x16x32_bf16 v[108:111], v[48:51], v[204:207], v[108:111]
	v_mfma_f32_16x16x32_bf16 v[104:107], v[76:79], v[204:207], v[104:107]
	v_mfma_f32_16x16x32_bf16 v[136:139], v[80:83], v[186:189], v[132:135]
	v_mfma_f32_16x16x32_bf16 v[124:127], v[52:55], v[200:203], v[124:127]
	v_mfma_f32_16x16x32_bf16 v[120:123], v[80:83], v[200:203], v[120:123]
	v_mfma_f32_16x16x32_bf16 v[108:111], v[52:55], v[208:211], v[108:111]
	v_mfma_f32_16x16x32_bf16 v[104:107], v[80:83], v[208:211], v[104:107]
	v_mfma_f32_16x16x32_bf16 v[56:59], v[220:223], v[116:119], v[56:59]
	v_mfma_f32_16x16x32_bf16 v[132:135], v[212:215], v[116:119], v[148:151]
	v_mfma_f32_16x16x32_bf16 v[144:147], v[236:239], v[128:131], v[56:59]
	v_mfma_f32_16x16x32_bf16 v[56:59], v[212:215], v[182:185], v[60:63]
	v_mfma_f32_16x16x32_bf16 v[148:151], v[216:219], v[128:131], v[132:135]
	v_mfma_f32_16x16x32_bf16 v[132:135], v[216:219], v[186:189], v[56:59]
	v_mfma_f32_16x16x32_bf16 v[56:59], v[220:223], v[182:185], v[72:75]
	v_mfma_f32_16x16x32_bf16 v[128:131], v[236:239], v[186:189], v[56:59]
	v_mfma_f32_16x16x32_bf16 v[56:59], v[212:215], v[196:199], v[84:87]
	v_mfma_f32_16x16x32_bf16 v[116:119], v[216:219], v[200:203], v[56:59]
	v_mfma_f32_16x16x32_bf16 v[56:59], v[220:223], v[196:199], v[112:115]
	v_mfma_f32_16x16x32_bf16 v[112:115], v[236:239], v[200:203], v[56:59]
	v_mfma_f32_16x16x32_bf16 v[56:59], v[212:215], v[204:207], v[100:103]
	v_mfma_f32_16x16x32_bf16 v[100:103], v[216:219], v[208:211], v[56:59]
	v_mfma_f32_16x16x32_bf16 v[56:59], v[220:223], v[204:207], v[96:99]
	v_mfma_f32_16x16x32_bf16 v[96:99], v[236:239], v[208:211], v[56:59]
	s_barrier
	s_add_i32 m0, s36, 0x18000
	ds_read_b128 v[56:59], v195 offset:49152
	global_load_lds_dwordx4 v168, s[98:99]
	s_add_i32 m0, s36, 0x1a000
	ds_read_b128 v[60:63], v195 offset:50176
	global_load_lds_dwordx4 v164, s[98:99]
	s_mov_b32 m0, s47
	s_nop 2
	ds_read_b128 v[72:75], v195 offset:51200
	ds_read_b128 v[84:87], v195 offset:52224
	ds_read_b128 v[182:185], v195 offset:53248
	ds_read_b128 v[186:189], v195 offset:54272
	ds_read_b128 v[196:199], v195 offset:55296
	global_load_lds_dwordx4 v160, s[100:101]
	s_mov_b32 m0, s49
	ds_read_b128 v[200:203], v195 offset:56320
	global_load_lds_dwordx4 v162, s[100:101]
	s_add_i32 m0, s36, 0x1c000
	s_add_u32 s8, s8, 0xb0080
	s_addc_u32 s9, s9, 0
	global_load_lds_dwordx4 v168, s[8:9]
	s_add_i32 m0, s36, 0x1e000
	s_add_i32 s58, s58, 2
	global_load_lds_dwordx4 v164, s[8:9]
	s_waitcnt lgkmcnt(0)
	s_waitcnt vmcnt(6)
	s_barrier
	v_mfma_f32_16x16x32_bf16 v[92:95], v[48:51], v[56:59], v[92:95]
	v_mfma_f32_16x16x32_bf16 v[88:91], v[76:79], v[56:59], v[88:91]
	v_mfma_f32_16x16x32_bf16 v[68:71], v[48:51], v[72:75], v[68:71]
	v_mfma_f32_16x16x32_bf16 v[64:67], v[76:79], v[72:75], v[64:67]
	v_mfma_f32_16x16x32_bf16 v[28:31], v[48:51], v[182:185], v[28:31]
	v_mfma_f32_16x16x32_bf16 v[24:27], v[76:79], v[182:185], v[24:27]
	v_mfma_f32_16x16x32_bf16 v[12:15], v[48:51], v[196:199], v[12:15]
	v_mfma_f32_16x16x32_bf16 v[8:11], v[76:79], v[196:199], v[8:11]
	v_mfma_f32_16x16x32_bf16 v[92:95], v[52:55], v[60:63], v[92:95]
	v_mfma_f32_16x16x32_bf16 v[88:91], v[80:83], v[60:63], v[88:91]
	v_mfma_f32_16x16x32_bf16 v[68:71], v[52:55], v[84:87], v[68:71]
	v_mfma_f32_16x16x32_bf16 v[64:67], v[80:83], v[84:87], v[64:67]
	v_mfma_f32_16x16x32_bf16 v[28:31], v[52:55], v[186:189], v[28:31]
	v_mfma_f32_16x16x32_bf16 v[24:27], v[80:83], v[186:189], v[24:27]
	v_mfma_f32_16x16x32_bf16 v[12:15], v[52:55], v[200:203], v[12:15]
	v_mfma_f32_16x16x32_bf16 v[8:11], v[80:83], v[200:203], v[8:11]
	v_mfma_f32_16x16x32_bf16 v[40:43], v[212:215], v[56:59], v[40:43]
	v_mfma_f32_16x16x32_bf16 v[80:83], v[216:219], v[60:63], v[40:43]
	v_mfma_f32_16x16x32_bf16 v[40:43], v[220:223], v[56:59], v[44:47]
	v_mfma_f32_16x16x32_bf16 v[36:39], v[212:215], v[72:75], v[36:39]
	v_mfma_f32_16x16x32_bf16 v[32:35], v[220:223], v[72:75], v[32:35]
	v_mfma_f32_16x16x32_bf16 v[20:23], v[212:215], v[182:185], v[20:23]
	v_mfma_f32_16x16x32_bf16 v[16:19], v[220:223], v[182:185], v[16:19]
	v_mfma_f32_16x16x32_bf16 v[4:7], v[212:215], v[196:199], v[4:7]
	v_mfma_f32_16x16x32_bf16 v[0:3], v[220:223], v[196:199], v[0:3]
	v_mfma_f32_16x16x32_bf16 v[76:79], v[236:239], v[60:63], v[40:43]
	v_mfma_f32_16x16x32_bf16 v[36:39], v[216:219], v[84:87], v[36:39]
	v_mfma_f32_16x16x32_bf16 v[32:35], v[236:239], v[84:87], v[32:35]
	v_mfma_f32_16x16x32_bf16 v[20:23], v[216:219], v[186:189], v[20:23]
	v_mfma_f32_16x16x32_bf16 v[16:19], v[236:239], v[186:189], v[16:19]
	v_mfma_f32_16x16x32_bf16 v[4:7], v[216:219], v[200:203], v[4:7]
	v_mfma_f32_16x16x32_bf16 v[0:3], v[236:239], v[200:203], v[0:3]
	s_add_u32 s56, s56, 0x100
	s_addc_u32 s57, s57, 0
	s_cmp_gt_u32 s58, 41
	s_mov_b64 s[24:25], s[2:3]
	s_barrier
	s_cbranch_scc0 .LBB0_1049
	s_lshl_b32 s2, s55, 8
	v_mov_b32_e32 v186, v193
	v_mov_b32_e32 v196, v192
	s_or_b32 s2, s2, s46
	v_mov_b32_e32 v52, 0
	v_lshl_add_u32 v182, v196, 3, s2
	s_add_i32 s2, s54, -16
	s_lshr_b32 s2, s2, 3
	s_add_i32 s2, s2, 1
	s_cmp_gt_i32 s54, 15
	s_cselect_b32 s8, s2, 0
	s_mul_i32 s96, s8, 0x1800
	s_lshl_b64 s[2:3], s[96:97], 2
	s_add_u32 s2, s41, s2
	v_ashrrev_i32_e32 v183, 31, v182
	s_addc_u32 s3, s42, s3
	v_lshlrev_b64 v[40:41], 2, v[182:183]
	v_lshl_add_u64 v[42:43], s[2:3], 0, v[40:41]
	global_load_dwordx4 v[72:75], v[42:43], off
	s_lshl_b32 s96, s8, 10
	s_lshl_b64 s[2:3], s[96:97], 2
	s_add_u32 s2, s43, s2
	s_addc_u32 s3, s44, s3
	v_lshl_add_u64 v[184:185], s[2:3], 0, v[40:41]
	s_and_b64 vcc, exec, s[4:5]
	v_mov_b32_e32 v60, 0
	v_mov_b32_e32 v61, v52
	v_mov_b32_e32 v62, 0
	v_mov_b32_e32 v63, 0
	s_cbranch_vccnz .LBB0_1052
	global_load_dwordx4 v[60:63], v[184:185], off
